# de-serialized load/wait chains: compress K-loop+w2, mixA/mixB1/mixB2 loads preloaded, ple+GEMM epilogues dwordx4, NSA output waits, top-k scalar compare
# speedup vs baseline: 1.0470x; 1.0225x over previous
; __device__ __forceinline__ unsigned pk2(float lo, float hi) { const f32x2v v = {lo, hi}; const bf16x2v r = __builtin_convertvector(v, bf16x2v); return __builtin_bit_cast(unsigned, r); }
; __device__ __forceinline__ float sigm(float x) { return __builtin_amdgcn_rcpf(1.f + __expf(-x)); }
; #define GEMM_EPI_LOOP _Pragma("unroll") for (int ai = 0; ai < 2; ++ai) _Pragma("unroll") for (int m = 0; m < 4; ++m) _Pragma("unroll") for (int bj = 0; bj < 2; ++bj)
; __device__ __forceinline__ void gemm_ple_phase(const bf16_t* a, const bf16_t* wpg, const bf16_t* pp, bf16_t* out, char* lds) {
;   gemm_phase(a, 1024, wpg, 1024, 1024, 4, lds, [&](f32x4 (&acc)[2][2][4][2], int tm, int tn) {
;     GEMM_LANE;
;     GEMM_EPI_LOOP {
;       const int row = tm * 256 + ai * 128 + wr * 64 + m * 16 + fr;
; #pragma unroll
;       for (int n = 0; n < 2; ++n) {
;         const int col = tn * 256 + bj * 128 + wc * 32 + n * 16 + 4 * fq;
;         const u32x2 pv = *(const u32x2*)(pp + (size_t)row * 1024 + col);
;         const f32x4 av = acc[ai][bj][m][n];
;         u32x2 o;
;         o.x = pk2(sigm(av[0]) * __uint_as_float(pv.x << 16), sigm(av[1]) * __uint_as_float(pv.x & 0xffff0000u));
;         o.y = pk2(sigm(av[2]) * __uint_as_float(pv.y << 16), sigm(av[3]) * __uint_as_float(pv.y & 0xffff0000u));
;         *(u32x2*)(out + (size_t)row * 1024 + col) = o;
;       }
;     }
;   });
; }
.LBB0_71:
	s_mul_i32 s30, s30, 0x80000
	s_lshl_b32 s42, s42, 9
	s_add_u32 s30, s30, s42
	v_readlane_b32 s16, v252, 36
	v_readlane_b32 s17, v252, 37
	v_lshrrev_b32_e32 v131, 1, v179
	v_and_b32_e32 v130, 16, v131
	v_and_b32_e32 v131, 8, v131
	v_lshl_or_b32 v130, v131, 2, v130
	v_and_b32_e32 v131, 0xc0, v179
	v_or_b32_e32 v130, v130, v131
	v_ashrrev_i32_e32 v128, 2, v179
	v_and_b32_e32 v128, 0xffffffc0, v128
	v_and_or_b32 v128, v179, 15, v128
	v_lshl_or_b32 v128, v128, 11, v130
	v_add_u32_e32 v128, s30, v128
	v_mov_b32_e32 v140, v128
	v_add_u32_e32 v141, 0x8000, v128
	v_add_u32_e32 v142, 0x10000, v128
	v_add_u32_e32 v143, 0x18000, v128
	v_add_u32_e32 v144, 0x40000, v128
	v_add_u32_e32 v145, 0x48000, v128
	v_add_u32_e32 v146, 0x50000, v128
	v_add_u32_e32 v147, 0x58000, v128
	global_load_dwordx4 v[134:137], v140, s[84:85]
	global_load_dwordx4 v[148:151], v140, s[84:85] offset:256
	global_load_dwordx4 v[152:155], v141, s[84:85]
	global_load_dwordx4 v[156:159], v141, s[84:85] offset:256
	global_load_dwordx4 v[160:163], v142, s[84:85]
	global_load_dwordx4 v[164:167], v142, s[84:85] offset:256
	global_load_dwordx4 v[168:171], v143, s[84:85]
	global_load_dwordx4 v[172:175], v143, s[84:85] offset:256
	global_load_dwordx4 v[180:183], v144, s[84:85]
	global_load_dwordx4 v[184:187], v144, s[84:85] offset:256
	global_load_dwordx4 v[188:191], v145, s[84:85]
	global_load_dwordx4 v[192:195], v145, s[84:85] offset:256
	global_load_dwordx4 v[196:199], v146, s[84:85]
	global_load_dwordx4 v[200:203], v146, s[84:85] offset:256
	global_load_dwordx4 v[204:207], v147, s[84:85]
	global_load_dwordx4 v[208:211], v147, s[84:85] offset:256
	v_mul_f32_e32 v0, 0xbfb8aa3b, v0
	v_mul_f32_e32 v1, 0xbfb8aa3b, v1
	v_mul_f32_e32 v2, 0xbfb8aa3b, v2
	v_mul_f32_e32 v3, 0xbfb8aa3b, v3
	v_exp_f32_e32 v0, v0
	v_exp_f32_e32 v1, v1
	v_exp_f32_e32 v2, v2
	v_exp_f32_e32 v3, v3
	v_add_f32_e32 v0, 1.0, v0
	v_add_f32_e32 v1, 1.0, v1
	v_add_f32_e32 v2, 1.0, v2
	v_add_f32_e32 v3, 1.0, v3
	v_rcp_f32_e32 v0, v0
	v_rcp_f32_e32 v1, v1
	v_rcp_f32_e32 v2, v2
	v_rcp_f32_e32 v3, v3
	v_mul_f32_e32 v4, 0xbfb8aa3b, v4
	v_mul_f32_e32 v5, 0xbfb8aa3b, v5
	v_mul_f32_e32 v6, 0xbfb8aa3b, v6
	v_mul_f32_e32 v7, 0xbfb8aa3b, v7
	v_exp_f32_e32 v4, v4
	v_exp_f32_e32 v5, v5
	v_exp_f32_e32 v6, v6
	v_exp_f32_e32 v7, v7
	v_add_f32_e32 v4, 1.0, v4
	v_add_f32_e32 v5, 1.0, v5
	v_add_f32_e32 v6, 1.0, v6
	v_add_f32_e32 v7, 1.0, v7
	v_rcp_f32_e32 v4, v4
	v_rcp_f32_e32 v5, v5
	v_rcp_f32_e32 v6, v6
	v_rcp_f32_e32 v7, v7
	v_mul_f32_e32 v8, 0xbfb8aa3b, v8
	v_mul_f32_e32 v9, 0xbfb8aa3b, v9
	v_mul_f32_e32 v10, 0xbfb8aa3b, v10
	v_mul_f32_e32 v11, 0xbfb8aa3b, v11
	v_exp_f32_e32 v8, v8
	v_exp_f32_e32 v9, v9
	v_exp_f32_e32 v10, v10
	v_exp_f32_e32 v11, v11
	v_add_f32_e32 v8, 1.0, v8
	v_add_f32_e32 v9, 1.0, v9
	v_add_f32_e32 v10, 1.0, v10
	v_add_f32_e32 v11, 1.0, v11
	v_rcp_f32_e32 v8, v8
	v_rcp_f32_e32 v9, v9
	v_rcp_f32_e32 v10, v10
	v_rcp_f32_e32 v11, v11
	v_mul_f32_e32 v12, 0xbfb8aa3b, v12
	v_mul_f32_e32 v13, 0xbfb8aa3b, v13
	v_mul_f32_e32 v14, 0xbfb8aa3b, v14
	v_mul_f32_e32 v15, 0xbfb8aa3b, v15
	v_exp_f32_e32 v12, v12
	v_exp_f32_e32 v13, v13
	v_exp_f32_e32 v14, v14
	v_exp_f32_e32 v15, v15
	v_add_f32_e32 v12, 1.0, v12
	v_add_f32_e32 v13, 1.0, v13
	v_add_f32_e32 v14, 1.0, v14
	v_add_f32_e32 v15, 1.0, v15
	v_rcp_f32_e32 v12, v12
	v_rcp_f32_e32 v13, v13
	v_rcp_f32_e32 v14, v14
	v_rcp_f32_e32 v15, v15
	v_mul_f32_e32 v16, 0xbfb8aa3b, v16
	v_mul_f32_e32 v17, 0xbfb8aa3b, v17
	v_mul_f32_e32 v18, 0xbfb8aa3b, v18
	v_mul_f32_e32 v19, 0xbfb8aa3b, v19
	v_exp_f32_e32 v16, v16
	v_exp_f32_e32 v17, v17
	v_exp_f32_e32 v18, v18
	v_exp_f32_e32 v19, v19
	v_add_f32_e32 v16, 1.0, v16
	v_add_f32_e32 v17, 1.0, v17
	v_add_f32_e32 v18, 1.0, v18
	v_add_f32_e32 v19, 1.0, v19
	v_rcp_f32_e32 v16, v16
	v_rcp_f32_e32 v17, v17
	v_rcp_f32_e32 v18, v18
	v_rcp_f32_e32 v19, v19
	v_mul_f32_e32 v20, 0xbfb8aa3b, v20
	v_mul_f32_e32 v21, 0xbfb8aa3b, v21
	v_mul_f32_e32 v22, 0xbfb8aa3b, v22
	v_mul_f32_e32 v23, 0xbfb8aa3b, v23
	v_exp_f32_e32 v20, v20
	v_exp_f32_e32 v21, v21
	v_exp_f32_e32 v22, v22
	v_exp_f32_e32 v23, v23
	v_add_f32_e32 v20, 1.0, v20
	v_add_f32_e32 v21, 1.0, v21
	v_add_f32_e32 v22, 1.0, v22
	v_add_f32_e32 v23, 1.0, v23
	v_rcp_f32_e32 v20, v20
	v_rcp_f32_e32 v21, v21
	v_rcp_f32_e32 v22, v22
	v_rcp_f32_e32 v23, v23
	v_mul_f32_e32 v24, 0xbfb8aa3b, v24
	v_mul_f32_e32 v25, 0xbfb8aa3b, v25
	v_mul_f32_e32 v26, 0xbfb8aa3b, v26
	v_mul_f32_e32 v27, 0xbfb8aa3b, v27
	v_exp_f32_e32 v24, v24
	v_exp_f32_e32 v25, v25
	v_exp_f32_e32 v26, v26
	v_exp_f32_e32 v27, v27
	v_add_f32_e32 v24, 1.0, v24
	v_add_f32_e32 v25, 1.0, v25
	v_add_f32_e32 v26, 1.0, v26
	v_add_f32_e32 v27, 1.0, v27
	v_rcp_f32_e32 v24, v24
	v_rcp_f32_e32 v25, v25
	v_rcp_f32_e32 v26, v26
	v_rcp_f32_e32 v27, v27
	v_mul_f32_e32 v28, 0xbfb8aa3b, v28
	v_mul_f32_e32 v29, 0xbfb8aa3b, v29
	v_mul_f32_e32 v30, 0xbfb8aa3b, v30
	v_mul_f32_e32 v31, 0xbfb8aa3b, v31
	v_exp_f32_e32 v28, v28
	v_exp_f32_e32 v29, v29
	v_exp_f32_e32 v30, v30
	v_exp_f32_e32 v31, v31
	v_add_f32_e32 v28, 1.0, v28
	v_add_f32_e32 v29, 1.0, v29
	v_add_f32_e32 v30, 1.0, v30
	v_add_f32_e32 v31, 1.0, v31
	v_rcp_f32_e32 v28, v28
	v_rcp_f32_e32 v29, v29
	v_rcp_f32_e32 v30, v30
	v_rcp_f32_e32 v31, v31
	v_mul_f32_e32 v32, 0xbfb8aa3b, v32
	v_mul_f32_e32 v33, 0xbfb8aa3b, v33
	v_mul_f32_e32 v34, 0xbfb8aa3b, v34
	v_mul_f32_e32 v35, 0xbfb8aa3b, v35
	v_exp_f32_e32 v32, v32
	v_exp_f32_e32 v33, v33
	v_exp_f32_e32 v34, v34
	v_exp_f32_e32 v35, v35
	v_add_f32_e32 v32, 1.0, v32
	v_add_f32_e32 v33, 1.0, v33
	v_add_f32_e32 v34, 1.0, v34
	v_add_f32_e32 v35, 1.0, v35
	v_rcp_f32_e32 v32, v32
	v_rcp_f32_e32 v33, v33
	v_rcp_f32_e32 v34, v34
	v_rcp_f32_e32 v35, v35
; __device__ __forceinline__ unsigned pk2(float lo, float hi) { const f32x2v v = {lo, hi}; const bf16x2v r = __builtin_convertvector(v, bf16x2v); return __builtin_bit_cast(unsigned, r); }
; __device__ __forceinline__ float sigm(float x) { return __builtin_amdgcn_rcpf(1.f + __expf(-x)); }
; #define GEMM_EPI_LOOP _Pragma("unroll") for (int ai = 0; ai < 2; ++ai) _Pragma("unroll") for (int m = 0; m < 4; ++m) _Pragma("unroll") for (int bj = 0; bj < 2; ++bj)
; __device__ __forceinline__ void gemm_ple_phase(const bf16_t* a, const bf16_t* wpg, const bf16_t* pp, bf16_t* out, char* lds) {
;   gemm_phase(a, 1024, wpg, 1024, 1024, 4, lds, [&](f32x4 (&acc)[2][2][4][2], int tm, int tn) {
;     GEMM_LANE;
;     GEMM_EPI_LOOP {
;       const int row = tm * 256 + ai * 128 + wr * 64 + m * 16 + fr;
; #pragma unroll
;       for (int n = 0; n < 2; ++n) {
;         const int col = tn * 256 + bj * 128 + wc * 32 + n * 16 + 4 * fq;
;         const u32x2 pv = *(const u32x2*)(pp + (size_t)row * 1024 + col);
;         const f32x4 av = acc[ai][bj][m][n];
;         u32x2 o;
;         o.x = pk2(sigm(av[0]) * __uint_as_float(pv.x << 16), sigm(av[1]) * __uint_as_float(pv.x & 0xffff0000u));
;         o.y = pk2(sigm(av[2]) * __uint_as_float(pv.y << 16), sigm(av[3]) * __uint_as_float(pv.y & 0xffff0000u));
;         *(u32x2*)(out + (size_t)row * 1024 + col) = o;
;       }
;     }
;   });
; }
	v_mul_f32_e32 v36, 0xbfb8aa3b, v36
	v_mul_f32_e32 v37, 0xbfb8aa3b, v37
	v_mul_f32_e32 v38, 0xbfb8aa3b, v38
	v_mul_f32_e32 v39, 0xbfb8aa3b, v39
	v_exp_f32_e32 v36, v36
	v_exp_f32_e32 v37, v37
	v_exp_f32_e32 v38, v38
	v_exp_f32_e32 v39, v39
	v_add_f32_e32 v36, 1.0, v36
	v_add_f32_e32 v37, 1.0, v37
	v_add_f32_e32 v38, 1.0, v38
	v_add_f32_e32 v39, 1.0, v39
	v_rcp_f32_e32 v36, v36
	v_rcp_f32_e32 v37, v37
	v_rcp_f32_e32 v38, v38
	v_rcp_f32_e32 v39, v39
	v_mul_f32_e32 v40, 0xbfb8aa3b, v40
	v_mul_f32_e32 v41, 0xbfb8aa3b, v41
	v_mul_f32_e32 v42, 0xbfb8aa3b, v42
	v_mul_f32_e32 v43, 0xbfb8aa3b, v43
	v_exp_f32_e32 v40, v40
	v_exp_f32_e32 v41, v41
	v_exp_f32_e32 v42, v42
	v_exp_f32_e32 v43, v43
	v_add_f32_e32 v40, 1.0, v40
	v_add_f32_e32 v41, 1.0, v41
	v_add_f32_e32 v42, 1.0, v42
	v_add_f32_e32 v43, 1.0, v43
	v_rcp_f32_e32 v40, v40
	v_rcp_f32_e32 v41, v41
	v_rcp_f32_e32 v42, v42
	v_rcp_f32_e32 v43, v43
	v_mul_f32_e32 v44, 0xbfb8aa3b, v44
	v_mul_f32_e32 v45, 0xbfb8aa3b, v45
	v_mul_f32_e32 v46, 0xbfb8aa3b, v46
	v_mul_f32_e32 v47, 0xbfb8aa3b, v47
	v_exp_f32_e32 v44, v44
	v_exp_f32_e32 v45, v45
	v_exp_f32_e32 v46, v46
	v_exp_f32_e32 v47, v47
	v_add_f32_e32 v44, 1.0, v44
	v_add_f32_e32 v45, 1.0, v45
	v_add_f32_e32 v46, 1.0, v46
	v_add_f32_e32 v47, 1.0, v47
	v_rcp_f32_e32 v44, v44
	v_rcp_f32_e32 v45, v45
	v_rcp_f32_e32 v46, v46
	v_rcp_f32_e32 v47, v47
	v_mul_f32_e32 v48, 0xbfb8aa3b, v48
	v_mul_f32_e32 v49, 0xbfb8aa3b, v49
	v_mul_f32_e32 v50, 0xbfb8aa3b, v50
	v_mul_f32_e32 v51, 0xbfb8aa3b, v51
	v_exp_f32_e32 v48, v48
	v_exp_f32_e32 v49, v49
	v_exp_f32_e32 v50, v50
	v_exp_f32_e32 v51, v51
	v_add_f32_e32 v48, 1.0, v48
	v_add_f32_e32 v49, 1.0, v49
	v_add_f32_e32 v50, 1.0, v50
	v_add_f32_e32 v51, 1.0, v51
	v_rcp_f32_e32 v48, v48
	v_rcp_f32_e32 v49, v49
	v_rcp_f32_e32 v50, v50
	v_rcp_f32_e32 v51, v51
	v_mul_f32_e32 v52, 0xbfb8aa3b, v52
	v_mul_f32_e32 v53, 0xbfb8aa3b, v53
	v_mul_f32_e32 v54, 0xbfb8aa3b, v54
	v_mul_f32_e32 v55, 0xbfb8aa3b, v55
	v_exp_f32_e32 v52, v52
	v_exp_f32_e32 v53, v53
	v_exp_f32_e32 v54, v54
	v_exp_f32_e32 v55, v55
	v_add_f32_e32 v52, 1.0, v52
	v_add_f32_e32 v53, 1.0, v53
	v_add_f32_e32 v54, 1.0, v54
	v_add_f32_e32 v55, 1.0, v55
	v_rcp_f32_e32 v52, v52
	v_rcp_f32_e32 v53, v53
	v_rcp_f32_e32 v54, v54
	v_rcp_f32_e32 v55, v55
	v_mul_f32_e32 v56, 0xbfb8aa3b, v56
	v_mul_f32_e32 v57, 0xbfb8aa3b, v57
	v_mul_f32_e32 v58, 0xbfb8aa3b, v58
	v_mul_f32_e32 v59, 0xbfb8aa3b, v59
	v_exp_f32_e32 v56, v56
	v_exp_f32_e32 v57, v57
	v_exp_f32_e32 v58, v58
	v_exp_f32_e32 v59, v59
	v_add_f32_e32 v56, 1.0, v56
	v_add_f32_e32 v57, 1.0, v57
	v_add_f32_e32 v58, 1.0, v58
	v_add_f32_e32 v59, 1.0, v59
	v_rcp_f32_e32 v56, v56
	v_rcp_f32_e32 v57, v57
	v_rcp_f32_e32 v58, v58
	v_rcp_f32_e32 v59, v59
	v_mul_f32_e32 v60, 0xbfb8aa3b, v60
	v_mul_f32_e32 v61, 0xbfb8aa3b, v61
	v_mul_f32_e32 v62, 0xbfb8aa3b, v62
	v_mul_f32_e32 v63, 0xbfb8aa3b, v63
	v_exp_f32_e32 v60, v60
	v_exp_f32_e32 v61, v61
	v_exp_f32_e32 v62, v62
	v_exp_f32_e32 v63, v63
	v_add_f32_e32 v60, 1.0, v60
	v_add_f32_e32 v61, 1.0, v61
	v_add_f32_e32 v62, 1.0, v62
	v_add_f32_e32 v63, 1.0, v63
	v_rcp_f32_e32 v60, v60
	v_rcp_f32_e32 v61, v61
	v_rcp_f32_e32 v62, v62
	v_rcp_f32_e32 v63, v63
	v_mul_f32_e32 v64, 0xbfb8aa3b, v64
	v_mul_f32_e32 v65, 0xbfb8aa3b, v65
	v_mul_f32_e32 v66, 0xbfb8aa3b, v66
	v_mul_f32_e32 v67, 0xbfb8aa3b, v67
	v_exp_f32_e32 v64, v64
	v_exp_f32_e32 v65, v65
	v_exp_f32_e32 v66, v66
	v_exp_f32_e32 v67, v67
	v_add_f32_e32 v64, 1.0, v64
	v_add_f32_e32 v65, 1.0, v65
	v_add_f32_e32 v66, 1.0, v66
	v_add_f32_e32 v67, 1.0, v67
	v_rcp_f32_e32 v64, v64
	v_rcp_f32_e32 v65, v65
	v_rcp_f32_e32 v66, v66
	v_rcp_f32_e32 v67, v67
	v_mul_f32_e32 v68, 0xbfb8aa3b, v68
	v_mul_f32_e32 v69, 0xbfb8aa3b, v69
	v_mul_f32_e32 v70, 0xbfb8aa3b, v70
	v_mul_f32_e32 v71, 0xbfb8aa3b, v71
	v_exp_f32_e32 v68, v68
	v_exp_f32_e32 v69, v69
	v_exp_f32_e32 v70, v70
	v_exp_f32_e32 v71, v71
	v_add_f32_e32 v68, 1.0, v68
	v_add_f32_e32 v69, 1.0, v69
	v_add_f32_e32 v70, 1.0, v70
	v_add_f32_e32 v71, 1.0, v71
	v_rcp_f32_e32 v68, v68
	v_rcp_f32_e32 v69, v69
	v_rcp_f32_e32 v70, v70
	v_rcp_f32_e32 v71, v71
	v_mul_f32_e32 v72, 0xbfb8aa3b, v72
	v_mul_f32_e32 v73, 0xbfb8aa3b, v73
	v_mul_f32_e32 v74, 0xbfb8aa3b, v74
	v_mul_f32_e32 v75, 0xbfb8aa3b, v75
	v_exp_f32_e32 v72, v72
	v_exp_f32_e32 v73, v73
	v_exp_f32_e32 v74, v74
	v_exp_f32_e32 v75, v75
	v_add_f32_e32 v72, 1.0, v72
	v_add_f32_e32 v73, 1.0, v73
	v_add_f32_e32 v74, 1.0, v74
	v_add_f32_e32 v75, 1.0, v75
	v_rcp_f32_e32 v72, v72
	v_rcp_f32_e32 v73, v73
	v_rcp_f32_e32 v74, v74
	v_rcp_f32_e32 v75, v75
	v_mul_f32_e32 v76, 0xbfb8aa3b, v76
	v_mul_f32_e32 v77, 0xbfb8aa3b, v77
	v_mul_f32_e32 v78, 0xbfb8aa3b, v78
	v_mul_f32_e32 v79, 0xbfb8aa3b, v79
	v_exp_f32_e32 v76, v76
	v_exp_f32_e32 v77, v77
	v_exp_f32_e32 v78, v78
	v_exp_f32_e32 v79, v79
	v_add_f32_e32 v76, 1.0, v76
	v_add_f32_e32 v77, 1.0, v77
	v_add_f32_e32 v78, 1.0, v78
	v_add_f32_e32 v79, 1.0, v79
	v_rcp_f32_e32 v76, v76
	v_rcp_f32_e32 v77, v77
	v_rcp_f32_e32 v78, v78
	v_rcp_f32_e32 v79, v79
	v_mul_f32_e32 v80, 0xbfb8aa3b, v80
	v_mul_f32_e32 v81, 0xbfb8aa3b, v81
	v_mul_f32_e32 v82, 0xbfb8aa3b, v82
	v_mul_f32_e32 v83, 0xbfb8aa3b, v83
	v_exp_f32_e32 v80, v80
	v_exp_f32_e32 v81, v81
	v_exp_f32_e32 v82, v82
	v_exp_f32_e32 v83, v83
	v_add_f32_e32 v80, 1.0, v80
	v_add_f32_e32 v81, 1.0, v81
	v_add_f32_e32 v82, 1.0, v82
	v_add_f32_e32 v83, 1.0, v83
	v_rcp_f32_e32 v80, v80
	v_rcp_f32_e32 v81, v81
	v_rcp_f32_e32 v82, v82
	v_rcp_f32_e32 v83, v83
	v_mul_f32_e32 v84, 0xbfb8aa3b, v84
	v_mul_f32_e32 v85, 0xbfb8aa3b, v85
	v_mul_f32_e32 v86, 0xbfb8aa3b, v86
	v_mul_f32_e32 v87, 0xbfb8aa3b, v87
	v_exp_f32_e32 v84, v84
	v_exp_f32_e32 v85, v85
	v_exp_f32_e32 v86, v86
; __device__ __forceinline__ unsigned pk2(float lo, float hi) { const f32x2v v = {lo, hi}; const bf16x2v r = __builtin_convertvector(v, bf16x2v); return __builtin_bit_cast(unsigned, r); }
; __device__ __forceinline__ float sigm(float x) { return __builtin_amdgcn_rcpf(1.f + __expf(-x)); }
; #define GEMM_EPI_LOOP _Pragma("unroll") for (int ai = 0; ai < 2; ++ai) _Pragma("unroll") for (int m = 0; m < 4; ++m) _Pragma("unroll") for (int bj = 0; bj < 2; ++bj)
; __device__ __forceinline__ void gemm_ple_phase(const bf16_t* a, const bf16_t* wpg, const bf16_t* pp, bf16_t* out, char* lds) {
;   gemm_phase(a, 1024, wpg, 1024, 1024, 4, lds, [&](f32x4 (&acc)[2][2][4][2], int tm, int tn) {
;     GEMM_LANE;
;     GEMM_EPI_LOOP {
;       const int row = tm * 256 + ai * 128 + wr * 64 + m * 16 + fr;
; #pragma unroll
;       for (int n = 0; n < 2; ++n) {
;         const int col = tn * 256 + bj * 128 + wc * 32 + n * 16 + 4 * fq;
;         const u32x2 pv = *(const u32x2*)(pp + (size_t)row * 1024 + col);
;         const f32x4 av = acc[ai][bj][m][n];
;         u32x2 o;
;         o.x = pk2(sigm(av[0]) * __uint_as_float(pv.x << 16), sigm(av[1]) * __uint_as_float(pv.x & 0xffff0000u));
;         o.y = pk2(sigm(av[2]) * __uint_as_float(pv.y << 16), sigm(av[3]) * __uint_as_float(pv.y & 0xffff0000u));
;         *(u32x2*)(out + (size_t)row * 1024 + col) = o;
;       }
;     }
;   });
; }
	v_exp_f32_e32 v87, v87
	v_add_f32_e32 v84, 1.0, v84
	v_add_f32_e32 v85, 1.0, v85
	v_add_f32_e32 v86, 1.0, v86
	v_add_f32_e32 v87, 1.0, v87
	v_rcp_f32_e32 v84, v84
	v_rcp_f32_e32 v85, v85
	v_rcp_f32_e32 v86, v86
	v_rcp_f32_e32 v87, v87
	v_mul_f32_e32 v88, 0xbfb8aa3b, v88
	v_mul_f32_e32 v89, 0xbfb8aa3b, v89
	v_mul_f32_e32 v90, 0xbfb8aa3b, v90
	v_mul_f32_e32 v91, 0xbfb8aa3b, v91
	v_exp_f32_e32 v88, v88
	v_exp_f32_e32 v89, v89
	v_exp_f32_e32 v90, v90
	v_exp_f32_e32 v91, v91
	v_add_f32_e32 v88, 1.0, v88
	v_add_f32_e32 v89, 1.0, v89
	v_add_f32_e32 v90, 1.0, v90
	v_add_f32_e32 v91, 1.0, v91
	v_rcp_f32_e32 v88, v88
	v_rcp_f32_e32 v89, v89
	v_rcp_f32_e32 v90, v90
	v_rcp_f32_e32 v91, v91
	v_mul_f32_e32 v92, 0xbfb8aa3b, v92
	v_mul_f32_e32 v93, 0xbfb8aa3b, v93
	v_mul_f32_e32 v94, 0xbfb8aa3b, v94
	v_mul_f32_e32 v95, 0xbfb8aa3b, v95
	v_exp_f32_e32 v92, v92
	v_exp_f32_e32 v93, v93
	v_exp_f32_e32 v94, v94
	v_exp_f32_e32 v95, v95
	v_add_f32_e32 v92, 1.0, v92
	v_add_f32_e32 v93, 1.0, v93
	v_add_f32_e32 v94, 1.0, v94
	v_add_f32_e32 v95, 1.0, v95
	v_rcp_f32_e32 v92, v92
	v_rcp_f32_e32 v93, v93
	v_rcp_f32_e32 v94, v94
	v_rcp_f32_e32 v95, v95
	v_mul_f32_e32 v96, 0xbfb8aa3b, v96
	v_mul_f32_e32 v97, 0xbfb8aa3b, v97
	v_mul_f32_e32 v98, 0xbfb8aa3b, v98
	v_mul_f32_e32 v99, 0xbfb8aa3b, v99
	v_exp_f32_e32 v96, v96
	v_exp_f32_e32 v97, v97
	v_exp_f32_e32 v98, v98
	v_exp_f32_e32 v99, v99
	v_add_f32_e32 v96, 1.0, v96
	v_add_f32_e32 v97, 1.0, v97
	v_add_f32_e32 v98, 1.0, v98
	v_add_f32_e32 v99, 1.0, v99
	v_rcp_f32_e32 v96, v96
	v_rcp_f32_e32 v97, v97
	v_rcp_f32_e32 v98, v98
	v_rcp_f32_e32 v99, v99
	v_mul_f32_e32 v100, 0xbfb8aa3b, v100
	v_mul_f32_e32 v101, 0xbfb8aa3b, v101
	v_mul_f32_e32 v102, 0xbfb8aa3b, v102
	v_mul_f32_e32 v103, 0xbfb8aa3b, v103
	v_exp_f32_e32 v100, v100
	v_exp_f32_e32 v101, v101
	v_exp_f32_e32 v102, v102
	v_exp_f32_e32 v103, v103
	v_add_f32_e32 v100, 1.0, v100
	v_add_f32_e32 v101, 1.0, v101
	v_add_f32_e32 v102, 1.0, v102
	v_add_f32_e32 v103, 1.0, v103
	v_rcp_f32_e32 v100, v100
	v_rcp_f32_e32 v101, v101
	v_rcp_f32_e32 v102, v102
	v_rcp_f32_e32 v103, v103
	v_mul_f32_e32 v104, 0xbfb8aa3b, v104
	v_mul_f32_e32 v105, 0xbfb8aa3b, v105
	v_mul_f32_e32 v106, 0xbfb8aa3b, v106
	v_mul_f32_e32 v107, 0xbfb8aa3b, v107
	v_exp_f32_e32 v104, v104
	v_exp_f32_e32 v105, v105
	v_exp_f32_e32 v106, v106
	v_exp_f32_e32 v107, v107
	v_add_f32_e32 v104, 1.0, v104
	v_add_f32_e32 v105, 1.0, v105
	v_add_f32_e32 v106, 1.0, v106
	v_add_f32_e32 v107, 1.0, v107
	v_rcp_f32_e32 v104, v104
	v_rcp_f32_e32 v105, v105
	v_rcp_f32_e32 v106, v106
	v_rcp_f32_e32 v107, v107
	v_mul_f32_e32 v108, 0xbfb8aa3b, v108
	v_mul_f32_e32 v109, 0xbfb8aa3b, v109
	v_mul_f32_e32 v110, 0xbfb8aa3b, v110
	v_mul_f32_e32 v111, 0xbfb8aa3b, v111
	v_exp_f32_e32 v108, v108
	v_exp_f32_e32 v109, v109
	v_exp_f32_e32 v110, v110
	v_exp_f32_e32 v111, v111
	v_add_f32_e32 v108, 1.0, v108
	v_add_f32_e32 v109, 1.0, v109
	v_add_f32_e32 v110, 1.0, v110
	v_add_f32_e32 v111, 1.0, v111
	v_rcp_f32_e32 v108, v108
	v_rcp_f32_e32 v109, v109
	v_rcp_f32_e32 v110, v110
	v_rcp_f32_e32 v111, v111
	v_mul_f32_e32 v112, 0xbfb8aa3b, v112
	v_mul_f32_e32 v113, 0xbfb8aa3b, v113
	v_mul_f32_e32 v114, 0xbfb8aa3b, v114
	v_mul_f32_e32 v115, 0xbfb8aa3b, v115
	v_exp_f32_e32 v112, v112
	v_exp_f32_e32 v113, v113
	v_exp_f32_e32 v114, v114
	v_exp_f32_e32 v115, v115
	v_add_f32_e32 v112, 1.0, v112
	v_add_f32_e32 v113, 1.0, v113
	v_add_f32_e32 v114, 1.0, v114
	v_add_f32_e32 v115, 1.0, v115
	v_rcp_f32_e32 v112, v112
	v_rcp_f32_e32 v113, v113
	v_rcp_f32_e32 v114, v114
	v_rcp_f32_e32 v115, v115
	v_mul_f32_e32 v116, 0xbfb8aa3b, v116
	v_mul_f32_e32 v117, 0xbfb8aa3b, v117
	v_mul_f32_e32 v118, 0xbfb8aa3b, v118
	v_mul_f32_e32 v119, 0xbfb8aa3b, v119
	v_exp_f32_e32 v116, v116
	v_exp_f32_e32 v117, v117
	v_exp_f32_e32 v118, v118
	v_exp_f32_e32 v119, v119
	v_add_f32_e32 v116, 1.0, v116
	v_add_f32_e32 v117, 1.0, v117
	v_add_f32_e32 v118, 1.0, v118
	v_add_f32_e32 v119, 1.0, v119
	v_rcp_f32_e32 v116, v116
	v_rcp_f32_e32 v117, v117
	v_rcp_f32_e32 v118, v118
	v_rcp_f32_e32 v119, v119
	v_mul_f32_e32 v120, 0xbfb8aa3b, v120
	v_mul_f32_e32 v121, 0xbfb8aa3b, v121
	v_mul_f32_e32 v122, 0xbfb8aa3b, v122
	v_mul_f32_e32 v123, 0xbfb8aa3b, v123
	v_exp_f32_e32 v120, v120
	v_exp_f32_e32 v121, v121
	v_exp_f32_e32 v122, v122
	v_exp_f32_e32 v123, v123
	v_add_f32_e32 v120, 1.0, v120
	v_add_f32_e32 v121, 1.0, v121
	v_add_f32_e32 v122, 1.0, v122
	v_add_f32_e32 v123, 1.0, v123
	v_rcp_f32_e32 v120, v120
	v_rcp_f32_e32 v121, v121
	v_rcp_f32_e32 v122, v122
	v_rcp_f32_e32 v123, v123
	v_mul_f32_e32 v124, 0xbfb8aa3b, v124
	v_mul_f32_e32 v125, 0xbfb8aa3b, v125
	v_mul_f32_e32 v126, 0xbfb8aa3b, v126
	v_mul_f32_e32 v127, 0xbfb8aa3b, v127
	v_exp_f32_e32 v124, v124
	v_exp_f32_e32 v125, v125
	v_exp_f32_e32 v126, v126
	v_exp_f32_e32 v127, v127
	v_add_f32_e32 v124, 1.0, v124
	v_add_f32_e32 v125, 1.0, v125
	v_add_f32_e32 v126, 1.0, v126
	v_add_f32_e32 v127, 1.0, v127
	v_rcp_f32_e32 v124, v124
	v_rcp_f32_e32 v125, v125
	v_rcp_f32_e32 v126, v126
	v_rcp_f32_e32 v127, v127
	s_waitcnt vmcnt(15)
	v_permlane16_swap_b32_e32 v134, v136
	v_permlane16_swap_b32_e32 v135, v137
	v_lshlrev_b32_e32 v132, 16, v134
	v_and_b32_e32 v134, 0xffff0000, v134
	v_lshlrev_b32_e32 v133, 16, v135
	v_and_b32_e32 v135, 0xffff0000, v135
	v_mul_f32_e32 v124, v124, v132
	v_mul_f32_e32 v125, v125, v134
	v_mul_f32_e32 v126, v126, v133
	v_mul_f32_e32 v127, v127, v135
	v_lshlrev_b32_e32 v132, 16, v136
	v_and_b32_e32 v136, 0xffff0000, v136
	v_lshlrev_b32_e32 v133, 16, v137
	v_and_b32_e32 v137, 0xffff0000, v137
	v_mul_f32_e32 v120, v120, v132
	v_mul_f32_e32 v121, v121, v136
	v_mul_f32_e32 v122, v122, v133
	v_mul_f32_e32 v123, v123, v137
	v_cvt_pk_bf16_f32 v124, v124, v125
	v_cvt_pk_bf16_f32 v125, v126, v127
	v_cvt_pk_bf16_f32 v126, v120, v121
	v_cvt_pk_bf16_f32 v127, v122, v123
	s_nop 1
	v_permlane16_swap_b32_e32 v124, v126
	v_permlane16_swap_b32_e32 v125, v127
	global_store_dwordx4 v140, v[124:127], s[16:17]
	s_waitcnt vmcnt(15)
; __device__ __forceinline__ unsigned pk2(float lo, float hi) { const f32x2v v = {lo, hi}; const bf16x2v r = __builtin_convertvector(v, bf16x2v); return __builtin_bit_cast(unsigned, r); }
; __device__ __forceinline__ float sigm(float x) { return __builtin_amdgcn_rcpf(1.f + __expf(-x)); }
; #define GEMM_EPI_LOOP _Pragma("unroll") for (int ai = 0; ai < 2; ++ai) _Pragma("unroll") for (int m = 0; m < 4; ++m) _Pragma("unroll") for (int bj = 0; bj < 2; ++bj)
; __device__ __forceinline__ void gemm_ple_phase(const bf16_t* a, const bf16_t* wpg, const bf16_t* pp, bf16_t* out, char* lds) {
;   gemm_phase(a, 1024, wpg, 1024, 1024, 4, lds, [&](f32x4 (&acc)[2][2][4][2], int tm, int tn) {
;     GEMM_LANE;
;     GEMM_EPI_LOOP {
;       const int row = tm * 256 + ai * 128 + wr * 64 + m * 16 + fr;
; #pragma unroll
;       for (int n = 0; n < 2; ++n) {
;         const int col = tn * 256 + bj * 128 + wc * 32 + n * 16 + 4 * fq;
;         const u32x2 pv = *(const u32x2*)(pp + (size_t)row * 1024 + col);
;         const f32x4 av = acc[ai][bj][m][n];
;         u32x2 o;
;         o.x = pk2(sigm(av[0]) * __uint_as_float(pv.x << 16), sigm(av[1]) * __uint_as_float(pv.x & 0xffff0000u));
;         o.y = pk2(sigm(av[2]) * __uint_as_float(pv.y << 16), sigm(av[3]) * __uint_as_float(pv.y & 0xffff0000u));
;         *(u32x2*)(out + (size_t)row * 1024 + col) = o;
;       }
;     }
;   });
; }
	v_permlane16_swap_b32_e32 v148, v150
	v_permlane16_swap_b32_e32 v149, v151
	v_lshlrev_b32_e32 v132, 16, v148
	v_and_b32_e32 v148, 0xffff0000, v148
	v_lshlrev_b32_e32 v133, 16, v149
	v_and_b32_e32 v149, 0xffff0000, v149
	v_mul_f32_e32 v116, v116, v132
	v_mul_f32_e32 v117, v117, v148
	v_mul_f32_e32 v118, v118, v133
	v_mul_f32_e32 v119, v119, v149
	v_lshlrev_b32_e32 v132, 16, v150
	v_and_b32_e32 v150, 0xffff0000, v150
	v_lshlrev_b32_e32 v133, 16, v151
	v_and_b32_e32 v151, 0xffff0000, v151
	v_mul_f32_e32 v112, v112, v132
	v_mul_f32_e32 v113, v113, v150
	v_mul_f32_e32 v114, v114, v133
	v_mul_f32_e32 v115, v115, v151
	v_cvt_pk_bf16_f32 v116, v116, v117
	v_cvt_pk_bf16_f32 v117, v118, v119
	v_cvt_pk_bf16_f32 v118, v112, v113
	v_cvt_pk_bf16_f32 v119, v114, v115
	s_nop 1
	v_permlane16_swap_b32_e32 v116, v118
	v_permlane16_swap_b32_e32 v117, v119
	global_store_dwordx4 v140, v[116:119], s[16:17] offset:256
	s_waitcnt vmcnt(15)
	v_permlane16_swap_b32_e32 v152, v154
	v_permlane16_swap_b32_e32 v153, v155
	v_lshlrev_b32_e32 v132, 16, v152
	v_and_b32_e32 v152, 0xffff0000, v152
	v_lshlrev_b32_e32 v133, 16, v153
	v_and_b32_e32 v153, 0xffff0000, v153
	v_mul_f32_e32 v108, v108, v132
	v_mul_f32_e32 v109, v109, v152
	v_mul_f32_e32 v110, v110, v133
	v_mul_f32_e32 v111, v111, v153
	v_lshlrev_b32_e32 v132, 16, v154
	v_and_b32_e32 v154, 0xffff0000, v154
	v_lshlrev_b32_e32 v133, 16, v155
	v_and_b32_e32 v155, 0xffff0000, v155
	v_mul_f32_e32 v104, v104, v132
	v_mul_f32_e32 v105, v105, v154
	v_mul_f32_e32 v106, v106, v133
	v_mul_f32_e32 v107, v107, v155
	v_cvt_pk_bf16_f32 v108, v108, v109
	v_cvt_pk_bf16_f32 v109, v110, v111
	v_cvt_pk_bf16_f32 v110, v104, v105
	v_cvt_pk_bf16_f32 v111, v106, v107
	s_nop 1
	v_permlane16_swap_b32_e32 v108, v110
	v_permlane16_swap_b32_e32 v109, v111
	global_store_dwordx4 v141, v[108:111], s[16:17]
	s_waitcnt vmcnt(15)
	v_permlane16_swap_b32_e32 v156, v158
	v_permlane16_swap_b32_e32 v157, v159
	v_lshlrev_b32_e32 v132, 16, v156
	v_and_b32_e32 v156, 0xffff0000, v156
	v_lshlrev_b32_e32 v133, 16, v157
	v_and_b32_e32 v157, 0xffff0000, v157
	v_mul_f32_e32 v100, v100, v132
	v_mul_f32_e32 v101, v101, v156
	v_mul_f32_e32 v102, v102, v133
	v_mul_f32_e32 v103, v103, v157
	v_lshlrev_b32_e32 v132, 16, v158
	v_and_b32_e32 v158, 0xffff0000, v158
	v_lshlrev_b32_e32 v133, 16, v159
	v_and_b32_e32 v159, 0xffff0000, v159
	v_mul_f32_e32 v96, v96, v132
	v_mul_f32_e32 v97, v97, v158
	v_mul_f32_e32 v98, v98, v133
	v_mul_f32_e32 v99, v99, v159
	v_cvt_pk_bf16_f32 v100, v100, v101
	v_cvt_pk_bf16_f32 v101, v102, v103
	v_cvt_pk_bf16_f32 v102, v96, v97
	v_cvt_pk_bf16_f32 v103, v98, v99
	s_nop 1
	v_permlane16_swap_b32_e32 v100, v102
	v_permlane16_swap_b32_e32 v101, v103
	global_store_dwordx4 v141, v[100:103], s[16:17] offset:256
	s_waitcnt vmcnt(15)
	v_permlane16_swap_b32_e32 v160, v162
	v_permlane16_swap_b32_e32 v161, v163
	v_lshlrev_b32_e32 v132, 16, v160
	v_and_b32_e32 v160, 0xffff0000, v160
	v_lshlrev_b32_e32 v133, 16, v161
	v_and_b32_e32 v161, 0xffff0000, v161
	v_mul_f32_e32 v92, v92, v132
	v_mul_f32_e32 v93, v93, v160
	v_mul_f32_e32 v94, v94, v133
	v_mul_f32_e32 v95, v95, v161
	v_lshlrev_b32_e32 v132, 16, v162
	v_and_b32_e32 v162, 0xffff0000, v162
	v_lshlrev_b32_e32 v133, 16, v163
	v_and_b32_e32 v163, 0xffff0000, v163
	v_mul_f32_e32 v88, v88, v132
	v_mul_f32_e32 v89, v89, v162
	v_mul_f32_e32 v90, v90, v133
	v_mul_f32_e32 v91, v91, v163
	v_cvt_pk_bf16_f32 v92, v92, v93
	v_cvt_pk_bf16_f32 v93, v94, v95
	v_cvt_pk_bf16_f32 v94, v88, v89
	v_cvt_pk_bf16_f32 v95, v90, v91
	s_nop 1
	v_permlane16_swap_b32_e32 v92, v94
	v_permlane16_swap_b32_e32 v93, v95
	global_store_dwordx4 v142, v[92:95], s[16:17]
	s_waitcnt vmcnt(15)
	v_permlane16_swap_b32_e32 v164, v166
	v_permlane16_swap_b32_e32 v165, v167
	v_lshlrev_b32_e32 v132, 16, v164
	v_and_b32_e32 v164, 0xffff0000, v164
	v_lshlrev_b32_e32 v133, 16, v165
	v_and_b32_e32 v165, 0xffff0000, v165
	v_mul_f32_e32 v84, v84, v132
	v_mul_f32_e32 v85, v85, v164
	v_mul_f32_e32 v86, v86, v133
	v_mul_f32_e32 v87, v87, v165
	v_lshlrev_b32_e32 v132, 16, v166
	v_and_b32_e32 v166, 0xffff0000, v166
	v_lshlrev_b32_e32 v133, 16, v167
	v_and_b32_e32 v167, 0xffff0000, v167
	v_mul_f32_e32 v80, v80, v132
	v_mul_f32_e32 v81, v81, v166
	v_mul_f32_e32 v82, v82, v133
	v_mul_f32_e32 v83, v83, v167
	v_cvt_pk_bf16_f32 v84, v84, v85
	v_cvt_pk_bf16_f32 v85, v86, v87
	v_cvt_pk_bf16_f32 v86, v80, v81
	v_cvt_pk_bf16_f32 v87, v82, v83
	s_nop 1
	v_permlane16_swap_b32_e32 v84, v86
	v_permlane16_swap_b32_e32 v85, v87
	global_store_dwordx4 v142, v[84:87], s[16:17] offset:256
	s_waitcnt vmcnt(15)
	v_permlane16_swap_b32_e32 v168, v170
	v_permlane16_swap_b32_e32 v169, v171
	v_lshlrev_b32_e32 v132, 16, v168
	v_and_b32_e32 v168, 0xffff0000, v168
	v_lshlrev_b32_e32 v133, 16, v169
	v_and_b32_e32 v169, 0xffff0000, v169
	v_mul_f32_e32 v76, v76, v132
	v_mul_f32_e32 v77, v77, v168
	v_mul_f32_e32 v78, v78, v133
	v_mul_f32_e32 v79, v79, v169
	v_lshlrev_b32_e32 v132, 16, v170
	v_and_b32_e32 v170, 0xffff0000, v170
	v_lshlrev_b32_e32 v133, 16, v171
	v_and_b32_e32 v171, 0xffff0000, v171
	v_mul_f32_e32 v72, v72, v132
	v_mul_f32_e32 v73, v73, v170
	v_mul_f32_e32 v74, v74, v133
	v_mul_f32_e32 v75, v75, v171
	v_cvt_pk_bf16_f32 v76, v76, v77
	v_cvt_pk_bf16_f32 v77, v78, v79
	v_cvt_pk_bf16_f32 v78, v72, v73
	v_cvt_pk_bf16_f32 v79, v74, v75
	s_nop 1
	v_permlane16_swap_b32_e32 v76, v78
	v_permlane16_swap_b32_e32 v77, v79
	global_store_dwordx4 v143, v[76:79], s[16:17]
	s_waitcnt vmcnt(15)
; __device__ __forceinline__ unsigned pk2(float lo, float hi) { const f32x2v v = {lo, hi}; const bf16x2v r = __builtin_convertvector(v, bf16x2v); return __builtin_bit_cast(unsigned, r); }
; __device__ __forceinline__ float sigm(float x) { return __builtin_amdgcn_rcpf(1.f + __expf(-x)); }
; #define GEMM_EPI_LOOP _Pragma("unroll") for (int ai = 0; ai < 2; ++ai) _Pragma("unroll") for (int m = 0; m < 4; ++m) _Pragma("unroll") for (int bj = 0; bj < 2; ++bj)
; __device__ __forceinline__ void gemm_ple_phase(const bf16_t* a, const bf16_t* wpg, const bf16_t* pp, bf16_t* out, char* lds) {
;   gemm_phase(a, 1024, wpg, 1024, 1024, 4, lds, [&](f32x4 (&acc)[2][2][4][2], int tm, int tn) {
;     GEMM_LANE;
;     GEMM_EPI_LOOP {
;       const int row = tm * 256 + ai * 128 + wr * 64 + m * 16 + fr;
; #pragma unroll
;       for (int n = 0; n < 2; ++n) {
;         const int col = tn * 256 + bj * 128 + wc * 32 + n * 16 + 4 * fq;
;         const u32x2 pv = *(const u32x2*)(pp + (size_t)row * 1024 + col);
;         const f32x4 av = acc[ai][bj][m][n];
;         u32x2 o;
;         o.x = pk2(sigm(av[0]) * __uint_as_float(pv.x << 16), sigm(av[1]) * __uint_as_float(pv.x & 0xffff0000u));
;         o.y = pk2(sigm(av[2]) * __uint_as_float(pv.y << 16), sigm(av[3]) * __uint_as_float(pv.y & 0xffff0000u));
;         *(u32x2*)(out + (size_t)row * 1024 + col) = o;
;       }
;     }
;   });
; }
	v_permlane16_swap_b32_e32 v172, v174
	v_permlane16_swap_b32_e32 v173, v175
	v_lshlrev_b32_e32 v132, 16, v172
	v_and_b32_e32 v172, 0xffff0000, v172
	v_lshlrev_b32_e32 v133, 16, v173
	v_and_b32_e32 v173, 0xffff0000, v173
	v_mul_f32_e32 v68, v68, v132
	v_mul_f32_e32 v69, v69, v172
	v_mul_f32_e32 v70, v70, v133
	v_mul_f32_e32 v71, v71, v173
	v_lshlrev_b32_e32 v132, 16, v174
	v_and_b32_e32 v174, 0xffff0000, v174
	v_lshlrev_b32_e32 v133, 16, v175
	v_and_b32_e32 v175, 0xffff0000, v175
	v_mul_f32_e32 v64, v64, v132
	v_mul_f32_e32 v65, v65, v174
	v_mul_f32_e32 v66, v66, v133
	v_mul_f32_e32 v67, v67, v175
	v_cvt_pk_bf16_f32 v68, v68, v69
	v_cvt_pk_bf16_f32 v69, v70, v71
	v_cvt_pk_bf16_f32 v70, v64, v65
	v_cvt_pk_bf16_f32 v71, v66, v67
	s_nop 1
	v_permlane16_swap_b32_e32 v68, v70
	v_permlane16_swap_b32_e32 v69, v71
	global_store_dwordx4 v143, v[68:71], s[16:17] offset:256
	s_waitcnt vmcnt(15)
	v_permlane16_swap_b32_e32 v180, v182
	v_permlane16_swap_b32_e32 v181, v183
	v_lshlrev_b32_e32 v132, 16, v180
	v_and_b32_e32 v180, 0xffff0000, v180
	v_lshlrev_b32_e32 v133, 16, v181
	v_and_b32_e32 v181, 0xffff0000, v181
	v_mul_f32_e32 v60, v60, v132
	v_mul_f32_e32 v61, v61, v180
	v_mul_f32_e32 v62, v62, v133
	v_mul_f32_e32 v63, v63, v181
	v_lshlrev_b32_e32 v132, 16, v182
	v_and_b32_e32 v182, 0xffff0000, v182
	v_lshlrev_b32_e32 v133, 16, v183
	v_and_b32_e32 v183, 0xffff0000, v183
	v_mul_f32_e32 v56, v56, v132
	v_mul_f32_e32 v57, v57, v182
	v_mul_f32_e32 v58, v58, v133
	v_mul_f32_e32 v59, v59, v183
	v_cvt_pk_bf16_f32 v60, v60, v61
	v_cvt_pk_bf16_f32 v61, v62, v63
	v_cvt_pk_bf16_f32 v62, v56, v57
	v_cvt_pk_bf16_f32 v63, v58, v59
	s_nop 1
	v_permlane16_swap_b32_e32 v60, v62
	v_permlane16_swap_b32_e32 v61, v63
	global_store_dwordx4 v144, v[60:63], s[16:17]
	s_waitcnt vmcnt(15)
	v_permlane16_swap_b32_e32 v184, v186
	v_permlane16_swap_b32_e32 v185, v187
	v_lshlrev_b32_e32 v132, 16, v184
	v_and_b32_e32 v184, 0xffff0000, v184
	v_lshlrev_b32_e32 v133, 16, v185
	v_and_b32_e32 v185, 0xffff0000, v185
	v_mul_f32_e32 v52, v52, v132
	v_mul_f32_e32 v53, v53, v184
	v_mul_f32_e32 v54, v54, v133
	v_mul_f32_e32 v55, v55, v185
	v_lshlrev_b32_e32 v132, 16, v186
	v_and_b32_e32 v186, 0xffff0000, v186
	v_lshlrev_b32_e32 v133, 16, v187
	v_and_b32_e32 v187, 0xffff0000, v187
	v_mul_f32_e32 v48, v48, v132
	v_mul_f32_e32 v49, v49, v186
	v_mul_f32_e32 v50, v50, v133
	v_mul_f32_e32 v51, v51, v187
	v_cvt_pk_bf16_f32 v52, v52, v53
	v_cvt_pk_bf16_f32 v53, v54, v55
	v_cvt_pk_bf16_f32 v54, v48, v49
	v_cvt_pk_bf16_f32 v55, v50, v51
	s_nop 1
	v_permlane16_swap_b32_e32 v52, v54
	v_permlane16_swap_b32_e32 v53, v55
	global_store_dwordx4 v144, v[52:55], s[16:17] offset:256
	s_waitcnt vmcnt(15)
	v_permlane16_swap_b32_e32 v188, v190
	v_permlane16_swap_b32_e32 v189, v191
	v_lshlrev_b32_e32 v132, 16, v188
	v_and_b32_e32 v188, 0xffff0000, v188
	v_lshlrev_b32_e32 v133, 16, v189
	v_and_b32_e32 v189, 0xffff0000, v189
	v_mul_f32_e32 v44, v44, v132
	v_mul_f32_e32 v45, v45, v188
	v_mul_f32_e32 v46, v46, v133
	v_mul_f32_e32 v47, v47, v189
	v_lshlrev_b32_e32 v132, 16, v190
	v_and_b32_e32 v190, 0xffff0000, v190
	v_lshlrev_b32_e32 v133, 16, v191
	v_and_b32_e32 v191, 0xffff0000, v191
	v_mul_f32_e32 v40, v40, v132
	v_mul_f32_e32 v41, v41, v190
	v_mul_f32_e32 v42, v42, v133
	v_mul_f32_e32 v43, v43, v191
	v_cvt_pk_bf16_f32 v44, v44, v45
	v_cvt_pk_bf16_f32 v45, v46, v47
	v_cvt_pk_bf16_f32 v46, v40, v41
	v_cvt_pk_bf16_f32 v47, v42, v43
	s_nop 1
	v_permlane16_swap_b32_e32 v44, v46
	v_permlane16_swap_b32_e32 v45, v47
	global_store_dwordx4 v145, v[44:47], s[16:17]
	s_waitcnt vmcnt(15)
	v_permlane16_swap_b32_e32 v192, v194
	v_permlane16_swap_b32_e32 v193, v195
	v_lshlrev_b32_e32 v132, 16, v192
	v_and_b32_e32 v192, 0xffff0000, v192
	v_lshlrev_b32_e32 v133, 16, v193
	v_and_b32_e32 v193, 0xffff0000, v193
	v_mul_f32_e32 v36, v36, v132
	v_mul_f32_e32 v37, v37, v192
	v_mul_f32_e32 v38, v38, v133
	v_mul_f32_e32 v39, v39, v193
	v_lshlrev_b32_e32 v132, 16, v194
	v_and_b32_e32 v194, 0xffff0000, v194
	v_lshlrev_b32_e32 v133, 16, v195
	v_and_b32_e32 v195, 0xffff0000, v195
	v_mul_f32_e32 v32, v32, v132
	v_mul_f32_e32 v33, v33, v194
	v_mul_f32_e32 v34, v34, v133
	v_mul_f32_e32 v35, v35, v195
	v_cvt_pk_bf16_f32 v36, v36, v37
	v_cvt_pk_bf16_f32 v37, v38, v39
	v_cvt_pk_bf16_f32 v38, v32, v33
	v_cvt_pk_bf16_f32 v39, v34, v35
	s_nop 1
	v_permlane16_swap_b32_e32 v36, v38
	v_permlane16_swap_b32_e32 v37, v39
	global_store_dwordx4 v145, v[36:39], s[16:17] offset:256
	s_waitcnt vmcnt(15)
; __device__ __forceinline__ unsigned pk2(float lo, float hi) { const f32x2v v = {lo, hi}; const bf16x2v r = __builtin_convertvector(v, bf16x2v); return __builtin_bit_cast(unsigned, r); }
; __device__ __forceinline__ float sigm(float x) { return __builtin_amdgcn_rcpf(1.f + __expf(-x)); }
; #define GEMM_EPI_LOOP _Pragma("unroll") for (int ai = 0; ai < 2; ++ai) _Pragma("unroll") for (int m = 0; m < 4; ++m) _Pragma("unroll") for (int bj = 0; bj < 2; ++bj)
; __device__ __forceinline__ void gemm_ple_phase(const bf16_t* a, const bf16_t* wpg, const bf16_t* pp, bf16_t* out, char* lds) {
;   gemm_phase(a, 1024, wpg, 1024, 1024, 4, lds, [&](f32x4 (&acc)[2][2][4][2], int tm, int tn) {
;     GEMM_LANE;
;     GEMM_EPI_LOOP {
;       const int row = tm * 256 + ai * 128 + wr * 64 + m * 16 + fr;
; #pragma unroll
;       for (int n = 0; n < 2; ++n) {
;         const int col = tn * 256 + bj * 128 + wc * 32 + n * 16 + 4 * fq;
;         const u32x2 pv = *(const u32x2*)(pp + (size_t)row * 1024 + col);
;         const f32x4 av = acc[ai][bj][m][n];
;         u32x2 o;
;         o.x = pk2(sigm(av[0]) * __uint_as_float(pv.x << 16), sigm(av[1]) * __uint_as_float(pv.x & 0xffff0000u));
;         o.y = pk2(sigm(av[2]) * __uint_as_float(pv.y << 16), sigm(av[3]) * __uint_as_float(pv.y & 0xffff0000u));
;         *(u32x2*)(out + (size_t)row * 1024 + col) = o;
;       }
;     }
;   });
; }
	v_permlane16_swap_b32_e32 v196, v198
	v_permlane16_swap_b32_e32 v197, v199
	v_lshlrev_b32_e32 v132, 16, v196
	v_and_b32_e32 v196, 0xffff0000, v196
	v_lshlrev_b32_e32 v133, 16, v197
	v_and_b32_e32 v197, 0xffff0000, v197
	v_mul_f32_e32 v28, v28, v132
	v_mul_f32_e32 v29, v29, v196
	v_mul_f32_e32 v30, v30, v133
	v_mul_f32_e32 v31, v31, v197
	v_lshlrev_b32_e32 v132, 16, v198
	v_and_b32_e32 v198, 0xffff0000, v198
	v_lshlrev_b32_e32 v133, 16, v199
	v_and_b32_e32 v199, 0xffff0000, v199
	v_mul_f32_e32 v24, v24, v132
	v_mul_f32_e32 v25, v25, v198
	v_mul_f32_e32 v26, v26, v133
	v_mul_f32_e32 v27, v27, v199
	v_cvt_pk_bf16_f32 v28, v28, v29
	v_cvt_pk_bf16_f32 v29, v30, v31
	v_cvt_pk_bf16_f32 v30, v24, v25
	v_cvt_pk_bf16_f32 v31, v26, v27
	s_nop 1
	v_permlane16_swap_b32_e32 v28, v30
	v_permlane16_swap_b32_e32 v29, v31
	global_store_dwordx4 v146, v[28:31], s[16:17]
	s_waitcnt vmcnt(15)
	v_permlane16_swap_b32_e32 v200, v202
	v_permlane16_swap_b32_e32 v201, v203
	v_lshlrev_b32_e32 v132, 16, v200
	v_and_b32_e32 v200, 0xffff0000, v200
	v_lshlrev_b32_e32 v133, 16, v201
	v_and_b32_e32 v201, 0xffff0000, v201
	v_mul_f32_e32 v20, v20, v132
	v_mul_f32_e32 v21, v21, v200
	v_mul_f32_e32 v22, v22, v133
	v_mul_f32_e32 v23, v23, v201
	v_lshlrev_b32_e32 v132, 16, v202
	v_and_b32_e32 v202, 0xffff0000, v202
	v_lshlrev_b32_e32 v133, 16, v203
	v_and_b32_e32 v203, 0xffff0000, v203
	v_mul_f32_e32 v16, v16, v132
	v_mul_f32_e32 v17, v17, v202
	v_mul_f32_e32 v18, v18, v133
	v_mul_f32_e32 v19, v19, v203
	v_cvt_pk_bf16_f32 v20, v20, v21
	v_cvt_pk_bf16_f32 v21, v22, v23
	v_cvt_pk_bf16_f32 v22, v16, v17
	v_cvt_pk_bf16_f32 v23, v18, v19
	s_nop 1
	v_permlane16_swap_b32_e32 v20, v22
	v_permlane16_swap_b32_e32 v21, v23
	global_store_dwordx4 v146, v[20:23], s[16:17] offset:256
	s_waitcnt vmcnt(15)
	v_permlane16_swap_b32_e32 v204, v206
	v_permlane16_swap_b32_e32 v205, v207
	v_lshlrev_b32_e32 v132, 16, v204
	v_and_b32_e32 v204, 0xffff0000, v204
	v_lshlrev_b32_e32 v133, 16, v205
	v_and_b32_e32 v205, 0xffff0000, v205
	v_mul_f32_e32 v12, v12, v132
	v_mul_f32_e32 v13, v13, v204
	v_mul_f32_e32 v14, v14, v133
	v_mul_f32_e32 v15, v15, v205
	v_lshlrev_b32_e32 v132, 16, v206
	v_and_b32_e32 v206, 0xffff0000, v206
	v_lshlrev_b32_e32 v133, 16, v207
	v_and_b32_e32 v207, 0xffff0000, v207
	v_mul_f32_e32 v8, v8, v132
	v_mul_f32_e32 v9, v9, v206
	v_mul_f32_e32 v10, v10, v133
	v_mul_f32_e32 v11, v11, v207
	v_cvt_pk_bf16_f32 v12, v12, v13
	v_cvt_pk_bf16_f32 v13, v14, v15
	v_cvt_pk_bf16_f32 v14, v8, v9
	v_cvt_pk_bf16_f32 v15, v10, v11
	s_nop 1
	v_permlane16_swap_b32_e32 v12, v14
	v_permlane16_swap_b32_e32 v13, v15
	global_store_dwordx4 v147, v[12:15], s[16:17]
	s_waitcnt vmcnt(15)
	v_permlane16_swap_b32_e32 v208, v210
	v_permlane16_swap_b32_e32 v209, v211
	v_lshlrev_b32_e32 v132, 16, v208
	v_and_b32_e32 v208, 0xffff0000, v208
	v_lshlrev_b32_e32 v133, 16, v209
	v_and_b32_e32 v209, 0xffff0000, v209
	v_mul_f32_e32 v4, v4, v132
	v_mul_f32_e32 v5, v5, v208
	v_mul_f32_e32 v6, v6, v133
	v_mul_f32_e32 v7, v7, v209
	v_lshlrev_b32_e32 v132, 16, v210
	v_and_b32_e32 v210, 0xffff0000, v210
	v_lshlrev_b32_e32 v133, 16, v211
	v_and_b32_e32 v211, 0xffff0000, v211
	v_mul_f32_e32 v0, v0, v132
	v_mul_f32_e32 v1, v1, v210
	v_mul_f32_e32 v2, v2, v133
	v_mul_f32_e32 v3, v3, v211
	v_cvt_pk_bf16_f32 v4, v4, v5
	v_cvt_pk_bf16_f32 v5, v6, v7
	v_cvt_pk_bf16_f32 v6, v0, v1
	v_cvt_pk_bf16_f32 v7, v2, v3
	s_nop 1
	v_permlane16_swap_b32_e32 v4, v6
	v_permlane16_swap_b32_e32 v5, v7
	global_store_dwordx4 v147, v[4:7], s[16:17] offset:256
	s_andn2_b64 vcc, exec, s[38:39]
	s_mov_b32 s42, s34
	s_mov_b32 s30, s36
	s_nop 1
	s_cbranch_vccz .LBB0_86

; __device__ __forceinline__ float bf2f(bf16_t v) { return __uint_as_float(((unsigned)v) << 16); }
; __device__ __forceinline__ unsigned pk2(float lo, float hi) { const f32x2v v = {lo, hi}; const bf16x2v r = __builtin_convertvector(v, bf16x2v); return __builtin_bit_cast(unsigned, r); }
; __device__ __forceinline__ float sigm(float x) { return __builtin_amdgcn_rcpf(1.f + __expf(-x)); }
; __device__ __forceinline__ void nsa_item(const Params& P, int b, int g, int c, const bf16_t* z, const bf16_t* kcv, bf16_t* y, char* lds) {
;     ...
; #pragma unroll
;   for (int r = 0; r < 2; ++r) {
;     const float gt = sigm(bf2f(zq[ZC_GC + hb + r]));
; #pragma unroll
;     for (int df = 0; df < 4; ++df) { u32x2 o; o.x = pk2(O[df][r][0] * gt, O[df][r][1] * gt); o.y = pk2(O[df][r][2] * gt, O[df][r][3] * gt); *(u32x2*)(yo + r * 64 + df * 16) = o; }
;   }
.LBB0_336:
	v_readlane_b32 s16, v252, 34
	s_waitcnt vmcnt(1)
	v_lshlrev_b64 v[48:49], 11, v[150:151]
	v_readlane_b32 s17, v252, 35
	s_lshl_b32 s46, s64, 1
	s_lshl_b32 s0, s63, 2
	v_lshl_add_u64 v[48:49], s[16:17], 0, v[48:49]
	v_lshl_add_u64 v[48:49], v[48:49], 0, s[46:47]
	v_lshl_add_u64 v[48:49], v[152:153], 1, v[48:49]
	v_lshlrev_b32_e32 v176, 3, v182
	v_lshl_add_u64 v[182:183], v[48:49], 0, v[176:177]
	v_lshl_add_u32 v48, v172, 1, s0
	v_ashrrev_i32_e32 v49, 31, v48
	v_lshl_add_u64 v[184:185], v[48:49], 1, v[148:149]
	s_movk_i32 s0, 0x1000
	v_add_co_u32_e32 v48, vcc, s0, v184
	s_add_i32 s0, s62, 1
	s_nop 0
	v_addc_co_u32_e32 v49, vcc, 0, v185, vcc
	global_load_ushort v50, v[48:49], off offset:512
	global_load_ushort v232, v[48:49], off offset:514
	s_lshl_b64 s[0:1], -1, s0
	s_not_b64 s[0:1], s[0:1]
	s_cmp_lt_i32 s62, 63
	s_cselect_b32 s31, s1, -1
	s_cselect_b32 s30, s0, -1
	s_add_i32 s0, s62, -1
	v_cmp_eq_u32_e32 vcc, s62, v188
	v_cmp_eq_u32_e64 s[0:1], s0, v188
	v_cmp_eq_u32_e64 s[36:37], 0, v188
	s_or_b64 s[0:1], vcc, s[0:1]
	s_or_b64 s[38:39], s[36:37], s[0:1]
	s_mov_b32 s0, 0x23240
	s_cmp_gt_i32 s62, 15
	s_mov_b32 s64, 0
	s_cselect_b64 s[34:35], -1, 0
	s_mov_b64 s[42:43], 0
	s_waitcnt vmcnt(0)
	v_lshlrev_b32_e32 v50, 16, v50
	v_mul_f32_e32 v50, 0xbfb8aa3b, v50
	v_exp_f32_e32 v50, v50
	s_nop 0
	v_add_f32_e32 v50, 1.0, v50
	v_rcp_f32_e32 v50, v50
	s_nop 0
	v_pk_mul_f32 v[44:45], v[44:45], v[50:51] op_sel_hi:[1,0]
	v_pk_mul_f32 v[46:47], v[46:47], v[50:51] op_sel_hi:[1,0]
	v_pk_mul_f32 v[40:41], v[40:41], v[50:51] op_sel_hi:[1,0]
	v_pk_mul_f32 v[42:43], v[42:43], v[50:51] op_sel_hi:[1,0]
	v_pk_mul_f32 v[36:37], v[36:37], v[50:51] op_sel_hi:[1,0]
	v_pk_mul_f32 v[38:39], v[38:39], v[50:51] op_sel_hi:[1,0]
	v_pk_mul_f32 v[32:33], v[32:33], v[50:51] op_sel_hi:[1,0]
	v_pk_mul_f32 v[34:35], v[34:35], v[50:51] op_sel_hi:[1,0]
	v_cvt_pk_bf16_f32 v44, v44, v45
	v_cvt_pk_bf16_f32 v45, v46, v47
	v_cvt_pk_bf16_f32 v40, v40, v41
	v_cvt_pk_bf16_f32 v41, v42, v43
	v_cvt_pk_bf16_f32 v36, v36, v37
	v_cvt_pk_bf16_f32 v37, v38, v39
	v_cvt_pk_bf16_f32 v32, v32, v33
	v_cvt_pk_bf16_f32 v33, v34, v35
	global_store_dwordx2 v[182:183], v[44:45], off offset:1024
	global_store_dwordx2 v[182:183], v[40:41], off offset:1056
	global_store_dwordx2 v[182:183], v[36:37], off offset:1088
	global_store_dwordx2 v[182:183], v[32:33], off offset:1120
	v_mov_b32_e32 v32, v232
	v_mov_b32_e32 v232, 6
	v_lshlrev_b32_e32 v32, 16, v32
	v_mul_f32_e32 v32, 0xbfb8aa3b, v32
	v_exp_f32_e32 v32, v32
	s_nop 0
	v_add_f32_e32 v32, 1.0, v32
	v_rcp_f32_e32 v32, v32
	s_nop 0
	v_pk_mul_f32 v[20:21], v[20:21], v[32:33] op_sel_hi:[1,0]
	v_pk_mul_f32 v[22:23], v[22:23], v[32:33] op_sel_hi:[1,0]
	v_cvt_pk_bf16_f32 v20, v20, v21
	v_cvt_pk_bf16_f32 v21, v22, v23
	global_store_dwordx2 v[182:183], v[20:21], off offset:1216
	v_pk_mul_f32 v[16:17], v[16:17], v[32:33] op_sel_hi:[1,0]
	v_pk_mul_f32 v[18:19], v[18:19], v[32:33] op_sel_hi:[1,0]
	v_lshlrev_b32_e32 v20, 7, v186
	v_lshlrev_b32_e32 v21, 6, v172
	v_cvt_pk_bf16_f32 v16, v16, v17
	v_cvt_pk_bf16_f32 v17, v18, v19
	v_add3_u32 v20, v20, v21, s0
	v_mul_i32_i24_e32 v21, 0x820, v172
	s_movk_i32 s0, 0x1040
	v_pk_mul_f32 v[28:29], v[28:29], v[32:33] op_sel_hi:[1,0]
	v_pk_mul_f32 v[30:31], v[30:31], v[32:33] op_sel_hi:[1,0]
	v_pk_mul_f32 v[24:25], v[24:25], v[32:33] op_sel_hi:[1,0]
	v_pk_mul_f32 v[26:27], v[26:27], v[32:33] op_sel_hi:[1,0]
	global_store_dwordx2 v[182:183], v[16:17], off offset:1248
	v_lshlrev_b64 v[16:17], v188, -1
	v_mad_u32_u24 v21, v186, s0, v21
	s_mov_b32 s0, 0x1f100
	v_cvt_pk_bf16_f32 v28, v28, v29
	v_cvt_pk_bf16_f32 v29, v30, v31
	v_cvt_pk_bf16_f32 v24, v24, v25
	v_cvt_pk_bf16_f32 v25, v26, v27
	v_not_b32_e32 v17, v17
	v_not_b32_e32 v16, v16
	v_lshlrev_b64 v[18:19], v188, 1
	v_add3_u32 v21, v21, v187, s0
	global_store_dwordx2 v[182:183], v[28:29], off offset:1152
	global_store_dwordx2 v[182:183], v[24:25], off offset:1184
	s_barrier
	s_branch .LBB0_338

; __device__ __forceinline__ void nsa_item(const Params& P, int b, int g, int c, const bf16_t* z, const bf16_t* kcv, bf16_t* y, char* lds) {
;     ...
;     for (int q8 = 0; q8 < 8; ++q8) {
;       const int qq = hp * 8 + q8;
;       const float sv = imp0[qq * 65 + lane] + imp1[qq * 65 + lane];
;       const unsigned u = __float_as_uint(forced ? 1e4f : sv);
;       u64 mk = V;
;       if (c + 1 > 16) {
;         unsigned thr = 0u;
;     ...
;         const u64 G = __ballot(u > thr) & V, E = __ballot(u == thr) & V;
;         const int need = 16 - (int)__popcll(G);
;         const int below = (int)__popcll(E & ((1ull << lane) - 1ull));
;         const bool se = (((E >> lane) & 1ull) != 0ull) && (below < need);
;         mk = G | __ballot(se);
;       }
.LBB0_338:
	s_andn2_b64 vcc, exec, s[34:35]
	s_mov_b64 s[0:1], s[30:31]
	s_cbranch_vccnz .LBB0_340
	v_add_u32_e32 v22, 0xffffbf00, v21
	ds_read_b32 v22, v22
	ds_read_b32 v23, v21
	s_brev_b32 s0, -4
	s_waitcnt lgkmcnt(0)
	v_add_f32_e32 v22, v22, v23
	v_cndmask_b32_e64 v22, v22, v226, s[38:39]
	v_cmp_lt_u32_e32 vcc, s0, v22
	s_and_b64 s[0:1], vcc, s[30:31]
	s_bcnt1_i32_b64 s46, s[0:1]
	s_cmp_gt_u32 s46, 15
	s_cselect_b32 s16, 2.0, 0
	s_or_b32 s17, s16, 0x20000000
	v_cmp_le_u32_e32 vcc, s17, v22
	s_and_b64 s[0:1], vcc, s[30:31]
	s_bcnt1_i32_b64 s46, s[0:1]
	s_cmp_gt_u32 s46, 15
	s_cselect_b32 s16, s17, s16
	s_or_b32 s17, s16, 0x10000000
	v_cmp_le_u32_e32 vcc, s17, v22
	s_and_b64 s[0:1], vcc, s[30:31]
	s_bcnt1_i32_b64 s46, s[0:1]
	s_cmp_gt_u32 s46, 15
	s_cselect_b32 s16, s17, s16
	s_or_b32 s17, s16, 0x8000000
	v_cmp_le_u32_e32 vcc, s17, v22
	s_and_b64 s[0:1], vcc, s[30:31]
	s_bcnt1_i32_b64 s46, s[0:1]
	s_cmp_gt_u32 s46, 15
	s_cselect_b32 s16, s17, s16
	s_or_b32 s17, s16, 0x4000000
	v_cmp_le_u32_e32 vcc, s17, v22
	s_and_b64 s[0:1], vcc, s[30:31]
	s_bcnt1_i32_b64 s46, s[0:1]
	s_cmp_gt_u32 s46, 15
	s_cselect_b32 s16, s17, s16
	s_or_b32 s17, s16, 0x2000000
	v_cmp_le_u32_e32 vcc, s17, v22
	s_and_b64 s[0:1], vcc, s[30:31]
	s_bcnt1_i32_b64 s46, s[0:1]
	s_cmp_gt_u32 s46, 15
	s_cselect_b32 s16, s17, s16
	s_or_b32 s17, s16, 0x1000000
	v_cmp_le_u32_e32 vcc, s17, v22
	s_and_b64 s[0:1], vcc, s[30:31]
	s_bcnt1_i32_b64 s46, s[0:1]
	s_cmp_gt_u32 s46, 15
	s_cselect_b32 s16, s17, s16
	s_or_b32 s17, s16, 0x800000
	v_cmp_le_u32_e32 vcc, s17, v22
	s_and_b64 s[0:1], vcc, s[30:31]
	s_bcnt1_i32_b64 s46, s[0:1]
	s_cmp_gt_u32 s46, 15
	s_cselect_b32 s16, s17, s16
	s_or_b32 s17, s16, 0x400000
	v_cmp_le_u32_e32 vcc, s17, v22
	s_and_b64 s[0:1], vcc, s[30:31]
	s_bcnt1_i32_b64 s46, s[0:1]
	s_cmp_gt_u32 s46, 15
	s_cselect_b32 s16, s17, s16
	s_or_b32 s17, s16, 0x200000
	v_cmp_le_u32_e32 vcc, s17, v22
	s_and_b64 s[0:1], vcc, s[30:31]
	s_bcnt1_i32_b64 s46, s[0:1]
	s_cmp_gt_u32 s46, 15
	s_cselect_b32 s16, s17, s16
	s_or_b32 s17, s16, 0x100000
	v_cmp_le_u32_e32 vcc, s17, v22
	s_and_b64 s[0:1], vcc, s[30:31]
	s_bcnt1_i32_b64 s46, s[0:1]
	s_cmp_gt_u32 s46, 15
	s_cselect_b32 s16, s17, s16
	s_or_b32 s17, s16, 0x80000
	v_cmp_le_u32_e32 vcc, s17, v22
	s_and_b64 s[0:1], vcc, s[30:31]
	s_bcnt1_i32_b64 s46, s[0:1]
	s_cmp_gt_u32 s46, 15
	s_cselect_b32 s16, s17, s16
	s_or_b32 s17, s16, 0x40000
	v_cmp_le_u32_e32 vcc, s17, v22
	s_and_b64 s[0:1], vcc, s[30:31]
	s_bcnt1_i32_b64 s46, s[0:1]
	s_cmp_gt_u32 s46, 15
	s_cselect_b32 s16, s17, s16
	s_or_b32 s17, s16, 0x20000
	v_cmp_le_u32_e32 vcc, s17, v22
	s_and_b64 s[0:1], vcc, s[30:31]
	s_bcnt1_i32_b64 s46, s[0:1]
	s_cmp_gt_u32 s46, 15
	s_cselect_b32 s16, s17, s16
	s_or_b32 s17, s16, 0x10000
	v_cmp_le_u32_e32 vcc, s17, v22
	s_and_b64 s[0:1], vcc, s[30:31]
	s_bcnt1_i32_b64 s46, s[0:1]
	s_cmp_gt_u32 s46, 15
	s_cselect_b32 s16, s17, s16
	s_or_b32 s17, s16, 0x8000
	v_cmp_le_u32_e32 vcc, s17, v22
	s_and_b64 s[0:1], vcc, s[30:31]
	s_bcnt1_i32_b64 s46, s[0:1]
	s_cmp_gt_u32 s46, 15
	s_cselect_b32 s16, s17, s16
	s_or_b32 s17, s16, 0x4000
	v_cmp_le_u32_e32 vcc, s17, v22
	s_and_b64 s[0:1], vcc, s[30:31]
	s_bcnt1_i32_b64 s46, s[0:1]
	s_cmp_gt_u32 s46, 15
	s_cselect_b32 s16, s17, s16
	s_or_b32 s17, s16, 0x2000
	v_cmp_le_u32_e32 vcc, s17, v22
	s_and_b64 s[0:1], vcc, s[30:31]
	s_bcnt1_i32_b64 s46, s[0:1]
	s_cmp_gt_u32 s46, 15
	s_cselect_b32 s16, s17, s16
	s_or_b32 s17, s16, 0x1000
	v_cmp_le_u32_e32 vcc, s17, v22
	s_and_b64 s[0:1], vcc, s[30:31]
	s_bcnt1_i32_b64 s46, s[0:1]
	s_cmp_gt_u32 s46, 15
	s_cselect_b32 s16, s17, s16
	s_or_b32 s17, s16, 0x800
	v_cmp_le_u32_e32 vcc, s17, v22
	s_and_b64 s[0:1], vcc, s[30:31]
	s_bcnt1_i32_b64 s46, s[0:1]
	s_cmp_gt_u32 s46, 15
	s_cselect_b32 s16, s17, s16
	s_or_b32 s17, s16, 0x400
	v_cmp_le_u32_e32 vcc, s17, v22
	s_and_b64 s[0:1], vcc, s[30:31]
	s_bcnt1_i32_b64 s46, s[0:1]
	s_cmp_gt_u32 s46, 15
	s_cselect_b32 s16, s17, s16
	s_or_b32 s17, s16, 0x200
	v_cmp_le_u32_e32 vcc, s17, v22
	s_and_b64 s[0:1], vcc, s[30:31]
	s_bcnt1_i32_b64 s46, s[0:1]
	s_cmp_gt_u32 s46, 15
	s_cselect_b32 s16, s17, s16
	s_or_b32 s17, s16, 0x100
	v_cmp_le_u32_e32 vcc, s17, v22
	s_and_b64 s[0:1], vcc, s[30:31]
	s_bcnt1_i32_b64 s46, s[0:1]
	s_cmp_gt_u32 s46, 15
	s_cselect_b32 s16, s17, s16
	s_or_b32 s17, s16, 0x80
	v_cmp_le_u32_e32 vcc, s17, v22
	s_and_b64 s[0:1], vcc, s[30:31]
	s_bcnt1_i32_b64 s46, s[0:1]
	s_cmp_gt_u32 s46, 15
	s_cselect_b32 s16, s17, s16
	s_or_b32 s17, s16, 64
	v_cmp_le_u32_e32 vcc, s17, v22
	s_and_b64 s[0:1], vcc, s[30:31]
	s_bcnt1_i32_b64 s46, s[0:1]
	s_cmp_gt_u32 s46, 15
	s_cselect_b32 s16, s17, s16
	s_or_b32 s17, s16, 32
	v_cmp_le_u32_e32 vcc, s17, v22
	s_and_b64 s[0:1], vcc, s[30:31]
	s_bcnt1_i32_b64 s46, s[0:1]
	s_cmp_gt_u32 s46, 15
	s_cselect_b32 s16, s17, s16
	s_or_b32 s17, s16, 16
	v_cmp_le_u32_e32 vcc, s17, v22
	s_and_b64 s[0:1], vcc, s[30:31]
	s_bcnt1_i32_b64 s46, s[0:1]
	s_cmp_gt_u32 s46, 15
	s_cselect_b32 s16, s17, s16
	s_or_b32 s17, s16, 8
	v_cmp_le_u32_e32 vcc, s17, v22
	s_and_b64 s[0:1], vcc, s[30:31]
	s_bcnt1_i32_b64 s46, s[0:1]
	s_cmp_gt_u32 s46, 15
	s_cselect_b32 s16, s17, s16
	s_or_b32 s17, s16, 4
	v_cmp_le_u32_e32 vcc, s17, v22
	s_and_b64 s[0:1], vcc, s[30:31]
	s_bcnt1_i32_b64 s46, s[0:1]
	s_cmp_gt_u32 s46, 15
	s_cselect_b32 s16, s17, s16
	s_or_b32 s17, s16, 2
	v_cmp_le_u32_e32 vcc, s17, v22
	s_and_b64 s[0:1], vcc, s[30:31]
	s_bcnt1_i32_b64 s46, s[0:1]
	s_cmp_gt_u32 s46, 15
	s_cselect_b32 s16, s17, s16
	s_or_b32 s17, s16, 1
	v_cmp_le_u32_e32 vcc, s17, v22
	s_and_b64 s[0:1], vcc, s[30:31]
	s_bcnt1_i32_b64 s46, s[0:1]
	v_cmp_gt_u64_e64 s[0:1], s[46:47], 15
	s_and_b64 s[0:1], s[0:1], exec
	s_cselect_b32 s0, s17, s16
	v_cmp_lt_u32_e32 vcc, s0, v22
	v_cmp_eq_u32_e64 s[0:1], s0, v22
	s_and_b64 s[0:1], s[0:1], s[30:31]
	s_and_b64 s[16:17], vcc, s[30:31]
	v_and_b32_e32 v22, s0, v16
	s_bcnt1_i32_b64 s46, s[16:17]
	v_and_b32_e32 v23, s1, v17
	v_bcnt_u32_b32 v22, v22, 0
	s_sub_i32 s46, 16, s46
	v_bcnt_u32_b32 v24, v23, v22
	v_and_b32_e32 v23, s1, v19
	v_and_b32_e32 v22, s0, v18
	v_cmp_ne_u64_e32 vcc, 0, v[22:23]
	v_cmp_gt_i32_e64 s[0:1], s46, v24
	s_and_b64 s[0:1], vcc, s[0:1]
	s_nop 0
	v_cndmask_b32_e64 v22, 0, 1, s[0:1]
	v_cmp_ne_u32_e32 vcc, 0, v22
	s_or_b64 s[0:1], vcc, s[16:17]

; __device__ __forceinline__ float bf2f(bf16_t v) { return __uint_as_float(((unsigned)v) << 16); }
; __device__ __forceinline__ unsigned pk2(float lo, float hi) { const f32x2v v = {lo, hi}; const bf16x2v r = __builtin_convertvector(v, bf16x2v); return __builtin_bit_cast(unsigned, r); }
; __device__ __forceinline__ float sigm(float x) { return __builtin_amdgcn_rcpf(1.f + __expf(-x)); }
; __device__ __forceinline__ void nsa_item(const Params& P, int b, int g, int c, const bf16_t* z, const bf16_t* kcv, bf16_t* y, char* lds) {
;     ...
; #pragma unroll
;     for (int r = 0; r < 2; ++r) {
;       float lt = l[r]; lt += __shfl_xor(lt, 16); lt += __shfl_xor(lt, 32);
;       const float gt = sigm(bf2f(zq[zg + hb + r])) * (lt > 0.f ? 1.f / lt : 0.f);
; #pragma unroll
;       for (int df = 0; df < 4; ++df) {
;         bf16_t* yp = yo + r * 64 + df * 16;
;         const u32x2 pr = *(const u32x2*)yp;
;         u32x2 o; o.x = pk2(__uint_as_float(pr.x << 16) + O[df][r][0] * gt, __uint_as_float(pr.x & 0xffff0000u) + O[df][r][1] * gt);
;         o.y = pk2(__uint_as_float(pr.y << 16) + O[df][r][2] * gt, __uint_as_float(pr.y & 0xffff0000u) + O[df][r][3] * gt);
;         *(u32x2*)yp = o;
;       }
;     }
.LBB0_347:
	s_lshl_b32 s46, s16, 1
	global_load_dwordx2 v[18:19], v[182:183], off offset:1024
	global_load_dwordx2 v[20:21], v[182:183], off offset:1056
	global_load_dwordx2 v[22:23], v[182:183], off offset:1088
	v_lshl_add_u64 v[24:25], v[184:185], 0, s[46:47]
	global_load_ushort v40, v[24:25], off
	global_load_dwordx2 v[26:27], v[182:183], off offset:1120
	ds_bpermute_b32 v16, v233, v190
	ds_bpermute_b32 v17, v233, v191
	s_waitcnt lgkmcnt(0)
	v_pk_add_f32 v[16:17], v[190:191], v[16:17]
	ds_bpermute_b32 v28, v234, v16
	ds_bpermute_b32 v29, v234, v17
	s_waitcnt lgkmcnt(0)
	v_pk_add_f32 v[16:17], v[16:17], v[28:29]
	s_nop 0
	v_div_scale_f32 v34, s[16:17], v16, v16, 1.0
	v_rcp_f32_e32 v35, v34
	v_div_scale_f32 v36, vcc, 1.0, v16, 1.0
	global_load_dwordx2 v[28:29], v[182:183], off offset:1152
	global_load_dwordx2 v[30:31], v[182:183], off offset:1184
	global_load_dwordx2 v[32:33], v[182:183], off offset:1216
	global_load_ushort v232, v[24:25], off offset:2
	global_load_dwordx2 v[230:231], v[182:183], off offset:1248
	v_fma_f32 v37, -v34, v35, 1.0
	v_fmac_f32_e32 v35, v37, v35
	v_mul_f32_e32 v37, v36, v35
	v_fma_f32 v38, -v34, v37, v36
	v_fmac_f32_e32 v37, v38, v35
	v_fma_f32 v34, -v34, v37, v36
	v_div_fmas_f32 v34, v34, v35, v37
	v_div_fixup_f32 v34, v34, v16, 1.0
	v_cmp_lt_f32_e32 vcc, 0, v16
	s_waitcnt vmcnt(7)
	v_and_b32_e32 v35, 0xffff0000, v18
	v_cndmask_b32_e32 v16, 0, v34, vcc
	s_waitcnt vmcnt(5)
	v_lshlrev_b32_e32 v38, 16, v22
	v_and_b32_e32 v39, 0xffff0000, v22
	s_waitcnt vmcnt(4)
	v_lshlrev_b32_e32 v22, 16, v40
	v_mul_f32_e32 v22, 0xbfb8aa3b, v22
	v_exp_f32_e32 v41, v22
	v_lshlrev_b32_e32 v34, 16, v18
	v_lshlrev_b32_e32 v18, 16, v19
	v_and_b32_e32 v19, 0xffff0000, v19
	v_add_f32_e32 v41, 1.0, v41
	v_rcp_f32_e32 v42, v41
	v_lshlrev_b32_e32 v36, 16, v20
	v_and_b32_e32 v37, 0xffff0000, v20
	v_lshlrev_b32_e32 v20, 16, v21
	v_mul_f32_e32 v16, v16, v42
	v_and_b32_e32 v21, 0xffff0000, v21
	v_lshlrev_b32_e32 v22, 16, v23
	v_and_b32_e32 v23, 0xffff0000, v23
	s_waitcnt vmcnt(3)
	v_lshlrev_b32_e32 v40, 16, v26
	v_and_b32_e32 v41, 0xffff0000, v26
	v_lshlrev_b32_e32 v26, 16, v27
	v_and_b32_e32 v27, 0xffff0000, v27
	v_pk_fma_f32 v[34:35], v[116:117], v[16:17], v[34:35] op_sel_hi:[1,0,1]
	v_pk_fma_f32 v[18:19], v[118:119], v[16:17], v[18:19] op_sel_hi:[1,0,1]
	v_pk_fma_f32 v[36:37], v[124:125], v[16:17], v[36:37] op_sel_hi:[1,0,1]
	v_pk_fma_f32 v[20:21], v[126:127], v[16:17], v[20:21] op_sel_hi:[1,0,1]
	v_pk_fma_f32 v[38:39], v[128:129], v[16:17], v[38:39] op_sel_hi:[1,0,1]
	v_pk_fma_f32 v[22:23], v[130:131], v[16:17], v[22:23] op_sel_hi:[1,0,1]
	v_pk_fma_f32 v[40:41], v[132:133], v[16:17], v[40:41] op_sel_hi:[1,0,1]
	v_pk_fma_f32 v[26:27], v[134:135], v[16:17], v[26:27] op_sel_hi:[1,0,1]
	v_cvt_pk_bf16_f32 v34, v34, v35
	v_cvt_pk_bf16_f32 v35, v18, v19
	v_cvt_pk_bf16_f32 v18, v36, v37
	v_cvt_pk_bf16_f32 v19, v20, v21
	v_cvt_pk_bf16_f32 v20, v38, v39
	v_cvt_pk_bf16_f32 v21, v22, v23
	v_cvt_pk_bf16_f32 v22, v40, v41
	v_cvt_pk_bf16_f32 v23, v26, v27
	global_store_dwordx2 v[182:183], v[34:35], off offset:1024
	global_store_dwordx2 v[182:183], v[18:19], off offset:1056
	global_store_dwordx2 v[182:183], v[20:21], off offset:1088
	global_store_dwordx2 v[182:183], v[22:23], off offset:1120
	s_waitcnt vmcnt(4)
	v_mov_b32_e32 v34, v232
	v_mov_b32_e32 v232, 6
	s_nop 0
	v_mov_b32_e32 v18, v230
	v_mov_b32_e32 v19, v231
	v_mov_b32_e32 v230, 0xc00
	v_mov_b32_e32 v231, 0xfe0
	v_div_scale_f32 v16, s[16:17], v17, v17, 1.0
	v_rcp_f32_e32 v20, v16
	v_div_scale_f32 v21, vcc, 1.0, v17, 1.0
	s_waitcnt vmcnt(7)
	v_lshlrev_b32_e32 v24, 16, v31
	v_fma_f32 v22, -v16, v20, 1.0
	v_fmac_f32_e32 v20, v22, v20
	v_mul_f32_e32 v22, v21, v20
	v_fma_f32 v23, -v16, v22, v21
	v_fmac_f32_e32 v22, v23, v20
	v_fma_f32 v16, -v16, v22, v21
	v_div_fmas_f32 v16, v16, v20, v22
	s_andn2_b64 vcc, exec, s[0:1]
	v_div_fixup_f32 v16, v16, v17, 1.0
	v_cmp_lt_f32_e64 s[0:1], 0, v17
	v_and_b32_e32 v17, 0xffff0000, v28
	v_and_b32_e32 v25, 0xffff0000, v31
	v_cndmask_b32_e64 v35, 0, v16, s[0:1]
	v_lshlrev_b32_e32 v16, 16, v28
	s_waitcnt vmcnt(6)
	v_lshlrev_b32_e32 v26, 16, v32
	v_and_b32_e32 v27, 0xffff0000, v32
	v_lshlrev_b32_e32 v20, 16, v29
	v_and_b32_e32 v21, 0xffff0000, v29
	v_lshlrev_b32_e32 v22, 16, v30
	v_and_b32_e32 v23, 0xffff0000, v30
	v_and_b32_e32 v29, 0xffff0000, v33
	s_mov_b64 s[0:1], 0
	v_lshlrev_b32_e32 v28, 16, v34
	v_mul_f32_e32 v28, 0xbfb8aa3b, v28
	v_exp_f32_e32 v31, v28
	v_lshlrev_b32_e32 v28, 16, v33
	v_lshlrev_b32_e32 v30, 16, v18
	v_add_f32_e32 v31, 1.0, v31
	v_rcp_f32_e32 v32, v31
	v_and_b32_e32 v31, 0xffff0000, v18
	v_lshlrev_b32_e32 v18, 16, v19
	v_and_b32_e32 v19, 0xffff0000, v19
	v_mul_f32_e32 v32, v35, v32
	v_pk_fma_f32 v[16:17], v[104:105], v[32:33], v[16:17] op_sel_hi:[1,0,1]
	v_pk_fma_f32 v[20:21], v[106:107], v[32:33], v[20:21] op_sel_hi:[1,0,1]
	v_pk_fma_f32 v[22:23], v[108:109], v[32:33], v[22:23] op_sel_hi:[1,0,1]
	v_pk_fma_f32 v[24:25], v[110:111], v[32:33], v[24:25] op_sel_hi:[1,0,1]
	v_pk_fma_f32 v[26:27], v[112:113], v[32:33], v[26:27] op_sel_hi:[1,0,1]
	v_pk_fma_f32 v[28:29], v[114:115], v[32:33], v[28:29] op_sel_hi:[1,0,1]
	v_pk_fma_f32 v[30:31], v[120:121], v[32:33], v[30:31] op_sel_hi:[1,0,1]
	v_pk_fma_f32 v[18:19], v[122:123], v[32:33], v[18:19] op_sel_hi:[1,0,1]
	v_cvt_pk_bf16_f32 v16, v16, v17
	v_cvt_pk_bf16_f32 v17, v20, v21
	v_cvt_pk_bf16_f32 v20, v22, v23
	v_cvt_pk_bf16_f32 v21, v24, v25
	v_cvt_pk_bf16_f32 v22, v26, v27
	v_cvt_pk_bf16_f32 v23, v28, v29
	v_cvt_pk_bf16_f32 v24, v30, v31
	v_cvt_pk_bf16_f32 v25, v18, v19
	global_store_dwordx2 v[182:183], v[16:17], off offset:1152
	global_store_dwordx2 v[182:183], v[20:21], off offset:1184
	global_store_dwordx2 v[182:183], v[22:23], off offset:1216
	global_store_dwordx2 v[182:183], v[24:25], off offset:1248
	s_cbranch_vccz .LBB0_192

; __device__ __forceinline__ float bf2f(bf16_t v) { return __uint_as_float(((unsigned)v) << 16); }
; __device__ __forceinline__ bf16_t f2bf(float f) { unsigned u = __float_as_uint(f); u += 0x7fffu + ((u >> 16) & 1u); return (bf16_t)(u >> 16); }
; __device__ __forceinline__ float gelu_t(float x) { float u = 0.7978845608028654f * (x + 0.044715f * x * x * x); return x * __builtin_amdgcn_rcpf(1.f + __expf(-2.f * u)); }
; __device__ __forceinline__ void mixB2_item(int idx, const bf16_t* z, const float* hsl, const float* Pc, const float* carryP, const float* carryH, bf16_t* y) {
;     ...
;   const size_t tokb = (size_t)b * SEQ + c * 64 + q * 16;
; #pragma unroll 4
;   for (int i = 0; i < 16; ++i) {
;     const size_t o = (tokb + i) * 256 + g * 64 + j;
;     const float h = hsl[o] + Pc[o] * H;
;     const float gt = bf2f(z[(tokb + i) * LDZ + ZC_BG + g * 64 + j]);
;     y[(tokb + i) * 1024 + 256 + g * 64 + j] = f2bf(h * gelu_t(gt));
;   }
.LBB0_535:
	v_lshl_add_u64 v[14:15], s[10:11], 0, v[2:3]
	v_add_co_u32_e32 v16, vcc, 0x16761000, v14
	s_nop 1
	v_addc_co_u32_e32 v17, vcc, 0, v15, vcc
	v_add_co_u32_e32 v18, vcc, 0x18761000, v14
	s_nop 1
	v_addc_co_u32_e32 v19, vcc, 0, v15, vcc
	v_lshl_add_u64 v[22:23], s[10:11], 0, v[10:11]
	v_lshl_add_u64 v[24:25], s[10:11], 0, v[12:13]
	global_load_dword v32, v[16:17], off
	global_load_dword v48, v[18:19], off
	global_load_ushort v64, v[22:23], off
	v_add_co_u32_e32 v22, vcc, 0x1400, v22
	s_nop 1
	v_addc_co_u32_e32 v23, vcc, 0, v23, vcc
	global_load_dword v33, v[16:17], off offset:1024
	global_load_dword v49, v[18:19], off offset:1024
	global_load_ushort v65, v[22:23], off
	v_add_co_u32_e32 v22, vcc, 0x1400, v22
	s_nop 1
	v_addc_co_u32_e32 v23, vcc, 0, v23, vcc
	global_load_dword v34, v[16:17], off offset:2048
	global_load_dword v50, v[18:19], off offset:2048
	global_load_ushort v66, v[22:23], off
	v_add_co_u32_e32 v22, vcc, 0x1400, v22
	s_nop 1
	v_addc_co_u32_e32 v23, vcc, 0, v23, vcc
	global_load_dword v35, v[16:17], off offset:3072
	global_load_dword v51, v[18:19], off offset:3072
	global_load_ushort v67, v[22:23], off
	v_add_co_u32_e32 v22, vcc, 0x1400, v22
	s_nop 1
	v_addc_co_u32_e32 v23, vcc, 0, v23, vcc
	v_add_co_u32_e32 v16, vcc, 0x1000, v16
	s_nop 1
	v_addc_co_u32_e32 v17, vcc, 0, v17, vcc
	v_add_co_u32_e32 v18, vcc, 0x1000, v18
	s_nop 1
	v_addc_co_u32_e32 v19, vcc, 0, v19, vcc
	global_load_dword v36, v[16:17], off
	global_load_dword v52, v[18:19], off
	global_load_ushort v68, v[22:23], off
	v_add_co_u32_e32 v22, vcc, 0x1400, v22
	s_nop 1
	v_addc_co_u32_e32 v23, vcc, 0, v23, vcc
	global_load_dword v37, v[16:17], off offset:1024
	global_load_dword v53, v[18:19], off offset:1024
	global_load_ushort v69, v[22:23], off
	v_add_co_u32_e32 v22, vcc, 0x1400, v22
	s_nop 1
	v_addc_co_u32_e32 v23, vcc, 0, v23, vcc
	global_load_dword v38, v[16:17], off offset:2048
	global_load_dword v54, v[18:19], off offset:2048
	global_load_ushort v70, v[22:23], off
	v_add_co_u32_e32 v22, vcc, 0x1400, v22
	s_nop 1
	v_addc_co_u32_e32 v23, vcc, 0, v23, vcc
	global_load_dword v39, v[16:17], off offset:3072
	global_load_dword v55, v[18:19], off offset:3072
	global_load_ushort v71, v[22:23], off
	v_add_co_u32_e32 v22, vcc, 0x1400, v22
	s_nop 1
	v_addc_co_u32_e32 v23, vcc, 0, v23, vcc
	v_add_co_u32_e32 v16, vcc, 0x1000, v16
	s_nop 1
	v_addc_co_u32_e32 v17, vcc, 0, v17, vcc
	v_add_co_u32_e32 v18, vcc, 0x1000, v18
	s_nop 1
	v_addc_co_u32_e32 v19, vcc, 0, v19, vcc
	global_load_dword v40, v[16:17], off
	global_load_dword v56, v[18:19], off
	global_load_ushort v72, v[22:23], off
	v_add_co_u32_e32 v22, vcc, 0x1400, v22
	s_nop 1
	v_addc_co_u32_e32 v23, vcc, 0, v23, vcc
	global_load_dword v41, v[16:17], off offset:1024
	global_load_dword v57, v[18:19], off offset:1024
	global_load_ushort v73, v[22:23], off
	v_add_co_u32_e32 v22, vcc, 0x1400, v22
	s_nop 1
	v_addc_co_u32_e32 v23, vcc, 0, v23, vcc
	global_load_dword v42, v[16:17], off offset:2048
	global_load_dword v58, v[18:19], off offset:2048
	global_load_ushort v74, v[22:23], off
	v_add_co_u32_e32 v22, vcc, 0x1400, v22
	s_nop 1
	v_addc_co_u32_e32 v23, vcc, 0, v23, vcc
	global_load_dword v43, v[16:17], off offset:3072
	global_load_dword v59, v[18:19], off offset:3072
	global_load_ushort v75, v[22:23], off
	v_add_co_u32_e32 v22, vcc, 0x1400, v22
	s_nop 1
	v_addc_co_u32_e32 v23, vcc, 0, v23, vcc
	v_add_co_u32_e32 v16, vcc, 0x1000, v16
	s_nop 1
	v_addc_co_u32_e32 v17, vcc, 0, v17, vcc
	v_add_co_u32_e32 v18, vcc, 0x1000, v18
	s_nop 1
	v_addc_co_u32_e32 v19, vcc, 0, v19, vcc
	global_load_dword v44, v[16:17], off
	global_load_dword v60, v[18:19], off
	global_load_ushort v76, v[22:23], off
	v_add_co_u32_e32 v22, vcc, 0x1400, v22
	s_nop 1
	v_addc_co_u32_e32 v23, vcc, 0, v23, vcc
	global_load_dword v45, v[16:17], off offset:1024
	global_load_dword v61, v[18:19], off offset:1024
	global_load_ushort v77, v[22:23], off
	v_add_co_u32_e32 v22, vcc, 0x1400, v22
	s_nop 1
	v_addc_co_u32_e32 v23, vcc, 0, v23, vcc
	global_load_dword v46, v[16:17], off offset:2048
	global_load_dword v62, v[18:19], off offset:2048
	global_load_ushort v78, v[22:23], off
	v_add_co_u32_e32 v22, vcc, 0x1400, v22
	s_nop 1
	v_addc_co_u32_e32 v23, vcc, 0, v23, vcc
	global_load_dword v47, v[16:17], off offset:3072
	global_load_dword v63, v[18:19], off offset:3072
	global_load_ushort v79, v[22:23], off
	s_waitcnt vmcnt(45)
	v_lshlrev_b32_e32 v26, 16, v64
	v_mul_f32_e32 v27, 0x3d372713, v26
	v_mul_f32_e32 v27, v27, v26
	v_fma_f32 v27, v27, v26, v26
	v_mul_f32_e32 v27, 0x3f4c422a, v27
	v_mul_f32_e32 v27, -2.0, v27
	v_mul_f32_e32 v27, 0x3fb8aa3b, v27
	v_exp_f32_e32 v27, v27
	v_mul_f32_e32 v28, v0, v48
	v_add_f32_e32 v27, 1.0, v27
	v_rcp_f32_e32 v27, v27
	v_add_f32_e32 v28, v32, v28
	v_mul_f32_e32 v27, v27, v26
	v_mul_f32_e32 v28, v28, v27
	v_bfe_u32 v29, v28, 16, 1
	v_add3_u32 v28, v28, v29, s60
	global_store_short_d16_hi v[24:25], v28, off
	s_waitcnt vmcnt(43)
	v_lshlrev_b32_e32 v26, 16, v65
	v_mul_f32_e32 v27, 0x3d372713, v26
	v_mul_f32_e32 v27, v27, v26
	v_fma_f32 v27, v27, v26, v26
	v_mul_f32_e32 v27, 0x3f4c422a, v27
	v_mul_f32_e32 v27, -2.0, v27
	v_mul_f32_e32 v27, 0x3fb8aa3b, v27
	v_exp_f32_e32 v27, v27
	v_mul_f32_e32 v28, v0, v49
	v_add_f32_e32 v27, 1.0, v27
	v_rcp_f32_e32 v27, v27
	v_add_f32_e32 v28, v33, v28
	v_mul_f32_e32 v27, v27, v26
	v_mul_f32_e32 v28, v28, v27
	v_bfe_u32 v29, v28, 16, 1
	v_add3_u32 v28, v28, v29, s60
	global_store_short_d16_hi v[24:25], v28, off offset:2048
	v_add_co_u32_e32 v24, vcc, 0x1000, v24
	s_nop 1
	v_addc_co_u32_e32 v25, vcc, 0, v25, vcc
	s_waitcnt vmcnt(41)
; __device__ __forceinline__ float bf2f(bf16_t v) { return __uint_as_float(((unsigned)v) << 16); }
; __device__ __forceinline__ bf16_t f2bf(float f) { unsigned u = __float_as_uint(f); u += 0x7fffu + ((u >> 16) & 1u); return (bf16_t)(u >> 16); }
; __device__ __forceinline__ float gelu_t(float x) { float u = 0.7978845608028654f * (x + 0.044715f * x * x * x); return x * __builtin_amdgcn_rcpf(1.f + __expf(-2.f * u)); }
; __device__ __forceinline__ void mixB2_item(int idx, const bf16_t* z, const float* hsl, const float* Pc, const float* carryP, const float* carryH, bf16_t* y) {
;     ...
;   const size_t tokb = (size_t)b * SEQ + c * 64 + q * 16;
; #pragma unroll 4
;   for (int i = 0; i < 16; ++i) {
;     const size_t o = (tokb + i) * 256 + g * 64 + j;
;     const float h = hsl[o] + Pc[o] * H;
;     const float gt = bf2f(z[(tokb + i) * LDZ + ZC_BG + g * 64 + j]);
;     y[(tokb + i) * 1024 + 256 + g * 64 + j] = f2bf(h * gelu_t(gt));
;   }
	v_lshlrev_b32_e32 v26, 16, v66
	v_mul_f32_e32 v27, 0x3d372713, v26
	v_mul_f32_e32 v27, v27, v26
	v_fma_f32 v27, v27, v26, v26
	v_mul_f32_e32 v27, 0x3f4c422a, v27
	v_mul_f32_e32 v27, -2.0, v27
	v_mul_f32_e32 v27, 0x3fb8aa3b, v27
	v_exp_f32_e32 v27, v27
	v_mul_f32_e32 v28, v0, v50
	v_add_f32_e32 v27, 1.0, v27
	v_rcp_f32_e32 v27, v27
	v_add_f32_e32 v28, v34, v28
	v_mul_f32_e32 v27, v27, v26
	v_mul_f32_e32 v28, v28, v27
	v_bfe_u32 v29, v28, 16, 1
	v_add3_u32 v28, v28, v29, s60
	global_store_short_d16_hi v[24:25], v28, off
	s_waitcnt vmcnt(39)
	v_lshlrev_b32_e32 v26, 16, v67
	v_mul_f32_e32 v27, 0x3d372713, v26
	v_mul_f32_e32 v27, v27, v26
	v_fma_f32 v27, v27, v26, v26
	v_mul_f32_e32 v27, 0x3f4c422a, v27
	v_mul_f32_e32 v27, -2.0, v27
	v_mul_f32_e32 v27, 0x3fb8aa3b, v27
	v_exp_f32_e32 v27, v27
	v_mul_f32_e32 v28, v0, v51
	v_add_f32_e32 v27, 1.0, v27
	v_rcp_f32_e32 v27, v27
	v_add_f32_e32 v28, v35, v28
	v_mul_f32_e32 v27, v27, v26
	v_mul_f32_e32 v28, v28, v27
	v_bfe_u32 v29, v28, 16, 1
	v_add3_u32 v28, v28, v29, s60
	global_store_short_d16_hi v[24:25], v28, off offset:2048
	v_add_co_u32_e32 v24, vcc, 0x1000, v24
	s_nop 1
	v_addc_co_u32_e32 v25, vcc, 0, v25, vcc
	s_waitcnt vmcnt(37)
	v_lshlrev_b32_e32 v26, 16, v68
	v_mul_f32_e32 v27, 0x3d372713, v26
	v_mul_f32_e32 v27, v27, v26
	v_fma_f32 v27, v27, v26, v26
	v_mul_f32_e32 v27, 0x3f4c422a, v27
	v_mul_f32_e32 v27, -2.0, v27
	v_mul_f32_e32 v27, 0x3fb8aa3b, v27
	v_exp_f32_e32 v27, v27
	v_mul_f32_e32 v28, v0, v52
	v_add_f32_e32 v27, 1.0, v27
	v_rcp_f32_e32 v27, v27
	v_add_f32_e32 v28, v36, v28
	v_mul_f32_e32 v27, v27, v26
	v_mul_f32_e32 v28, v28, v27
	v_bfe_u32 v29, v28, 16, 1
	v_add3_u32 v28, v28, v29, s60
	global_store_short_d16_hi v[24:25], v28, off
	s_waitcnt vmcnt(35)
	v_lshlrev_b32_e32 v26, 16, v69
	v_mul_f32_e32 v27, 0x3d372713, v26
	v_mul_f32_e32 v27, v27, v26
	v_fma_f32 v27, v27, v26, v26
	v_mul_f32_e32 v27, 0x3f4c422a, v27
	v_mul_f32_e32 v27, -2.0, v27
	v_mul_f32_e32 v27, 0x3fb8aa3b, v27
	v_exp_f32_e32 v27, v27
	v_mul_f32_e32 v28, v0, v53
	v_add_f32_e32 v27, 1.0, v27
	v_rcp_f32_e32 v27, v27
	v_add_f32_e32 v28, v37, v28
	v_mul_f32_e32 v27, v27, v26
	v_mul_f32_e32 v28, v28, v27
	v_bfe_u32 v29, v28, 16, 1
	v_add3_u32 v28, v28, v29, s60
	global_store_short_d16_hi v[24:25], v28, off offset:2048
	v_add_co_u32_e32 v24, vcc, 0x1000, v24
	s_nop 1
	v_addc_co_u32_e32 v25, vcc, 0, v25, vcc
	s_waitcnt vmcnt(33)
	v_lshlrev_b32_e32 v26, 16, v70
	v_mul_f32_e32 v27, 0x3d372713, v26
	v_mul_f32_e32 v27, v27, v26
	v_fma_f32 v27, v27, v26, v26
	v_mul_f32_e32 v27, 0x3f4c422a, v27
	v_mul_f32_e32 v27, -2.0, v27
	v_mul_f32_e32 v27, 0x3fb8aa3b, v27
	v_exp_f32_e32 v27, v27
	v_mul_f32_e32 v28, v0, v54
	v_add_f32_e32 v27, 1.0, v27
	v_rcp_f32_e32 v27, v27
	v_add_f32_e32 v28, v38, v28
	v_mul_f32_e32 v27, v27, v26
	v_mul_f32_e32 v28, v28, v27
	v_bfe_u32 v29, v28, 16, 1
	v_add3_u32 v28, v28, v29, s60
	global_store_short_d16_hi v[24:25], v28, off
	s_waitcnt vmcnt(31)
	v_lshlrev_b32_e32 v26, 16, v71
	v_mul_f32_e32 v27, 0x3d372713, v26
	v_mul_f32_e32 v27, v27, v26
	v_fma_f32 v27, v27, v26, v26
	v_mul_f32_e32 v27, 0x3f4c422a, v27
	v_mul_f32_e32 v27, -2.0, v27
	v_mul_f32_e32 v27, 0x3fb8aa3b, v27
	v_exp_f32_e32 v27, v27
	v_mul_f32_e32 v28, v0, v55
	v_add_f32_e32 v27, 1.0, v27
	v_rcp_f32_e32 v27, v27
	v_add_f32_e32 v28, v39, v28
	v_mul_f32_e32 v27, v27, v26
	v_mul_f32_e32 v28, v28, v27
	v_bfe_u32 v29, v28, 16, 1
	v_add3_u32 v28, v28, v29, s60
	global_store_short_d16_hi v[24:25], v28, off offset:2048
	v_add_co_u32_e32 v24, vcc, 0x1000, v24
	s_nop 1
	v_addc_co_u32_e32 v25, vcc, 0, v25, vcc
	s_waitcnt vmcnt(29)
	v_lshlrev_b32_e32 v26, 16, v72
	v_mul_f32_e32 v27, 0x3d372713, v26
	v_mul_f32_e32 v27, v27, v26
	v_fma_f32 v27, v27, v26, v26
	v_mul_f32_e32 v27, 0x3f4c422a, v27
	v_mul_f32_e32 v27, -2.0, v27
	v_mul_f32_e32 v27, 0x3fb8aa3b, v27
	v_exp_f32_e32 v27, v27
	v_mul_f32_e32 v28, v0, v56
	v_add_f32_e32 v27, 1.0, v27
	v_rcp_f32_e32 v27, v27
	v_add_f32_e32 v28, v40, v28
	v_mul_f32_e32 v27, v27, v26
	v_mul_f32_e32 v28, v28, v27
	v_bfe_u32 v29, v28, 16, 1
	v_add3_u32 v28, v28, v29, s60
	global_store_short_d16_hi v[24:25], v28, off
	s_waitcnt vmcnt(27)
; __device__ __forceinline__ float bf2f(bf16_t v) { return __uint_as_float(((unsigned)v) << 16); }
; __device__ __forceinline__ bf16_t f2bf(float f) { unsigned u = __float_as_uint(f); u += 0x7fffu + ((u >> 16) & 1u); return (bf16_t)(u >> 16); }
; __device__ __forceinline__ float gelu_t(float x) { float u = 0.7978845608028654f * (x + 0.044715f * x * x * x); return x * __builtin_amdgcn_rcpf(1.f + __expf(-2.f * u)); }
; __device__ __forceinline__ void mixB2_item(int idx, const bf16_t* z, const float* hsl, const float* Pc, const float* carryP, const float* carryH, bf16_t* y) {
;     ...
;   const size_t tokb = (size_t)b * SEQ + c * 64 + q * 16;
; #pragma unroll 4
;   for (int i = 0; i < 16; ++i) {
;     const size_t o = (tokb + i) * 256 + g * 64 + j;
;     const float h = hsl[o] + Pc[o] * H;
;     const float gt = bf2f(z[(tokb + i) * LDZ + ZC_BG + g * 64 + j]);
;     y[(tokb + i) * 1024 + 256 + g * 64 + j] = f2bf(h * gelu_t(gt));
;   }
	v_lshlrev_b32_e32 v26, 16, v73
	v_mul_f32_e32 v27, 0x3d372713, v26
	v_mul_f32_e32 v27, v27, v26
	v_fma_f32 v27, v27, v26, v26
	v_mul_f32_e32 v27, 0x3f4c422a, v27
	v_mul_f32_e32 v27, -2.0, v27
	v_mul_f32_e32 v27, 0x3fb8aa3b, v27
	v_exp_f32_e32 v27, v27
	v_mul_f32_e32 v28, v0, v57
	v_add_f32_e32 v27, 1.0, v27
	v_rcp_f32_e32 v27, v27
	v_add_f32_e32 v28, v41, v28
	v_mul_f32_e32 v27, v27, v26
	v_mul_f32_e32 v28, v28, v27
	v_bfe_u32 v29, v28, 16, 1
	v_add3_u32 v28, v28, v29, s60
	global_store_short_d16_hi v[24:25], v28, off offset:2048
	v_add_co_u32_e32 v24, vcc, 0x1000, v24
	s_nop 1
	v_addc_co_u32_e32 v25, vcc, 0, v25, vcc
	s_waitcnt vmcnt(25)
	v_lshlrev_b32_e32 v26, 16, v74
	v_mul_f32_e32 v27, 0x3d372713, v26
	v_mul_f32_e32 v27, v27, v26
	v_fma_f32 v27, v27, v26, v26
	v_mul_f32_e32 v27, 0x3f4c422a, v27
	v_mul_f32_e32 v27, -2.0, v27
	v_mul_f32_e32 v27, 0x3fb8aa3b, v27
	v_exp_f32_e32 v27, v27
	v_mul_f32_e32 v28, v0, v58
	v_add_f32_e32 v27, 1.0, v27
	v_rcp_f32_e32 v27, v27
	v_add_f32_e32 v28, v42, v28
	v_mul_f32_e32 v27, v27, v26
	v_mul_f32_e32 v28, v28, v27
	v_bfe_u32 v29, v28, 16, 1
	v_add3_u32 v28, v28, v29, s60
	global_store_short_d16_hi v[24:25], v28, off
	s_waitcnt vmcnt(23)
	v_lshlrev_b32_e32 v26, 16, v75
	v_mul_f32_e32 v27, 0x3d372713, v26
	v_mul_f32_e32 v27, v27, v26
	v_fma_f32 v27, v27, v26, v26
	v_mul_f32_e32 v27, 0x3f4c422a, v27
	v_mul_f32_e32 v27, -2.0, v27
	v_mul_f32_e32 v27, 0x3fb8aa3b, v27
	v_exp_f32_e32 v27, v27
	v_mul_f32_e32 v28, v0, v59
	v_add_f32_e32 v27, 1.0, v27
	v_rcp_f32_e32 v27, v27
	v_add_f32_e32 v28, v43, v28
	v_mul_f32_e32 v27, v27, v26
	v_mul_f32_e32 v28, v28, v27
	v_bfe_u32 v29, v28, 16, 1
	v_add3_u32 v28, v28, v29, s60
	global_store_short_d16_hi v[24:25], v28, off offset:2048
	v_add_co_u32_e32 v24, vcc, 0x1000, v24
	s_nop 1
	v_addc_co_u32_e32 v25, vcc, 0, v25, vcc
	s_waitcnt vmcnt(21)
	v_lshlrev_b32_e32 v26, 16, v76
	v_mul_f32_e32 v27, 0x3d372713, v26
	v_mul_f32_e32 v27, v27, v26
	v_fma_f32 v27, v27, v26, v26
	v_mul_f32_e32 v27, 0x3f4c422a, v27
	v_mul_f32_e32 v27, -2.0, v27
	v_mul_f32_e32 v27, 0x3fb8aa3b, v27
	v_exp_f32_e32 v27, v27
	v_mul_f32_e32 v28, v0, v60
	v_add_f32_e32 v27, 1.0, v27
	v_rcp_f32_e32 v27, v27
	v_add_f32_e32 v28, v44, v28
	v_mul_f32_e32 v27, v27, v26
	v_mul_f32_e32 v28, v28, v27
	v_bfe_u32 v29, v28, 16, 1
	v_add3_u32 v28, v28, v29, s60
	global_store_short_d16_hi v[24:25], v28, off
	s_waitcnt vmcnt(19)
	v_lshlrev_b32_e32 v26, 16, v77
	v_mul_f32_e32 v27, 0x3d372713, v26
	v_mul_f32_e32 v27, v27, v26
	v_fma_f32 v27, v27, v26, v26
	v_mul_f32_e32 v27, 0x3f4c422a, v27
	v_mul_f32_e32 v27, -2.0, v27
	v_mul_f32_e32 v27, 0x3fb8aa3b, v27
	v_exp_f32_e32 v27, v27
	v_mul_f32_e32 v28, v0, v61
	v_add_f32_e32 v27, 1.0, v27
	v_rcp_f32_e32 v27, v27
	v_add_f32_e32 v28, v45, v28
	v_mul_f32_e32 v27, v27, v26
	v_mul_f32_e32 v28, v28, v27
	v_bfe_u32 v29, v28, 16, 1
	v_add3_u32 v28, v28, v29, s60
	global_store_short_d16_hi v[24:25], v28, off offset:2048
	v_add_co_u32_e32 v24, vcc, 0x1000, v24
	s_nop 1
	v_addc_co_u32_e32 v25, vcc, 0, v25, vcc
	s_waitcnt vmcnt(17)
	v_lshlrev_b32_e32 v26, 16, v78
	v_mul_f32_e32 v27, 0x3d372713, v26
	v_mul_f32_e32 v27, v27, v26
	v_fma_f32 v27, v27, v26, v26
	v_mul_f32_e32 v27, 0x3f4c422a, v27
	v_mul_f32_e32 v27, -2.0, v27
	v_mul_f32_e32 v27, 0x3fb8aa3b, v27
	v_exp_f32_e32 v27, v27
	v_mul_f32_e32 v28, v0, v62
	v_add_f32_e32 v27, 1.0, v27
	v_rcp_f32_e32 v27, v27
	v_add_f32_e32 v28, v46, v28
	v_mul_f32_e32 v27, v27, v26
	v_mul_f32_e32 v28, v28, v27
	v_bfe_u32 v29, v28, 16, 1
	v_add3_u32 v28, v28, v29, s60
	global_store_short_d16_hi v[24:25], v28, off
	s_waitcnt vmcnt(15)
	v_lshlrev_b32_e32 v26, 16, v79
	v_mul_f32_e32 v27, 0x3d372713, v26
	v_mul_f32_e32 v27, v27, v26
	v_fma_f32 v27, v27, v26, v26
	v_mul_f32_e32 v27, 0x3f4c422a, v27
	v_mul_f32_e32 v27, -2.0, v27
	v_mul_f32_e32 v27, 0x3fb8aa3b, v27
	v_exp_f32_e32 v27, v27
	v_mul_f32_e32 v28, v0, v63
	v_add_f32_e32 v27, 1.0, v27
	v_rcp_f32_e32 v27, v27
	v_add_f32_e32 v28, v47, v28
	v_mul_f32_e32 v27, v27, v26
	v_mul_f32_e32 v28, v28, v27
	v_bfe_u32 v29, v28, 16, 1
	v_add3_u32 v28, v28, v29, s60
	global_store_short_d16_hi v[24:25], v28, off offset:2048
	v_readlane_b32 s0, v253, 4
	s_movk_i32 s1, 0x7ff
	s_nop 0
	v_add_u32_e32 v20, s0, v20
	v_cmp_lt_i32_e32 vcc, s1, v20
	s_or_b64 s[34:35], vcc, s[34:35]
	v_add_u16_e32 v21, s0, v21
	s_andn2_b64 exec, exec, s[34:35]
	s_cbranch_execnz .LBB0_500

; __device__ __forceinline__ f32x4 mfma16(bf16x8 a, bf16x8 b, f32x4 c) { return __builtin_amdgcn_mfma_f32_16x16x32_bf16(a, b, c, 0, 0, 0); }
; __device__ __forceinline__ void compress_item(const Params& P, int layer, int idx, const bf16_t* z, bf16_t* kcv, char* lds) {
;     ...
; #pragma unroll 4
;   for (int kk = 0; kk < 16; ++kk) {
;     const int ks = 16 * w + kk, l = ks >> 1, d0 = (ks & 1) * 32;
;     const bf16x8 xf = *(const bf16x8*)(zb + (size_t)l * LDZ + d0);
; #pragma unroll
;     for (int jf = 0; jf < 8; ++jf) { const bf16x8 wf = *(const bf16x8*)(wb + (size_t)jf * 16 * 2048 + ks * 32); acc[jf] = mfma16(wf, xf, acc[jf]); }
;   }
.LBB0_542:
	v_lshl_add_u64 v[58:59], v[36:37], 0, v[176:177]
	v_lshl_add_u64 v[82:83], v[34:35], 0, v[176:177]
	s_mov_b32 s34, 0xb761000
	v_add_co_u32_e32 v74, vcc, s34, v58
	s_nop 1
	v_addc_co_u32_e32 v75, vcc, 0, v59, vcc
	s_mov_b32 s34, 0x5500000
	v_add_co_u32_e32 v56, vcc, s34, v82
	s_nop 1
	v_addc_co_u32_e32 v57, vcc, 0, v83, vcc
	s_mov_b32 s34, 0x5510000
	v_add_co_u32_e32 v54, vcc, s34, v82
	s_nop 1
	v_addc_co_u32_e32 v55, vcc, 0, v83, vcc
	s_mov_b32 s34, 0x5520000
	v_add_co_u32_e32 v52, vcc, s34, v82
	s_nop 1
	v_addc_co_u32_e32 v53, vcc, 0, v83, vcc
	s_mov_b32 s34, 0x5530000
	v_add_co_u32_e32 v50, vcc, s34, v82
	s_nop 1
	v_addc_co_u32_e32 v51, vcc, 0, v83, vcc
	s_mov_b32 s34, 0x5540000
	v_add_co_u32_e32 v48, vcc, s34, v82
	s_nop 1
	v_addc_co_u32_e32 v49, vcc, 0, v83, vcc
	s_mov_b32 s34, 0x5550000
	v_add_co_u32_e32 v46, vcc, s34, v82
	s_nop 1
	v_addc_co_u32_e32 v47, vcc, 0, v83, vcc
	s_mov_b32 s34, 0x5560000
	v_add_co_u32_e32 v44, vcc, s34, v82
	s_nop 1
	v_addc_co_u32_e32 v45, vcc, 0, v83, vcc
	s_mov_b32 s34, 0x5570000
	v_add_co_u32_e32 v42, vcc, s34, v82
	s_nop 1
	v_addc_co_u32_e32 v43, vcc, 0, v83, vcc
	v_lshl_add_u64 v[76:77], v[40:41], 0, v[176:177]
	v_add_co_u32_e32 v78, vcc, s35, v58
	s_nop 1
	v_addc_co_u32_e32 v79, vcc, 0, v59, vcc
	v_lshl_add_u64 v[80:81], v[38:39], 0, v[176:177]
	s_add_i32 s17, s17, -4
	v_lshl_add_u64 v[34:35], v[34:35], 0, s[20:21]
	v_lshl_add_u64 v[36:37], v[36:37], 0, s[36:37]
	v_lshl_add_u64 v[40:41], v[40:41], 0, s[36:37]
	v_lshl_add_u64 v[38:39], v[38:39], 0, s[36:37]
	global_load_dwordx4 v[84:87], v[74:75], off
	global_load_dwordx4 v[88:91], v[56:57], off
	global_load_dwordx4 v[92:95], v[54:55], off
	global_load_dwordx4 v[96:99], v[52:53], off
	global_load_dwordx4 v[100:103], v[50:51], off
	global_load_dwordx4 v[104:107], v[48:49], off
	global_load_dwordx4 v[108:111], v[46:47], off
	global_load_dwordx4 v[112:115], v[44:45], off
	global_load_dwordx4 v[116:119], v[42:43], off
	global_load_dwordx4 v[120:123], v[76:77], off
	global_load_dwordx4 v[124:127], v[56:57], off offset:64
	global_load_dwordx4 v[128:131], v[54:55], off offset:64
	global_load_dwordx4 v[132:135], v[52:53], off offset:64
	global_load_dwordx4 v[136:139], v[50:51], off offset:64
	global_load_dwordx4 v[140:143], v[48:49], off offset:64
	global_load_dwordx4 v[144:147], v[46:47], off offset:64
	global_load_dwordx4 v[148:151], v[44:45], off offset:64
	global_load_dwordx4 v[152:155], v[42:43], off offset:64
	s_waitcnt vmcnt(16)
	v_mfma_f32_16x16x32_bf16 v[0:3], v[88:91], v[84:87], v[0:3]
	s_waitcnt vmcnt(15)
	v_mfma_f32_16x16x32_bf16 v[4:7], v[92:95], v[84:87], v[4:7]
	s_waitcnt vmcnt(14)
	v_mfma_f32_16x16x32_bf16 v[8:11], v[96:99], v[84:87], v[8:11]
	s_waitcnt vmcnt(13)
	v_mfma_f32_16x16x32_bf16 v[12:15], v[100:103], v[84:87], v[12:15]
	s_waitcnt vmcnt(12)
	v_mfma_f32_16x16x32_bf16 v[16:19], v[104:107], v[84:87], v[16:19]
	s_waitcnt vmcnt(11)
	v_mfma_f32_16x16x32_bf16 v[20:23], v[108:111], v[84:87], v[20:23]
	s_waitcnt vmcnt(10)
	v_mfma_f32_16x16x32_bf16 v[24:27], v[112:115], v[84:87], v[24:27]
	s_waitcnt vmcnt(9)
	v_mfma_f32_16x16x32_bf16 v[28:31], v[116:119], v[84:87], v[28:31]
	global_load_dwordx4 v[84:87], v[78:79], off offset:1024
	global_load_dwordx4 v[88:91], v[56:57], off offset:128
	global_load_dwordx4 v[92:95], v[54:55], off offset:128
	global_load_dwordx4 v[96:99], v[52:53], off offset:128
	global_load_dwordx4 v[100:103], v[50:51], off offset:128
	global_load_dwordx4 v[104:107], v[48:49], off offset:128
	global_load_dwordx4 v[108:111], v[46:47], off offset:128
	global_load_dwordx4 v[112:115], v[44:45], off offset:128
	global_load_dwordx4 v[116:119], v[42:43], off offset:128
	s_waitcnt vmcnt(16)
	v_mfma_f32_16x16x32_bf16 v[0:3], v[124:127], v[120:123], v[0:3]
	s_waitcnt vmcnt(15)
	v_mfma_f32_16x16x32_bf16 v[4:7], v[128:131], v[120:123], v[4:7]
	s_waitcnt vmcnt(14)
	v_mfma_f32_16x16x32_bf16 v[8:11], v[132:135], v[120:123], v[8:11]
	s_waitcnt vmcnt(13)
	v_mfma_f32_16x16x32_bf16 v[12:15], v[136:139], v[120:123], v[12:15]
	s_waitcnt vmcnt(12)
	v_mfma_f32_16x16x32_bf16 v[16:19], v[140:143], v[120:123], v[16:19]
	s_waitcnt vmcnt(11)
	v_mfma_f32_16x16x32_bf16 v[20:23], v[144:147], v[120:123], v[20:23]
	s_waitcnt vmcnt(10)
	v_mfma_f32_16x16x32_bf16 v[24:27], v[148:151], v[120:123], v[24:27]
	s_waitcnt vmcnt(9)
	v_mfma_f32_16x16x32_bf16 v[28:31], v[152:155], v[120:123], v[28:31]
	global_load_dwordx4 v[120:123], v[80:81], off
	global_load_dwordx4 v[124:127], v[56:57], off offset:192
	global_load_dwordx4 v[128:131], v[54:55], off offset:192
	global_load_dwordx4 v[132:135], v[52:53], off offset:192
	global_load_dwordx4 v[136:139], v[50:51], off offset:192
	global_load_dwordx4 v[140:143], v[48:49], off offset:192
	global_load_dwordx4 v[144:147], v[46:47], off offset:192
	global_load_dwordx4 v[148:151], v[44:45], off offset:192
	global_load_dwordx4 v[152:155], v[42:43], off offset:192
	s_waitcnt vmcnt(16)
	v_mfma_f32_16x16x32_bf16 v[0:3], v[88:91], v[84:87], v[0:3]
	s_waitcnt vmcnt(15)
	v_mfma_f32_16x16x32_bf16 v[4:7], v[92:95], v[84:87], v[4:7]
	s_waitcnt vmcnt(14)
	v_mfma_f32_16x16x32_bf16 v[8:11], v[96:99], v[84:87], v[8:11]
	s_waitcnt vmcnt(13)
	v_mfma_f32_16x16x32_bf16 v[12:15], v[100:103], v[84:87], v[12:15]
	s_waitcnt vmcnt(12)
	v_mfma_f32_16x16x32_bf16 v[16:19], v[104:107], v[84:87], v[16:19]
	s_waitcnt vmcnt(11)
	v_mfma_f32_16x16x32_bf16 v[20:23], v[108:111], v[84:87], v[20:23]
	s_waitcnt vmcnt(10)
	v_mfma_f32_16x16x32_bf16 v[24:27], v[112:115], v[84:87], v[24:27]
	s_waitcnt vmcnt(9)
	v_mfma_f32_16x16x32_bf16 v[28:31], v[116:119], v[84:87], v[28:31]
	s_waitcnt vmcnt(7)
	v_mfma_f32_16x16x32_bf16 v[0:3], v[124:127], v[120:123], v[0:3]
	s_waitcnt vmcnt(6)
	v_mfma_f32_16x16x32_bf16 v[4:7], v[128:131], v[120:123], v[4:7]
	s_waitcnt vmcnt(5)
	v_mfma_f32_16x16x32_bf16 v[8:11], v[132:135], v[120:123], v[8:11]
	s_waitcnt vmcnt(4)
	v_mfma_f32_16x16x32_bf16 v[12:15], v[136:139], v[120:123], v[12:15]
	s_waitcnt vmcnt(3)
	v_mfma_f32_16x16x32_bf16 v[16:19], v[140:143], v[120:123], v[16:19]
	s_waitcnt vmcnt(2)
	v_mfma_f32_16x16x32_bf16 v[20:23], v[144:147], v[120:123], v[20:23]
	s_waitcnt vmcnt(1)
	v_mfma_f32_16x16x32_bf16 v[24:27], v[148:151], v[120:123], v[24:27]
	s_waitcnt vmcnt(0)
	v_mfma_f32_16x16x32_bf16 v[28:31], v[152:155], v[120:123], v[28:31]
	s_cmp_eq_u32 s17, 0
	s_cbranch_scc0 .LBB0_542
; __device__ __forceinline__ float gelu_t(float x) { float u = 0.7978845608028654f * (x + 0.044715f * x * x * x); return x * __builtin_amdgcn_rcpf(1.f + __expf(-2.f * u)); }
; __device__ __forceinline__ void compress_item(const Params& P, int layer, int idx, const bf16_t* z, bf16_t* kcv, char* lds) {
;     ...
; #pragma unroll
;   for (int jf = 0; jf < 8; ++jf)
; #pragma unroll
;     for (int e = 0; e < 4; ++e) part[(w * 16 + fr) * 132 + jf * 16 + 4 * fq + e] = acc[jf][e];
;   __syncthreads();
;   const float* cb1 = (const float*)(P.ws + OFF_CB1) + (layer * 2 + kv) * 128;
;   {
;     const int n = tid >> 4, j0 = (tid & 15) * 8;
; #pragma unroll
;     for (int e = 0; e < 8; ++e) { const int j = j0 + e; const float v = ((part[(0 * 16 + n) * 132 + j] + part[(1 * 16 + n) * 132 + j]) + part[(2 * 16 + n) * 132 + j]) + part[(3 * 16 + n) * 132 + j];
;       hid[n * 129 + j] = gelu_t(v + cb1[j]); }
;   }
;   __syncthreads();
;   {
;     const int n = tid >> 4, d0 = (tid & 15) * 4;
;     const float* w2 = P.cmp_w2 + (size_t)(layer * 2 + kv) * 128 * 64 + d0;
;     const float4 bb = *(const float4*)(P.cmp_b2 + (layer * 2 + kv) * 64 + d0);
;     float o0 = bb.x, o1 = bb.y, o2 = bb.z, o3 = bb.w;
; #pragma unroll 8
;     for (int j = 0; j < 128; ++j) { const float hv = hid[n * 129 + j]; const float4 wa = *(const float4*)(w2 + j * 64); o0 += hv * wa.x; o1 += hv * wa.y; o2 += hv * wa.z; o3 += hv * wa.w; }
	v_and_b32_e32 v34, 3, v72
	v_and_or_b32 v35, v73, 48, v70
	v_mul_u32_u24_e32 v35, 0x210, v35
	v_lshlrev_b32_e32 v34, 4, v34
	v_add3_u32 v34, v60, v35, v34
	ds_write_b128 v34, v[0:3]
	ds_write_b128 v34, v[4:7] offset:64
	ds_write_b128 v34, v[8:11] offset:128
	ds_write_b128 v34, v[12:15] offset:192
	ds_write_b128 v34, v[16:19] offset:256
	ds_write_b128 v34, v[20:23] offset:320
	ds_write_b128 v34, v[24:27] offset:384
	ds_write_b128 v34, v[28:31] offset:448
	v_lshlrev_b32_e32 v0, 7, v32
	v_readlane_b32 s34, v253, 7
	v_ashrrev_i32_e32 v1, 31, v0
	v_readlane_b32 s35, v253, 8
	v_lshlrev_b32_e32 v176, 5, v70
	s_waitcnt lgkmcnt(0)
	v_lshl_add_u64 v[0:1], v[0:1], 2, s[34:35]
	v_lshl_add_u64 v[4:5], v[0:1], 0, v[176:177]
	s_barrier
	global_load_dwordx4 v[0:3], v[4:5], off
	global_load_dwordx4 v[6:9], v[4:5], off offset:16
	v_bfe_u32 v5, v71, 4, 4
	v_mul_u32_u24_e32 v4, 0x84, v5
	v_lshlrev_b32_e32 v18, 2, v4
	v_add3_u32 v4, v60, v18, v176
	ds_read_b64 v[10:11], v4
	ds_read_b64 v[12:13], v4 offset:8448
	ds_read_b64 v[14:15], v4 offset:16896
	ds_read_b64 v[16:17], v4 offset:25344
	s_mov_b32 s17, 0x8800
	v_readlane_b32 s60, v252, 18
	s_waitcnt lgkmcnt(2)
	v_pk_add_f32 v[10:11], v[10:11], v[12:13]
	v_readlane_b32 s74, v252, 32
	s_waitcnt lgkmcnt(1)
	v_pk_add_f32 v[10:11], v[10:11], v[14:15]
	v_readlane_b32 s75, v252, 33
	s_waitcnt lgkmcnt(0)
	v_pk_add_f32 v[10:11], v[10:11], v[16:17]
	v_mul_i32_i24_e32 v16, -12, v5
	v_add3_u32 v12, v4, v16, s17
	v_add3_u32 v17, v60, v176, v18
	v_lshlrev_b32_e32 v176, 4, v70
	s_mov_b32 s17, 0x8818
	v_readlane_b32 s72, v252, 30
	v_readlane_b32 s73, v252, 31
	s_mov_b64 s[34:35], 0
	v_readlane_b32 s61, v252, 19
	v_readlane_b32 s62, v252, 20
	v_readlane_b32 s63, v252, 21
	v_readlane_b32 s64, v252, 22
	v_readlane_b32 s65, v252, 23
	v_readlane_b32 s66, v252, 24
	v_readlane_b32 s67, v252, 25
	v_readlane_b32 s68, v252, 26
	v_readlane_b32 s69, v252, 27
	v_readlane_b32 s70, v252, 28
	v_readlane_b32 s71, v252, 29
	s_waitcnt vmcnt(1)
	v_pk_add_f32 v[0:1], v[10:11], v[0:1]
	s_nop 0
	v_mul_f32_e32 v10, 0x3d372713, v0
	v_mul_f32_e32 v11, 0x3d372713, v1
	v_mul_f32_e32 v10, v0, v10
	v_mul_f32_e32 v11, v1, v11
	v_fma_f32 v10, v0, v10, v0
	v_fma_f32 v11, v1, v11, v1
	v_mul_f32_e32 v10, 0x3f4c422a, v10
	v_mul_f32_e32 v11, 0x3f4c422a, v11
	v_mul_f32_e32 v10, -2.0, v10
	v_mul_f32_e32 v11, -2.0, v11
	v_mul_f32_e32 v10, 0x3fb8aa3b, v10
	v_mul_f32_e32 v11, 0x3fb8aa3b, v11
	v_exp_f32_e32 v10, v10
	v_exp_f32_e32 v11, v11
	v_add_f32_e32 v10, 1.0, v10
	v_add_f32_e32 v11, 1.0, v11
	v_rcp_f32_e32 v10, v10
	v_rcp_f32_e32 v11, v11
	s_nop 0
	v_pk_mul_f32 v[0:1], v[0:1], v[10:11]
	ds_write2_b32 v12, v0, v1 offset1:1
	ds_read_b64 v[0:1], v17 offset:8
	ds_read_b64 v[10:11], v4 offset:8456
	ds_read_b64 v[12:13], v4 offset:16904
	ds_read_b64 v[14:15], v4 offset:25352
	s_waitcnt lgkmcnt(2)
	v_pk_add_f32 v[0:1], v[0:1], v[10:11]
	s_waitcnt lgkmcnt(1)
	v_pk_add_f32 v[0:1], v[0:1], v[12:13]
	v_mad_i32_i24 v10, v5, -12, v17
	s_waitcnt lgkmcnt(0)
	v_pk_add_f32 v[0:1], v[0:1], v[14:15]
	v_add_u32_e32 v11, 0x8808, v10
	v_pk_add_f32 v[0:1], v[0:1], v[2:3]
	v_mad_u32_u24 v14, v5, 12, v10
	v_mul_f32_e32 v2, 0x3d372713, v0
	v_mul_f32_e32 v3, 0x3d372713, v1
	v_mul_f32_e32 v2, v0, v2
	v_mul_f32_e32 v3, v1, v3
	v_fma_f32 v2, v0, v2, v0
	v_fma_f32 v3, v1, v3, v1
	v_mul_f32_e32 v2, 0x3f4c422a, v2
	v_mul_f32_e32 v3, 0x3f4c422a, v3
	v_mul_f32_e32 v2, -2.0, v2
	v_mul_f32_e32 v3, -2.0, v3
	v_mul_f32_e32 v2, 0x3fb8aa3b, v2
	v_mul_f32_e32 v3, 0x3fb8aa3b, v3
	v_exp_f32_e32 v2, v2
	v_exp_f32_e32 v3, v3
	v_add_f32_e32 v2, 1.0, v2
	v_add_f32_e32 v3, 1.0, v3
	v_rcp_f32_e32 v2, v2
	v_rcp_f32_e32 v3, v3
	s_nop 0
	v_pk_mul_f32 v[0:1], v[0:1], v[2:3]
	ds_write2_b32 v11, v0, v1 offset1:1
	ds_read_b64 v[0:1], v14 offset:16
	ds_read_b64 v[2:3], v4 offset:8464
	ds_read_b64 v[10:11], v4 offset:16912
	ds_read_b64 v[12:13], v4 offset:25360
	s_waitcnt lgkmcnt(2)
	v_pk_add_f32 v[0:1], v[0:1], v[2:3]
	s_waitcnt lgkmcnt(1)
	v_pk_add_f32 v[0:1], v[0:1], v[10:11]
	s_waitcnt lgkmcnt(0)
	v_pk_add_f32 v[0:1], v[0:1], v[12:13]
	v_lshlrev_b32_e32 v12, 6, v32
	s_waitcnt vmcnt(0)
	v_pk_add_f32 v[0:1], v[0:1], v[6:7]
	v_mad_i32_i24 v6, v5, -12, v14
	v_mul_f32_e32 v2, 0x3d372713, v0
	v_mul_f32_e32 v3, 0x3d372713, v1
	v_mul_f32_e32 v2, v0, v2
	v_mul_f32_e32 v3, v1, v3
	v_fma_f32 v2, v0, v2, v0
	v_fma_f32 v3, v1, v3, v1
	v_mul_f32_e32 v2, 0x3f4c422a, v2
	v_mul_f32_e32 v3, 0x3f4c422a, v3
	v_mul_f32_e32 v2, -2.0, v2
	v_mul_f32_e32 v3, -2.0, v3
	v_mul_f32_e32 v2, 0x3fb8aa3b, v2
	v_mul_f32_e32 v3, 0x3fb8aa3b, v3
	v_exp_f32_e32 v2, v2
	v_exp_f32_e32 v3, v3
	v_add_u32_e32 v7, 0x8810, v6
	v_mad_u32_u24 v14, v5, 12, v6
	v_add_f32_e32 v2, 1.0, v2
	v_add_f32_e32 v3, 1.0, v3
	v_rcp_f32_e32 v2, v2
	v_rcp_f32_e32 v3, v3
	v_ashrrev_i32_e32 v13, 31, v12
	v_pk_mul_f32 v[0:1], v[0:1], v[2:3]
	ds_write2_b32 v7, v0, v1 offset1:1
	ds_read_b64 v[0:1], v14 offset:24
	ds_read_b64 v[2:3], v4 offset:8472
	ds_read_b64 v[6:7], v4 offset:16920
	ds_read_b64 v[10:11], v4 offset:25368
	s_waitcnt lgkmcnt(2)
	v_pk_add_f32 v[0:1], v[0:1], v[2:3]
	s_waitcnt lgkmcnt(1)
	v_pk_add_f32 v[0:1], v[0:1], v[6:7]
	s_waitcnt lgkmcnt(0)
	v_pk_add_f32 v[0:1], v[0:1], v[10:11]
	s_nop 0
	v_pk_add_f32 v[0:1], v[0:1], v[8:9]
	v_add3_u32 v8, v16, v18, v64
	v_mul_f32_e32 v2, 0x3d372713, v0
	v_mul_f32_e32 v3, 0x3d372713, v1
	v_mul_f32_e32 v2, v0, v2
	v_mul_f32_e32 v3, v1, v3
	v_fma_f32 v2, v0, v2, v0
	v_fma_f32 v3, v1, v3, v1
	v_mul_f32_e32 v2, 0x3f4c422a, v2
	v_mul_f32_e32 v3, 0x3f4c422a, v3
	v_mul_f32_e32 v2, -2.0, v2
	v_mul_f32_e32 v3, -2.0, v3
	v_mul_f32_e32 v2, 0x3fb8aa3b, v2
	v_mul_f32_e32 v3, 0x3fb8aa3b, v3
	v_exp_f32_e32 v4, v2
	v_exp_f32_e32 v6, v3
	v_lshl_add_u64 v[2:3], v[12:13], 2, s[74:75]
	v_lshl_add_u64 v[2:3], v[2:3], 0, v[176:177]
	v_add_f32_e32 v4, 1.0, v4
	v_add_f32_e32 v7, 1.0, v6
	v_rcp_f32_e32 v6, v4
	v_rcp_f32_e32 v7, v7
	v_add3_u32 v4, v14, v16, s17
	v_pk_mul_f32 v[0:1], v[0:1], v[6:7]
	ds_write2_b32 v4, v0, v1 offset1:1
	s_waitcnt lgkmcnt(0)
	s_barrier
	global_load_dwordx4 v[0:3], v[2:3], off
	v_lshlrev_b64 v[6:7], 15, v[32:33]
	v_lshl_add_u64 v[6:7], s[72:73], 0, v[6:7]
	v_lshlrev_b32_e32 v4, 2, v70
	v_lshl_add_u64 v[6:7], v[6:7], 0, v[176:177]
	v_lshl_add_u64 v[16:17], v[6:7], 0, s[34:35]
	global_load_dwordx4 v[84:87], v[16:17], off
	global_load_dwordx4 v[88:91], v[16:17], off offset:256
	global_load_dwordx4 v[92:95], v[16:17], off offset:512
	global_load_dwordx4 v[96:99], v[16:17], off offset:768
	global_load_dwordx4 v[100:103], v[16:17], off offset:1024
	global_load_dwordx4 v[104:107], v[16:17], off offset:1280
	global_load_dwordx4 v[108:111], v[16:17], off offset:1536
	global_load_dwordx4 v[112:115], v[16:17], off offset:1792
; __device__ __forceinline__ unsigned pk2(float lo, float hi) { const f32x2v v = {lo, hi}; const bf16x2v r = __builtin_convertvector(v, bf16x2v); return __builtin_bit_cast(unsigned, r); }
; __device__ __forceinline__ void compress_item(const Params& P, int layer, int idx, const bf16_t* z, bf16_t* kcv, char* lds) {
;     ...
;     const int n = tid >> 4, d0 = (tid & 15) * 4;
;     const float* w2 = P.cmp_w2 + (size_t)(layer * 2 + kv) * 128 * 64 + d0;
;     const float4 bb = *(const float4*)(P.cmp_b2 + (layer * 2 + kv) * 64 + d0);
;     float o0 = bb.x, o1 = bb.y, o2 = bb.z, o3 = bb.w;
; #pragma unroll 8
;     for (int j = 0; j < 128; ++j) { const float hv = hid[n * 129 + j]; const float4 wa = *(const float4*)(w2 + j * 64); o0 += hv * wa.x; o1 += hv * wa.y; o2 += hv * wa.z; o3 += hv * wa.w; }
;     u32x2 ov; ov.x = pk2(o0, o1); ov.y = pk2(o2, o3);
;     if ((n0 + n) >= 255) { ov.x = 0u; ov.y = 0u; }
;     *(u32x2*)(kcv + ((size_t)((kv * 8 + b) * 2 + g) * 256 + n0 + n) * 64 + d0) = ov;
.LBB0_544:
	global_load_dwordx4 v[124:127], v[16:17], off offset:2048
	global_load_dwordx4 v[128:131], v[16:17], off offset:2304
	global_load_dwordx4 v[132:135], v[16:17], off offset:2560
	global_load_dwordx4 v[136:139], v[16:17], off offset:2816
	global_load_dwordx4 v[140:143], v[16:17], off offset:3072
	global_load_dwordx4 v[144:147], v[16:17], off offset:3328
	global_load_dwordx4 v[148:151], v[16:17], off offset:3584
	global_load_dwordx4 v[152:155], v[16:17], off offset:3840
	ds_read2_b32 v[116:117], v8 offset0:0 offset1:1
	ds_read2_b32 v[118:119], v8 offset0:2 offset1:3
	ds_read2_b32 v[120:121], v8 offset0:4 offset1:5
	ds_read2_b32 v[122:123], v8 offset0:6 offset1:7
	s_waitcnt vmcnt(15) lgkmcnt(3)
	v_pk_fma_f32 v[0:1], v[116:117], v[84:85], v[0:1] op_sel_hi:[0,1,1]
	v_pk_fma_f32 v[2:3], v[116:117], v[86:87], v[2:3] op_sel_hi:[0,1,1]
	s_waitcnt vmcnt(14)
	v_pk_fma_f32 v[0:1], v[116:117], v[88:89], v[0:1] op_sel:[1,0,0]
	v_pk_fma_f32 v[2:3], v[116:117], v[90:91], v[2:3] op_sel:[1,0,0]
	s_waitcnt vmcnt(13) lgkmcnt(2)
	v_pk_fma_f32 v[0:1], v[118:119], v[92:93], v[0:1] op_sel_hi:[0,1,1]
	v_pk_fma_f32 v[2:3], v[118:119], v[94:95], v[2:3] op_sel_hi:[0,1,1]
	s_waitcnt vmcnt(12)
	v_pk_fma_f32 v[0:1], v[118:119], v[96:97], v[0:1] op_sel:[1,0,0]
	v_pk_fma_f32 v[2:3], v[118:119], v[98:99], v[2:3] op_sel:[1,0,0]
	s_waitcnt vmcnt(11) lgkmcnt(1)
	v_pk_fma_f32 v[0:1], v[120:121], v[100:101], v[0:1] op_sel_hi:[0,1,1]
	v_pk_fma_f32 v[2:3], v[120:121], v[102:103], v[2:3] op_sel_hi:[0,1,1]
	s_waitcnt vmcnt(10)
	v_pk_fma_f32 v[0:1], v[120:121], v[104:105], v[0:1] op_sel:[1,0,0]
	v_pk_fma_f32 v[2:3], v[120:121], v[106:107], v[2:3] op_sel:[1,0,0]
	s_waitcnt vmcnt(9) lgkmcnt(0)
	v_pk_fma_f32 v[0:1], v[122:123], v[108:109], v[0:1] op_sel_hi:[0,1,1]
	v_pk_fma_f32 v[2:3], v[122:123], v[110:111], v[2:3] op_sel_hi:[0,1,1]
	s_waitcnt vmcnt(8)
	v_pk_fma_f32 v[0:1], v[122:123], v[112:113], v[0:1] op_sel:[1,0,0]
	v_pk_fma_f32 v[2:3], v[122:123], v[114:115], v[2:3] op_sel:[1,0,0]
	s_add_u32 s34, s34, 0x1000
	s_addc_u32 s35, s35, 0
	s_cmpk_lg_u32 s34, 0x8000
	s_cbranch_scc0 .Lw2_last
	v_lshl_add_u64 v[16:17], v[6:7], 0, s[34:35]
	global_load_dwordx4 v[84:87], v[16:17], off
	global_load_dwordx4 v[88:91], v[16:17], off offset:256
	global_load_dwordx4 v[92:95], v[16:17], off offset:512
	global_load_dwordx4 v[96:99], v[16:17], off offset:768
	global_load_dwordx4 v[100:103], v[16:17], off offset:1024
	global_load_dwordx4 v[104:107], v[16:17], off offset:1280
	global_load_dwordx4 v[108:111], v[16:17], off offset:1536
	global_load_dwordx4 v[112:115], v[16:17], off offset:1792
	ds_read2_b32 v[116:117], v8 offset0:8 offset1:9
	ds_read2_b32 v[118:119], v8 offset0:10 offset1:11
	ds_read2_b32 v[120:121], v8 offset0:12 offset1:13
	ds_read2_b32 v[122:123], v8 offset0:14 offset1:15
	v_add_u32_e32 v8, 64, v8
	s_waitcnt vmcnt(15) lgkmcnt(3)
	v_pk_fma_f32 v[0:1], v[116:117], v[124:125], v[0:1] op_sel_hi:[0,1,1]
	v_pk_fma_f32 v[2:3], v[116:117], v[126:127], v[2:3] op_sel_hi:[0,1,1]
	s_waitcnt vmcnt(14)
	v_pk_fma_f32 v[0:1], v[116:117], v[128:129], v[0:1] op_sel:[1,0,0]
	v_pk_fma_f32 v[2:3], v[116:117], v[130:131], v[2:3] op_sel:[1,0,0]
	s_waitcnt vmcnt(13) lgkmcnt(2)
	v_pk_fma_f32 v[0:1], v[118:119], v[132:133], v[0:1] op_sel_hi:[0,1,1]
	v_pk_fma_f32 v[2:3], v[118:119], v[134:135], v[2:3] op_sel_hi:[0,1,1]
	s_waitcnt vmcnt(12)
	v_pk_fma_f32 v[0:1], v[118:119], v[136:137], v[0:1] op_sel:[1,0,0]
	v_pk_fma_f32 v[2:3], v[118:119], v[138:139], v[2:3] op_sel:[1,0,0]
	s_waitcnt vmcnt(11) lgkmcnt(1)
	v_pk_fma_f32 v[0:1], v[120:121], v[140:141], v[0:1] op_sel_hi:[0,1,1]
	v_pk_fma_f32 v[2:3], v[120:121], v[142:143], v[2:3] op_sel_hi:[0,1,1]
	s_waitcnt vmcnt(10)
	v_pk_fma_f32 v[0:1], v[120:121], v[144:145], v[0:1] op_sel:[1,0,0]
	v_pk_fma_f32 v[2:3], v[120:121], v[146:147], v[2:3] op_sel:[1,0,0]
	s_waitcnt vmcnt(9) lgkmcnt(0)
	v_pk_fma_f32 v[0:1], v[122:123], v[148:149], v[0:1] op_sel_hi:[0,1,1]
	v_pk_fma_f32 v[2:3], v[122:123], v[150:151], v[2:3] op_sel_hi:[0,1,1]
	s_waitcnt vmcnt(8)
	v_pk_fma_f32 v[0:1], v[122:123], v[152:153], v[0:1] op_sel:[1,0,0]
	v_pk_fma_f32 v[2:3], v[122:123], v[154:155], v[2:3] op_sel:[1,0,0]
	s_branch .LBB0_544
.Lw2_last:
	ds_read2_b32 v[116:117], v8 offset0:8 offset1:9
	ds_read2_b32 v[118:119], v8 offset0:10 offset1:11
	ds_read2_b32 v[120:121], v8 offset0:12 offset1:13
	ds_read2_b32 v[122:123], v8 offset0:14 offset1:15
	s_waitcnt vmcnt(7) lgkmcnt(3)
	v_pk_fma_f32 v[0:1], v[116:117], v[124:125], v[0:1] op_sel_hi:[0,1,1]
	v_pk_fma_f32 v[2:3], v[116:117], v[126:127], v[2:3] op_sel_hi:[0,1,1]
	s_waitcnt vmcnt(6)
	v_pk_fma_f32 v[0:1], v[116:117], v[128:129], v[0:1] op_sel:[1,0,0]
	v_pk_fma_f32 v[2:3], v[116:117], v[130:131], v[2:3] op_sel:[1,0,0]
	s_waitcnt vmcnt(5) lgkmcnt(2)
	v_pk_fma_f32 v[0:1], v[118:119], v[132:133], v[0:1] op_sel_hi:[0,1,1]
	v_pk_fma_f32 v[2:3], v[118:119], v[134:135], v[2:3] op_sel_hi:[0,1,1]
	s_waitcnt vmcnt(4)
	v_pk_fma_f32 v[0:1], v[118:119], v[136:137], v[0:1] op_sel:[1,0,0]
	v_pk_fma_f32 v[2:3], v[118:119], v[138:139], v[2:3] op_sel:[1,0,0]
	s_waitcnt vmcnt(3) lgkmcnt(1)
	v_pk_fma_f32 v[0:1], v[120:121], v[140:141], v[0:1] op_sel_hi:[0,1,1]
	v_pk_fma_f32 v[2:3], v[120:121], v[142:143], v[2:3] op_sel_hi:[0,1,1]
	s_waitcnt vmcnt(2)
	v_pk_fma_f32 v[0:1], v[120:121], v[144:145], v[0:1] op_sel:[1,0,0]
	v_pk_fma_f32 v[2:3], v[120:121], v[146:147], v[2:3] op_sel:[1,0,0]
	s_waitcnt vmcnt(1) lgkmcnt(0)
	v_pk_fma_f32 v[0:1], v[122:123], v[148:149], v[0:1] op_sel_hi:[0,1,1]
	v_pk_fma_f32 v[2:3], v[122:123], v[150:151], v[2:3] op_sel_hi:[0,1,1]
	s_waitcnt vmcnt(0)
	v_pk_fma_f32 v[0:1], v[122:123], v[152:153], v[0:1] op_sel:[1,0,0]
	v_pk_fma_f32 v[2:3], v[122:123], v[154:155], v[2:3] op_sel:[1,0,0]
	v_cvt_pk_bf16_f32 v0, v0, v1
	v_cvt_pk_bf16_f32 v1, v2, v3
	v_or_b32_e32 v2, v5, v68
	s_movk_i32 s36, 0xff
	v_and_b32_e32 v6, 1, v67
	v_cmp_ne_u32_e32 vcc, s36, v2
	v_lshlrev_b32_e32 v2, 4, v66
	v_lshlrev_b32_e32 v3, 1, v69
	v_or3_b32 v2, v3, v2, v6
	v_ashrrev_i32_e32 v3, 31, v2
	v_lshlrev_b64 v[2:3], 8, v[2:3]
	v_or3_b32 v2, v2, v68, v5
	v_readlane_b32 s34, v252, 42
	v_readlane_b32 s17, v253, 4
	v_lshlrev_b64 v[2:3], 7, v[2:3]
	v_readlane_b32 s35, v252, 43
	v_add_u32_e32 v65, s17, v65
	s_movk_i32 s17, 0x1ff
	v_cndmask_b32_e32 v1, 0, v1, vcc
	v_cndmask_b32_e32 v0, 0, v0, vcc
	v_lshl_add_u64 v[2:3], s[34:35], 0, v[2:3]
	v_lshlrev_b32_e32 v176, 1, v4
	v_cmp_lt_i32_e32 vcc, s17, v65
	v_lshl_add_u64 v[2:3], v[2:3], 0, v[176:177]
	s_or_b64 s[30:31], vcc, s[30:31]
	s_movk_i32 s61, 0x1400
	global_store_dwordx2 v[2:3], v[0:1], off
	s_barrier
	s_andn2_b64 exec, exec, s[30:31]
	s_cbranch_execnz .LBB0_541

; __device__ __forceinline__ unsigned pk2(float lo, float hi) { const f32x2v v = {lo, hi}; const bf16x2v r = __builtin_convertvector(v, bf16x2v); return __builtin_bit_cast(unsigned, r); }
; __device__ __forceinline__ float gelu_t(float x) { float u = 0.7978845608028654f * (x + 0.044715f * x * x * x); return x * __builtin_amdgcn_rcpf(1.f + __expf(-2.f * u)); }
; __device__ __forceinline__ f32x4 mfma16(bf16x8 a, bf16x8 b, f32x4 c) { return __builtin_amdgcn_mfma_f32_16x16x32_bf16(a, b, c, 0, 0, 0); }
; __device__ __forceinline__ void mixA_item(const Params& P, int layer, int idx, const bf16_t* z, bf16_t* y, char* lds) {
;     ...
;   for (int ks = 0; ks <= w; ++ks) {
;     bf16x8 wf[2], vf[4];
; #pragma unroll
;     for (int tm = 0; tm < 2; ++tm) wf[tm] = *(const bf16x8*)(W + (size_t)(32 * w + tm * 16 + fr) * 128 + ks * 32 + 8 * fq);
; #pragma unroll
;     for (int dn = 0; dn < 4; ++dn) vf[dn] = *(const bf16x8*)(vT + (dn * 16 + fr) * 136 + ks * 32 + 8 * fq);
; #pragma unroll
;     for (int tm = 0; tm < 2; ++tm)
; #pragma unroll
;       for (int dn = 0; dn < 4; ++dn) acc[tm][dn] = mfma16(vf[dn], wf[tm], acc[tm][dn]);
;   }
; #pragma unroll
;   for (int tm = 0; tm < 2; ++tm) {
;     const int t = 32 * w + tm * 16 + fr;
;     const float bias = P.sgu_b[(layer * 4 + g) * 128 + t];
; #pragma unroll
;     for (int dn = 0; dn < 4; ++dn) {
;       const int d = dn * 16 + 4 * fq;
;       const uint2 uu = *(const uint2*)(z + (size_t)(tok0 + t) * LDZ + ZC_AU + g * 64 + d);
;       const float u0 = gelu_t(__uint_as_float(uu.x << 16)), u1 = gelu_t(__uint_as_float(uu.x & 0xffff0000u)),
;                   u2 = gelu_t(__uint_as_float(uu.y << 16)), u3 = gelu_t(__uint_as_float(uu.y & 0xffff0000u));
;       uint2 o; o.x = pk2(u0 * (acc[tm][dn][0] + bias), u1 * (acc[tm][dn][1] + bias)); o.y = pk2(u2 * (acc[tm][dn][2] + bias), u3 * (acc[tm][dn][3] + bias));
;       *(uint2*)(y + (size_t)(tok0 + t) * 1024 + g * 64 + d) = o;
;     }
;   }
.LBB0_551:
	global_load_dwordx4 v[46:49], v[34:35], off
	ds_read_b128 v[50:53], v41
	ds_read_b128 v[54:57], v41 offset:4352
	ds_read_b128 v[62:65], v41 offset:8704
	ds_read_b128 v[66:69], v41 offset:13056
	v_add_co_u32_e32 v58, vcc, s38, v34
	v_add_u32_e32 v44, -1, v44
	s_nop 0
	v_addc_co_u32_e32 v59, vcc, 0, v35, vcc
	v_cmp_eq_u32_e32 vcc, 0, v44
	v_add_u32_e32 v41, 64, v41
	s_or_b64 s[30:31], vcc, s[30:31]
	v_lshl_add_u64 v[34:35], v[34:35], 0, 64
	s_waitcnt vmcnt(0) lgkmcnt(3)
	v_mfma_f32_16x16x32_bf16 v[28:31], v[50:53], v[46:49], v[28:31]
	s_waitcnt lgkmcnt(2)
	v_mfma_f32_16x16x32_bf16 v[24:27], v[54:57], v[46:49], v[24:27]
	s_waitcnt lgkmcnt(1)
	v_mfma_f32_16x16x32_bf16 v[20:23], v[62:65], v[46:49], v[20:23]
	s_waitcnt lgkmcnt(0)
	v_mfma_f32_16x16x32_bf16 v[16:19], v[66:69], v[46:49], v[16:19]
	global_load_dwordx4 v[46:49], v[58:59], off
	s_waitcnt vmcnt(0)
	v_mfma_f32_16x16x32_bf16 v[12:15], v[50:53], v[46:49], v[12:15]
	v_mfma_f32_16x16x32_bf16 v[8:11], v[54:57], v[46:49], v[8:11]
	v_mfma_f32_16x16x32_bf16 v[4:7], v[62:65], v[46:49], v[4:7]
	v_mfma_f32_16x16x32_bf16 v[0:3], v[66:69], v[46:49], v[0:3]
	s_andn2_b64 exec, exec, s[30:31]
	s_cbranch_execnz .LBB0_551
	s_or_b64 exec, exec, s[30:31]
	v_lshl_or_b32 v45, v33, 5, v38
	v_lshlrev_b32_e32 v176, 1, v32
	v_readlane_b32 s30, v252, 34
	v_lshl_add_u64 v[32:33], s[84:85], 0, v[176:177]
	v_readlane_b32 s31, v252, 35
	v_or_b32_e32 v36, v45, v36
	v_lshl_or_b32 v44, v37, 7, s16
	v_lshl_add_u64 v[34:35], s[30:31], 0, v[176:177]
	v_mad_i64_i32 v[46:47], s[30:31], v36, s43, v[32:33]
	v_lshlrev_b32_e32 v176, 3, v40
	v_lshl_add_u64 v[40:41], v[46:47], 0, v[176:177]
	global_load_dwordx2 v[46:47], v[40:41], off
	global_load_dwordx2 v[86:87], v[40:41], off offset:32
	global_load_dwordx2 v[88:89], v[40:41], off offset:64
	global_load_dwordx2 v[90:91], v[40:41], off offset:96
	v_add_co_u32_e32 v92, vcc, 0x14000, v40
	s_nop 1
	v_addc_co_u32_e32 v93, vcc, 0, v41, vcc
	global_load_dwordx2 v[94:95], v[92:93], off
	global_load_dwordx2 v[96:97], v[92:93], off offset:32
	global_load_dwordx2 v[98:99], v[92:93], off offset:64
	global_load_dwordx2 v[100:101], v[92:93], off offset:96
	v_or_b32_e32 v37, v45, v44
	v_readlane_b32 s60, v252, 2
	v_lshlrev_b32_e32 v37, 2, v37
	v_readlane_b32 s66, v252, 8
	v_readlane_b32 s67, v252, 9
	v_readlane_b32 s61, v252, 3
	v_readlane_b32 s62, v252, 4
	v_readlane_b32 s63, v252, 5
	v_readlane_b32 s64, v252, 6
	v_readlane_b32 s65, v252, 7
	global_load_dword v38, v37, s[66:67]
	v_ashrrev_i32_e32 v37, 31, v36
	v_lshlrev_b64 v[48:49], 11, v[36:37]
	v_lshl_add_u64 v[48:49], v[34:35], 0, v[48:49]
	v_readlane_b32 s68, v252, 10
	v_readlane_b32 s69, v252, 11
	v_readlane_b32 s70, v252, 12
	v_readlane_b32 s71, v252, 13
	v_readlane_b32 s72, v252, 14
	v_readlane_b32 s73, v252, 15
	v_readlane_b32 s74, v252, 16
	v_readlane_b32 s75, v252, 17
	s_waitcnt vmcnt(1)
	v_lshlrev_b32_e32 v50, 16, v46
	v_mul_f32_e32 v37, 0x3d372713, v50
	v_mul_f32_e32 v37, v37, v50
	v_mov_b32_e32 v52, v50
	v_fmac_f32_e32 v52, v37, v52
	v_mul_f32_e32 v37, 0x3f4c422a, v52
	v_mul_f32_e32 v37, -2.0, v37
	v_mul_f32_e32 v37, 0x3fb8aa3b, v37
	v_exp_f32_e32 v37, v37
	v_and_b32_e32 v51, 0xffff0000, v46
	v_mov_b32_e32 v53, v51
	s_waitcnt vmcnt(0)
	v_pk_add_f32 v[28:29], v[28:29], v[38:39] op_sel_hi:[1,0]
	v_add_f32_e32 v37, 1.0, v37
	v_rcp_f32_e32 v52, v37
	v_mul_f32_e32 v37, 0x3d372713, v51
	v_mul_f32_e32 v37, v37, v51
	v_fmac_f32_e32 v53, v37, v53
	v_mul_f32_e32 v37, 0x3f4c422a, v53
	v_mul_f32_e32 v37, -2.0, v37
	v_mul_f32_e32 v37, 0x3fb8aa3b, v37
	v_exp_f32_e32 v37, v37
	v_lshlrev_b32_e32 v46, 16, v47
	v_and_b32_e32 v47, 0xffff0000, v47
	v_pk_add_f32 v[30:31], v[30:31], v[38:39] op_sel_hi:[1,0]
	v_add_f32_e32 v37, 1.0, v37
	v_rcp_f32_e32 v53, v37
	v_mov_b32_e32 v37, v47
	v_pk_add_f32 v[24:25], v[24:25], v[38:39] op_sel_hi:[1,0]
	v_pk_add_f32 v[26:27], v[26:27], v[38:39] op_sel_hi:[1,0]
	v_pk_mul_f32 v[50:51], v[52:53], v[50:51]
	v_pk_add_f32 v[20:21], v[20:21], v[38:39] op_sel_hi:[1,0]
	v_pk_mul_f32 v[28:29], v[28:29], v[50:51]
	v_pk_add_f32 v[22:23], v[22:23], v[38:39] op_sel_hi:[1,0]
	v_cvt_pk_bf16_f32 v50, v28, v29
	v_mul_f32_e32 v28, 0x3d372713, v46
	v_mul_f32_e32 v28, v28, v46
	v_mov_b32_e32 v29, v46
	v_fmac_f32_e32 v29, v28, v29
	v_mul_f32_e32 v28, 0x3f4c422a, v29
	v_mul_f32_e32 v29, 0x3d372713, v47
	v_mul_f32_e32 v29, v29, v47
	v_fmac_f32_e32 v37, v29, v37
	v_mul_f32_e32 v29, 0x3f4c422a, v37
	v_mul_f32_e32 v28, -2.0, v28
	v_mul_f32_e32 v29, -2.0, v29
	v_mul_f32_e32 v28, 0x3fb8aa3b, v28
	v_mul_f32_e32 v29, 0x3fb8aa3b, v29
	v_exp_f32_e32 v28, v28
	v_exp_f32_e32 v29, v29
	v_pk_add_f32 v[16:17], v[16:17], v[38:39] op_sel_hi:[1,0]
	v_pk_add_f32 v[18:19], v[18:19], v[38:39] op_sel_hi:[1,0]
	v_add_f32_e32 v28, 1.0, v28
	v_add_f32_e32 v29, 1.0, v29
	v_rcp_f32_e32 v28, v28
	v_rcp_f32_e32 v29, v29
	s_nop 0
	v_pk_mul_f32 v[28:29], v[28:29], v[46:47]
	s_nop 0
	v_pk_mul_f32 v[28:29], v[30:31], v[28:29]
	v_mov_b32_e32 v30, v86
	v_mov_b32_e32 v31, v87
	v_cvt_pk_bf16_f32 v51, v28, v29
	v_lshl_add_u64 v[28:29], v[48:49], 0, v[176:177]
	global_store_dwordx2 v[28:29], v[50:51], off
	v_lshlrev_b32_e32 v46, 16, v30
	v_mul_f32_e32 v37, 0x3d372713, v46
	v_mul_f32_e32 v37, v37, v46
	v_mov_b32_e32 v48, v46
	v_fmac_f32_e32 v48, v37, v48
	v_mul_f32_e32 v37, 0x3f4c422a, v48
	v_mul_f32_e32 v37, -2.0, v37
	v_mul_f32_e32 v37, 0x3fb8aa3b, v37
	v_exp_f32_e32 v37, v37
	v_and_b32_e32 v47, 0xffff0000, v30
	v_mov_b32_e32 v49, v47
	v_lshlrev_b32_e32 v30, 16, v31
	v_add_f32_e32 v37, 1.0, v37
	v_rcp_f32_e32 v48, v37
	v_mul_f32_e32 v37, 0x3d372713, v47
	v_mul_f32_e32 v37, v37, v47
	v_fmac_f32_e32 v49, v37, v49
	v_mul_f32_e32 v37, 0x3f4c422a, v49
; __device__ __forceinline__ unsigned pk2(float lo, float hi) { const f32x2v v = {lo, hi}; const bf16x2v r = __builtin_convertvector(v, bf16x2v); return __builtin_bit_cast(unsigned, r); }
; __device__ __forceinline__ float gelu_t(float x) { float u = 0.7978845608028654f * (x + 0.044715f * x * x * x); return x * __builtin_amdgcn_rcpf(1.f + __expf(-2.f * u)); }
; __device__ __forceinline__ void mixA_item(const Params& P, int layer, int idx, const bf16_t* z, bf16_t* y, char* lds) {
;     ...
;   for (int tm = 0; tm < 2; ++tm) {
;     const int t = 32 * w + tm * 16 + fr;
;     const float bias = P.sgu_b[(layer * 4 + g) * 128 + t];
; #pragma unroll
;     for (int dn = 0; dn < 4; ++dn) {
;       const int d = dn * 16 + 4 * fq;
;       const uint2 uu = *(const uint2*)(z + (size_t)(tok0 + t) * LDZ + ZC_AU + g * 64 + d);
;       const float u0 = gelu_t(__uint_as_float(uu.x << 16)), u1 = gelu_t(__uint_as_float(uu.x & 0xffff0000u)),
;                   u2 = gelu_t(__uint_as_float(uu.y << 16)), u3 = gelu_t(__uint_as_float(uu.y & 0xffff0000u));
;       uint2 o; o.x = pk2(u0 * (acc[tm][dn][0] + bias), u1 * (acc[tm][dn][1] + bias)); o.y = pk2(u2 * (acc[tm][dn][2] + bias), u3 * (acc[tm][dn][3] + bias));
;       *(uint2*)(y + (size_t)(tok0 + t) * 1024 + g * 64 + d) = o;
;     }
;   }
	v_mul_f32_e32 v37, -2.0, v37
	v_mul_f32_e32 v37, 0x3fb8aa3b, v37
	v_exp_f32_e32 v37, v37
	v_and_b32_e32 v31, 0xffff0000, v31
	v_add_f32_e32 v37, 1.0, v37
	v_rcp_f32_e32 v49, v37
	v_mov_b32_e32 v37, v30
	v_pk_mul_f32 v[46:47], v[48:49], v[46:47]
	s_nop 0
	v_pk_mul_f32 v[24:25], v[24:25], v[46:47]
	s_nop 0
	v_cvt_pk_bf16_f32 v24, v24, v25
	v_mul_f32_e32 v25, 0x3d372713, v30
	v_mul_f32_e32 v25, v25, v30
	v_fmac_f32_e32 v37, v25, v37
	v_mul_f32_e32 v25, 0x3f4c422a, v37
	v_mul_f32_e32 v25, -2.0, v25
	v_mul_f32_e32 v25, 0x3fb8aa3b, v25
	v_exp_f32_e32 v25, v25
	v_mov_b32_e32 v37, v31
	v_add_f32_e32 v25, 1.0, v25
	v_rcp_f32_e32 v46, v25
	v_mul_f32_e32 v25, 0x3d372713, v31
	v_mul_f32_e32 v25, v25, v31
	v_fmac_f32_e32 v37, v25, v37
	v_mul_f32_e32 v25, 0x3f4c422a, v37
	v_mul_f32_e32 v25, -2.0, v25
	v_mul_f32_e32 v25, 0x3fb8aa3b, v25
	v_exp_f32_e32 v25, v25
	s_nop 0
	v_add_f32_e32 v25, 1.0, v25
	v_rcp_f32_e32 v47, v25
	s_nop 0
	v_pk_mul_f32 v[30:31], v[46:47], v[30:31]
	s_nop 0
	v_pk_mul_f32 v[26:27], v[26:27], v[30:31]
	s_nop 0
	v_cvt_pk_bf16_f32 v25, v26, v27
	global_store_dwordx2 v[28:29], v[24:25], off offset:32
	v_mov_b32_e32 v24, v88
	v_mov_b32_e32 v25, v89
	v_lshlrev_b32_e32 v26, 16, v24
	v_mul_f32_e32 v30, 0x3d372713, v26
	v_mul_f32_e32 v30, v30, v26
	v_mov_b32_e32 v31, v26
	v_and_b32_e32 v27, 0xffff0000, v24
	v_fmac_f32_e32 v31, v30, v31
	v_mul_f32_e32 v30, 0x3f4c422a, v31
	v_mul_f32_e32 v31, 0x3d372713, v27
	v_mul_f32_e32 v31, v31, v27
	v_mov_b32_e32 v37, v27
	v_fmac_f32_e32 v37, v31, v37
	v_mul_f32_e32 v31, 0x3f4c422a, v37
	v_mul_f32_e32 v30, -2.0, v30
	v_mul_f32_e32 v31, -2.0, v31
	v_mul_f32_e32 v30, 0x3fb8aa3b, v30
	v_mul_f32_e32 v31, 0x3fb8aa3b, v31
	v_exp_f32_e32 v30, v30
	v_exp_f32_e32 v31, v31
	v_lshlrev_b32_e32 v24, 16, v25
	v_and_b32_e32 v25, 0xffff0000, v25
	v_add_f32_e32 v30, 1.0, v30
	v_add_f32_e32 v31, 1.0, v31
	v_rcp_f32_e32 v30, v30
	v_rcp_f32_e32 v31, v31
	s_nop 0
	v_pk_mul_f32 v[26:27], v[30:31], v[26:27]
	s_nop 0
	v_pk_mul_f32 v[20:21], v[20:21], v[26:27]
	v_mov_b32_e32 v26, v24
	v_cvt_pk_bf16_f32 v20, v20, v21
	v_mul_f32_e32 v21, 0x3d372713, v24
	v_mul_f32_e32 v21, v21, v24
	v_fmac_f32_e32 v26, v21, v26
	v_mul_f32_e32 v21, 0x3f4c422a, v26
	v_mul_f32_e32 v21, -2.0, v21
	v_mul_f32_e32 v21, 0x3fb8aa3b, v21
	v_exp_f32_e32 v21, v21
	v_mov_b32_e32 v27, v25
	v_add_f32_e32 v21, 1.0, v21
	v_rcp_f32_e32 v26, v21
	v_mul_f32_e32 v21, 0x3d372713, v25
	v_mul_f32_e32 v21, v21, v25
	v_fmac_f32_e32 v27, v21, v27
	v_mul_f32_e32 v21, 0x3f4c422a, v27
	v_mul_f32_e32 v21, -2.0, v21
	v_mul_f32_e32 v21, 0x3fb8aa3b, v21
	v_exp_f32_e32 v21, v21
	s_nop 0
	v_add_f32_e32 v21, 1.0, v21
	v_rcp_f32_e32 v27, v21
	s_nop 0
	v_pk_mul_f32 v[24:25], v[26:27], v[24:25]
	s_nop 0
	v_pk_mul_f32 v[22:23], v[22:23], v[24:25]
	s_nop 0
	v_cvt_pk_bf16_f32 v21, v22, v23
	global_store_dwordx2 v[28:29], v[20:21], off offset:64
	v_mov_b32_e32 v20, v90
	v_mov_b32_e32 v21, v91
	v_lshlrev_b32_e32 v22, 16, v20
	v_mul_f32_e32 v24, 0x3d372713, v22
	v_mul_f32_e32 v24, v24, v22
	v_mov_b32_e32 v25, v22
	v_and_b32_e32 v23, 0xffff0000, v20
	v_fmac_f32_e32 v25, v24, v25
	v_mul_f32_e32 v24, 0x3f4c422a, v25
	v_mul_f32_e32 v25, 0x3d372713, v23
	v_mul_f32_e32 v25, v25, v23
	v_mov_b32_e32 v26, v23
	v_fmac_f32_e32 v26, v25, v26
	v_mul_f32_e32 v25, 0x3f4c422a, v26
	v_mul_f32_e32 v24, -2.0, v24
	v_mul_f32_e32 v25, -2.0, v25
	v_mul_f32_e32 v24, 0x3fb8aa3b, v24
	v_mul_f32_e32 v25, 0x3fb8aa3b, v25
	v_exp_f32_e32 v24, v24
	v_exp_f32_e32 v25, v25
	v_lshlrev_b32_e32 v20, 16, v21
	v_and_b32_e32 v21, 0xffff0000, v21
	v_add_f32_e32 v24, 1.0, v24
	v_add_f32_e32 v25, 1.0, v25
	v_rcp_f32_e32 v24, v24
	v_rcp_f32_e32 v25, v25
	s_nop 0
	v_pk_mul_f32 v[22:23], v[24:25], v[22:23]
	s_nop 0
	v_pk_mul_f32 v[16:17], v[16:17], v[22:23]
	v_mov_b32_e32 v22, v20
	v_cvt_pk_bf16_f32 v16, v16, v17
	v_mul_f32_e32 v17, 0x3d372713, v20
	v_mul_f32_e32 v17, v17, v20
	v_fmac_f32_e32 v22, v17, v22
	v_mul_f32_e32 v17, 0x3f4c422a, v22
	v_mul_f32_e32 v17, -2.0, v17
	v_mul_f32_e32 v17, 0x3fb8aa3b, v17
	v_exp_f32_e32 v17, v17
	v_mov_b32_e32 v23, v21
	v_add_f32_e32 v17, 1.0, v17
	v_rcp_f32_e32 v22, v17
	v_mul_f32_e32 v17, 0x3d372713, v21
	v_mul_f32_e32 v17, v17, v21
	v_fmac_f32_e32 v23, v17, v23
	v_mul_f32_e32 v17, 0x3f4c422a, v23
	v_mul_f32_e32 v17, -2.0, v17
	v_mul_f32_e32 v17, 0x3fb8aa3b, v17
	v_exp_f32_e32 v17, v17
	s_nop 0
	v_add_f32_e32 v17, 1.0, v17
	v_rcp_f32_e32 v23, v17
	s_nop 0
	v_pk_mul_f32 v[20:21], v[22:23], v[20:21]
	s_nop 0
	v_pk_mul_f32 v[18:19], v[18:19], v[20:21]
	s_nop 0
	v_cvt_pk_bf16_f32 v17, v18, v19
	v_or_b32_e32 v18, 16, v36
	v_ashrrev_i32_e32 v19, 31, v18
	v_mad_i64_i32 v[20:21], s[30:31], v18, s43, v[32:33]
	v_lshlrev_b64 v[18:19], 11, v[18:19]
	v_lshl_add_u64 v[22:23], v[34:35], 0, v[18:19]
	v_lshl_add_u64 v[18:19], v[20:21], 0, v[176:177]
	v_mov_b32_e32 v20, v94
	v_mov_b32_e32 v21, v95
	v_readlane_b32 s30, v253, 4
	global_store_dwordx2 v[28:29], v[16:17], off offset:96
	v_add_lshl_u32 v16, v45, v44, 2
	global_load_dword v16, v16, s[66:67] offset:64
	v_add_u32_e32 v43, s30, v43
	v_subrev_u16_e32 v42, s30, v42
	s_movk_i32 s30, 0x3ff
	v_readlane_b32 s31, v254, 44
	v_cmp_lt_i32_e32 vcc, s30, v43
	s_or_b64 s[36:37], vcc, s[36:37]
	v_add_u32_e32 v39, s31, v39
	s_waitcnt vmcnt(2)
	v_lshlrev_b32_e32 v24, 16, v20
	v_mul_f32_e32 v17, 0x3d372713, v24
	v_mul_f32_e32 v17, v17, v24
	v_mov_b32_e32 v26, v24
	v_fmac_f32_e32 v26, v17, v26
	v_mul_f32_e32 v17, 0x3f4c422a, v26
	v_mul_f32_e32 v17, -2.0, v17
	v_mul_f32_e32 v17, 0x3fb8aa3b, v17
	v_exp_f32_e32 v17, v17
	v_and_b32_e32 v25, 0xffff0000, v20
	v_mov_b32_e32 v27, v25
	v_lshlrev_b32_e32 v20, 16, v21
	v_add_f32_e32 v17, 1.0, v17
	v_rcp_f32_e32 v26, v17
	v_mul_f32_e32 v17, 0x3d372713, v25
	v_mul_f32_e32 v17, v17, v25
	v_fmac_f32_e32 v27, v17, v27
	v_mul_f32_e32 v17, 0x3f4c422a, v27
	v_mul_f32_e32 v17, -2.0, v17
	v_mul_f32_e32 v17, 0x3fb8aa3b, v17
	v_exp_f32_e32 v17, v17
	v_and_b32_e32 v21, 0xffff0000, v21
	v_add_f32_e32 v17, 1.0, v17
	v_rcp_f32_e32 v27, v17
	s_waitcnt vmcnt(0)
; __device__ __forceinline__ unsigned pk2(float lo, float hi) { const f32x2v v = {lo, hi}; const bf16x2v r = __builtin_convertvector(v, bf16x2v); return __builtin_bit_cast(unsigned, r); }
; __device__ __forceinline__ float gelu_t(float x) { float u = 0.7978845608028654f * (x + 0.044715f * x * x * x); return x * __builtin_amdgcn_rcpf(1.f + __expf(-2.f * u)); }
; __device__ __forceinline__ void mixA_item(const Params& P, int layer, int idx, const bf16_t* z, bf16_t* y, char* lds) {
;     ...
;   for (int tm = 0; tm < 2; ++tm) {
;     const int t = 32 * w + tm * 16 + fr;
;     const float bias = P.sgu_b[(layer * 4 + g) * 128 + t];
; #pragma unroll
;     for (int dn = 0; dn < 4; ++dn) {
;       const int d = dn * 16 + 4 * fq;
;       const uint2 uu = *(const uint2*)(z + (size_t)(tok0 + t) * LDZ + ZC_AU + g * 64 + d);
;       const float u0 = gelu_t(__uint_as_float(uu.x << 16)), u1 = gelu_t(__uint_as_float(uu.x & 0xffff0000u)),
;                   u2 = gelu_t(__uint_as_float(uu.y << 16)), u3 = gelu_t(__uint_as_float(uu.y & 0xffff0000u));
;       uint2 o; o.x = pk2(u0 * (acc[tm][dn][0] + bias), u1 * (acc[tm][dn][1] + bias)); o.y = pk2(u2 * (acc[tm][dn][2] + bias), u3 * (acc[tm][dn][3] + bias));
;       *(uint2*)(y + (size_t)(tok0 + t) * 1024 + g * 64 + d) = o;
;     }
;   }
	v_pk_add_f32 v[12:13], v[12:13], v[16:17] op_sel_hi:[1,0]
	v_mov_b32_e32 v17, v21
	v_pk_mul_f32 v[24:25], v[26:27], v[24:25]
	s_nop 0
	v_pk_mul_f32 v[12:13], v[12:13], v[24:25]
	s_nop 0
	v_cvt_pk_bf16_f32 v24, v12, v13
	v_mul_f32_e32 v12, 0x3d372713, v20
	v_mul_f32_e32 v12, v12, v20
	v_mov_b32_e32 v13, v20
	v_fmac_f32_e32 v13, v12, v13
	v_mul_f32_e32 v12, 0x3f4c422a, v13
	v_mul_f32_e32 v13, 0x3d372713, v21
	v_mul_f32_e32 v13, v13, v21
	v_fmac_f32_e32 v17, v13, v17
	v_mul_f32_e32 v13, 0x3f4c422a, v17
	v_mul_f32_e32 v12, -2.0, v12
	v_mul_f32_e32 v13, -2.0, v13
	v_mul_f32_e32 v12, 0x3fb8aa3b, v12
	v_mul_f32_e32 v13, 0x3fb8aa3b, v13
	v_exp_f32_e32 v12, v12
	v_exp_f32_e32 v13, v13
	v_pk_add_f32 v[14:15], v[14:15], v[16:17] op_sel_hi:[1,0]
	v_add_f32_e32 v12, 1.0, v12
	v_add_f32_e32 v13, 1.0, v13
	v_rcp_f32_e32 v12, v12
	v_rcp_f32_e32 v13, v13
	s_nop 0
	v_pk_mul_f32 v[12:13], v[12:13], v[20:21]
	s_nop 0
	v_pk_mul_f32 v[12:13], v[14:15], v[12:13]
	v_mov_b32_e32 v14, v96
	v_mov_b32_e32 v15, v97
	v_cvt_pk_bf16_f32 v25, v12, v13
	v_lshl_add_u64 v[12:13], v[22:23], 0, v[176:177]
	global_store_dwordx2 v[12:13], v[24:25], off
	v_lshlrev_b32_e32 v20, 16, v14
	v_mul_f32_e32 v17, 0x3d372713, v20
	v_mul_f32_e32 v17, v17, v20
	v_mov_b32_e32 v22, v20
	v_fmac_f32_e32 v22, v17, v22
	v_mul_f32_e32 v17, 0x3f4c422a, v22
	v_mul_f32_e32 v17, -2.0, v17
	v_mul_f32_e32 v17, 0x3fb8aa3b, v17
	v_exp_f32_e32 v17, v17
	v_and_b32_e32 v21, 0xffff0000, v14
	v_mov_b32_e32 v23, v21
	v_lshlrev_b32_e32 v14, 16, v15
	v_add_f32_e32 v17, 1.0, v17
	v_rcp_f32_e32 v22, v17
	v_mul_f32_e32 v17, 0x3d372713, v21
	v_mul_f32_e32 v17, v17, v21
	v_fmac_f32_e32 v23, v17, v23
	v_mul_f32_e32 v17, 0x3f4c422a, v23
	v_mul_f32_e32 v17, -2.0, v17
	v_mul_f32_e32 v17, 0x3fb8aa3b, v17
	v_exp_f32_e32 v17, v17
	v_and_b32_e32 v15, 0xffff0000, v15
	v_add_f32_e32 v17, 1.0, v17
	v_rcp_f32_e32 v23, v17
	v_pk_add_f32 v[8:9], v[8:9], v[16:17] op_sel_hi:[1,0]
	v_mov_b32_e32 v17, v14
	v_pk_mul_f32 v[20:21], v[22:23], v[20:21]
	s_nop 0
	v_pk_mul_f32 v[8:9], v[8:9], v[20:21]
	s_nop 0
	v_cvt_pk_bf16_f32 v8, v8, v9
	v_mul_f32_e32 v9, 0x3d372713, v14
	v_mul_f32_e32 v9, v9, v14
	v_fmac_f32_e32 v17, v9, v17
	v_mul_f32_e32 v9, 0x3f4c422a, v17
	v_mul_f32_e32 v9, -2.0, v9
	v_mul_f32_e32 v9, 0x3fb8aa3b, v9
	v_exp_f32_e32 v9, v9
	v_mov_b32_e32 v17, v15
	v_add_f32_e32 v9, 1.0, v9
	v_rcp_f32_e32 v20, v9
	v_mul_f32_e32 v9, 0x3d372713, v15
	v_mul_f32_e32 v9, v9, v15
	v_fmac_f32_e32 v17, v9, v17
	v_mul_f32_e32 v9, 0x3f4c422a, v17
	v_mul_f32_e32 v9, -2.0, v9
	v_mul_f32_e32 v9, 0x3fb8aa3b, v9
	v_exp_f32_e32 v9, v9
	v_pk_add_f32 v[10:11], v[10:11], v[16:17] op_sel_hi:[1,0]
	v_add_f32_e32 v9, 1.0, v9
	v_rcp_f32_e32 v21, v9
	s_nop 0
	v_pk_mul_f32 v[14:15], v[20:21], v[14:15]
	s_nop 0
	v_pk_mul_f32 v[10:11], v[10:11], v[14:15]
	s_nop 0
	v_cvt_pk_bf16_f32 v9, v10, v11
	global_store_dwordx2 v[12:13], v[8:9], off offset:32
	v_mov_b32_e32 v8, v98
	v_mov_b32_e32 v9, v99
	v_lshlrev_b32_e32 v10, 16, v8
	v_mul_f32_e32 v14, 0x3d372713, v10
	v_mul_f32_e32 v14, v14, v10
	v_mov_b32_e32 v15, v10
	v_and_b32_e32 v11, 0xffff0000, v8
	v_fmac_f32_e32 v15, v14, v15
	v_mul_f32_e32 v14, 0x3f4c422a, v15
	v_mul_f32_e32 v15, 0x3d372713, v11
	v_mul_f32_e32 v15, v15, v11
	v_mov_b32_e32 v17, v11
	v_fmac_f32_e32 v17, v15, v17
	v_mul_f32_e32 v15, 0x3f4c422a, v17
	v_mul_f32_e32 v14, -2.0, v14
	v_mul_f32_e32 v15, -2.0, v15
	v_mul_f32_e32 v14, 0x3fb8aa3b, v14
	v_mul_f32_e32 v15, 0x3fb8aa3b, v15
	v_exp_f32_e32 v14, v14
	v_exp_f32_e32 v15, v15
	v_pk_add_f32 v[4:5], v[4:5], v[16:17] op_sel_hi:[1,0]
	v_lshlrev_b32_e32 v8, 16, v9
	v_add_f32_e32 v14, 1.0, v14
	v_add_f32_e32 v15, 1.0, v15
	v_rcp_f32_e32 v14, v14
	v_rcp_f32_e32 v15, v15
	v_and_b32_e32 v9, 0xffff0000, v9
	v_pk_add_f32 v[6:7], v[6:7], v[16:17] op_sel_hi:[1,0]
	v_pk_add_f32 v[0:1], v[0:1], v[16:17] op_sel_hi:[1,0]
	v_pk_mul_f32 v[10:11], v[14:15], v[10:11]
	v_pk_add_f32 v[2:3], v[2:3], v[16:17] op_sel_hi:[1,0]
	v_pk_mul_f32 v[4:5], v[4:5], v[10:11]
	v_mov_b32_e32 v10, v8
	v_cvt_pk_bf16_f32 v4, v4, v5
	v_mul_f32_e32 v5, 0x3d372713, v8
	v_mul_f32_e32 v5, v5, v8
	v_fmac_f32_e32 v10, v5, v10
	v_mul_f32_e32 v5, 0x3f4c422a, v10
	v_mul_f32_e32 v5, -2.0, v5
	v_mul_f32_e32 v5, 0x3fb8aa3b, v5
	v_exp_f32_e32 v5, v5
	v_mov_b32_e32 v11, v9
	v_add_f32_e32 v5, 1.0, v5
	v_rcp_f32_e32 v10, v5
	v_mul_f32_e32 v5, 0x3d372713, v9
	v_mul_f32_e32 v5, v5, v9
	v_fmac_f32_e32 v11, v5, v11
	v_mul_f32_e32 v5, 0x3f4c422a, v11
	v_mul_f32_e32 v5, -2.0, v5
	v_mul_f32_e32 v5, 0x3fb8aa3b, v5
	v_exp_f32_e32 v5, v5
	s_nop 0
	v_add_f32_e32 v5, 1.0, v5
	v_rcp_f32_e32 v11, v5
	s_nop 0
	v_pk_mul_f32 v[8:9], v[10:11], v[8:9]
	s_nop 0
	v_pk_mul_f32 v[6:7], v[6:7], v[8:9]
	s_nop 0
	v_cvt_pk_bf16_f32 v5, v6, v7
	global_store_dwordx2 v[12:13], v[4:5], off offset:64
	v_mov_b32_e32 v4, v100
	v_mov_b32_e32 v5, v101
	v_lshlrev_b32_e32 v6, 16, v4
	v_mul_f32_e32 v8, 0x3d372713, v6
	v_mul_f32_e32 v8, v8, v6
	v_mov_b32_e32 v9, v6
	v_and_b32_e32 v7, 0xffff0000, v4
	v_fmac_f32_e32 v9, v8, v9
	v_mul_f32_e32 v8, 0x3f4c422a, v9
	v_mul_f32_e32 v9, 0x3d372713, v7
	v_mul_f32_e32 v9, v9, v7
	v_mov_b32_e32 v10, v7
	v_fmac_f32_e32 v10, v9, v10
	v_mul_f32_e32 v9, 0x3f4c422a, v10
	v_mul_f32_e32 v8, -2.0, v8
	v_mul_f32_e32 v9, -2.0, v9
	v_mul_f32_e32 v8, 0x3fb8aa3b, v8
	v_mul_f32_e32 v9, 0x3fb8aa3b, v9
	v_exp_f32_e32 v8, v8
	v_exp_f32_e32 v9, v9
	v_lshlrev_b32_e32 v4, 16, v5
	v_and_b32_e32 v5, 0xffff0000, v5
	v_add_f32_e32 v8, 1.0, v8
	v_add_f32_e32 v9, 1.0, v9
	v_rcp_f32_e32 v8, v8
	v_rcp_f32_e32 v9, v9
	s_nop 0
	v_pk_mul_f32 v[6:7], v[8:9], v[6:7]
	s_nop 0
	v_pk_mul_f32 v[0:1], v[0:1], v[6:7]
	v_mov_b32_e32 v6, v4
	v_cvt_pk_bf16_f32 v0, v0, v1
	v_mul_f32_e32 v1, 0x3d372713, v4
	v_mul_f32_e32 v1, v1, v4
	v_fmac_f32_e32 v6, v1, v6
	v_mul_f32_e32 v1, 0x3f4c422a, v6
	v_mul_f32_e32 v1, -2.0, v1
	v_mul_f32_e32 v1, 0x3fb8aa3b, v1
	v_exp_f32_e32 v1, v1
	v_mov_b32_e32 v7, v5
	v_add_f32_e32 v1, 1.0, v1
	v_rcp_f32_e32 v6, v1
	v_mul_f32_e32 v1, 0x3d372713, v5
	v_mul_f32_e32 v1, v1, v5
	v_fmac_f32_e32 v7, v1, v7
	v_mul_f32_e32 v1, 0x3f4c422a, v7
	v_mul_f32_e32 v1, -2.0, v1
	v_mul_f32_e32 v1, 0x3fb8aa3b, v1
	v_exp_f32_e32 v1, v1
	s_nop 0
	v_add_f32_e32 v1, 1.0, v1
	v_rcp_f32_e32 v7, v1
	s_nop 0
	v_pk_mul_f32 v[4:5], v[6:7], v[4:5]
	s_nop 0
	v_pk_mul_f32 v[2:3], v[2:3], v[4:5]
	s_nop 0
	v_cvt_pk_bf16_f32 v1, v2, v3
	global_store_dwordx2 v[12:13], v[0:1], off offset:96
	s_barrier
	s_andn2_b64 exec, exec, s[36:37]
	s_cbranch_execnz .LBB0_548

; __device__ __forceinline__ bf16_t f2bf(float f) { unsigned u = __float_as_uint(f); u += 0x7fffu + ((u >> 16) & 1u); return (bf16_t)(u >> 16); }
; __device__ __forceinline__ void mixB1_item(const Params& P, int layer, int idx, const bf16_t* z, float* hsl, float* Pc, float* carryP, float* carryH, char* lds) {
;     ...
;   {
;     const int t = tid >> 2, q = tid & 3;
;     float accv[16];
; #pragma unroll
;     for (int i = 0; i < 16; ++i) accv[i] = P.conv_b[layer * 256 + g * 64 + q * 16 + i];
; #pragma unroll
;     for (int k = 0; k < 4; ++k) {
;       const int pos = c * 64 + t - 3 + k;
;       if (pos >= 0) {
;         const bf16_t* zr = z + (tokb + pos) * LDZ + ZC_BX + g * 64 + q * 16;
;         float v[16]; unpack8(*(const u32x4*)zr, v); unpack8(*(const u32x4*)(zr + 8), v + 8);
;         const float* cw = P.conv_w + (size_t)(layer * 4 + k) * 256 + g * 64 + q * 16;
; #pragma unroll
;         for (int i = 0; i < 16; ++i) accv[i] += v[i] * cw[i];
;       }
;     }
; #pragma unroll
;     for (int i = 0; i < 16; ++i) { xcf[t * 65 + q * 16 + i] = accv[i]; xcb[t * 72 + q * 16 + i] = f2bf(accv[i]); }
;   }
.LBB0_562:
	s_or_b64 exec, exec, s[0:1]
	v_or3_b32 v17, v24, v37, v32
	v_mov_b64_e32 v[20:21], s[84:85]
	v_mad_u64_u32 v[20:21], s[0:1], v17, s39, v[20:21]
	v_mad_i32_i24 v21, v33, s39, v21
	v_mov_b32_e32 v19, v177
	v_lshl_add_u64 v[18:19], v[20:21], 0, v[18:19]
	v_mov_b32_e32 v17, v177
	v_lshl_add_u64 v[18:19], v[18:19], 0, v[16:17]
	v_mul_u32_u24_e32 v17, 0x104, v24
	global_load_dwordx4 v[20:23], v[18:19], off offset:1040
	global_load_dwordx4 v[44:47], v[18:19], off offset:1024
	v_add3_u32 v56, v60, v17, v176
	v_mul_u32_u24_e32 v17, 0x90, v24
	v_add3_u32 v41, v60, v17, v16
	global_load_dwordx4 v[16:19], v[28:29], off offset:3120
	global_load_dwordx4 v[24:27], v[28:29], off offset:3104
	global_load_dwordx4 v[48:51], v[28:29], off offset:3088
	global_load_dwordx4 v[52:55], v[28:29], off offset:3072
	v_add_u32_e32 v57, 0x2400, v56
	s_mov_b32 s0, 0x7060302
	v_and_b32_e32 v40, 0xff, v43
	v_lshrrev_b32_e32 v39, 6, v40
	v_and_b32_e32 v31, 15, v43
	v_lshl_or_b32 v176, v30, 13, s17
	v_mov_b32_e32 v69, v177
	v_and_b32_e32 v38, 63, v43
	v_readlane_b32 s64, v252, 2
	v_readlane_b32 s65, v252, 3
	v_readlane_b32 s66, v252, 4
	v_readlane_b32 s67, v252, 5
	v_readlane_b32 s68, v252, 6
	v_readlane_b32 s69, v252, 7
	v_readlane_b32 s70, v252, 8
	v_readlane_b32 s71, v252, 9
	v_readlane_b32 s72, v252, 10
	v_readlane_b32 s73, v252, 11
	v_readlane_b32 s74, v252, 12
	v_readlane_b32 s75, v252, 13
	v_readlane_b32 s60, v252, 18
	v_readlane_b32 s78, v252, 16
	v_readlane_b32 s79, v252, 17
	v_readlane_b32 s62, v252, 20
	v_readlane_b32 s63, v252, 21
	v_readlane_b32 s64, v252, 22
	v_readlane_b32 s65, v252, 23
	s_mov_b32 s30, 0xbeaaaaab
	s_mov_b32 s31, 0xf800000
	v_readlane_b32 s76, v252, 14
	v_readlane_b32 s77, v252, 15
	v_readlane_b32 s61, v252, 19
	v_readlane_b32 s66, v252, 24
	v_readlane_b32 s67, v252, 25
	v_readlane_b32 s68, v252, 26
	v_readlane_b32 s69, v252, 27
	v_readlane_b32 s70, v252, 28
	v_readlane_b32 s71, v252, 29
	v_readlane_b32 s72, v252, 30
	v_readlane_b32 s73, v252, 31
	v_readlane_b32 s74, v252, 32
	v_readlane_b32 s75, v252, 33
	s_waitcnt vmcnt(0)
	v_lshlrev_b32_e32 v28, 16, v44
	v_and_b32_e32 v29, 0xffff0000, v44
	v_add_u32_e32 v44, 0x2408, v56
	v_pk_fma_f32 v[12:13], v[52:53], v[28:29], v[12:13]
	v_lshlrev_b32_e32 v28, 16, v45
	v_and_b32_e32 v29, 0xffff0000, v45
	v_pk_fma_f32 v[14:15], v[54:55], v[28:29], v[14:15]
	ds_write2_b32 v44, v14, v15 offset1:1
	v_bfe_u32 v28, v15, 16, 1
	v_bfe_u32 v29, v14, 16, 1
	v_bfe_u32 v44, v13, 16, 1
	v_bfe_u32 v45, v12, 16, 1
	ds_write2_b32 v57, v12, v13 offset1:1
	v_add3_u32 v14, v14, v29, s38
	v_add3_u32 v15, v15, v28, s38
	v_add3_u32 v28, v12, v45, s38
	v_add3_u32 v29, v13, v44, s38
	v_lshlrev_b32_e32 v12, 16, v46
	v_and_b32_e32 v13, 0xffff0000, v46
	v_add_u32_e32 v44, 0x2410, v56
	v_pk_fma_f32 v[8:9], v[48:49], v[12:13], v[8:9]
	v_lshlrev_b32_e32 v12, 16, v47
	v_and_b32_e32 v13, 0xffff0000, v47
	ds_write2_b32 v44, v8, v9 offset1:1
	v_add_u32_e32 v44, 0x2418, v56
	v_pk_fma_f32 v[10:11], v[50:51], v[12:13], v[10:11]
	ds_write2_b32 v44, v10, v11 offset1:1
	v_bfe_u32 v12, v11, 16, 1
	v_bfe_u32 v13, v10, 16, 1
	v_bfe_u32 v44, v9, 16, 1
	v_bfe_u32 v45, v8, 16, 1
	v_add3_u32 v10, v10, v13, s38
	v_add3_u32 v11, v11, v12, s38
	v_add3_u32 v8, v8, v45, s38
	v_add3_u32 v12, v9, v44, s38
	v_perm_b32 v11, v11, v10, s0
	v_perm_b32 v9, v15, v14, s0
	v_perm_b32 v10, v12, v8, s0
	v_perm_b32 v8, v29, v28, s0
	ds_write_b128 v41, v[8:11]
	v_lshlrev_b32_e32 v8, 16, v20
	v_and_b32_e32 v9, 0xffff0000, v20
	v_add_u32_e32 v10, 0x2420, v56
	v_pk_fma_f32 v[4:5], v[24:25], v[8:9], v[4:5]
	v_lshlrev_b32_e32 v8, 16, v21
	v_and_b32_e32 v9, 0xffff0000, v21
	ds_write2_b32 v10, v4, v5 offset1:1
	v_add_u32_e32 v10, 0x2428, v56
	v_pk_fma_f32 v[6:7], v[26:27], v[8:9], v[6:7]
	ds_write2_b32 v10, v6, v7 offset1:1
	v_bfe_u32 v8, v7, 16, 1
	v_bfe_u32 v9, v6, 16, 1
	v_bfe_u32 v10, v5, 16, 1
	v_bfe_u32 v11, v4, 16, 1
	v_add3_u32 v6, v6, v9, s38
	v_add3_u32 v7, v7, v8, s38
	v_add3_u32 v8, v4, v11, s38
	v_add3_u32 v9, v5, v10, s38
	v_lshlrev_b32_e32 v4, 16, v22
	v_and_b32_e32 v5, 0xffff0000, v22
	v_add_u32_e32 v10, 0x2430, v56
	v_pk_fma_f32 v[0:1], v[16:17], v[4:5], v[0:1]
	v_lshlrev_b32_e32 v4, 16, v23
	v_and_b32_e32 v5, 0xffff0000, v23
	ds_write2_b32 v10, v0, v1 offset1:1
	v_add_u32_e32 v10, 0x2438, v56
	v_pk_fma_f32 v[2:3], v[18:19], v[4:5], v[2:3]
	ds_write2_b32 v10, v2, v3 offset1:1
	v_bfe_u32 v4, v3, 16, 1
	v_bfe_u32 v5, v2, 16, 1
	v_bfe_u32 v10, v1, 16, 1
	v_bfe_u32 v11, v0, 16, 1
	v_add3_u32 v2, v2, v5, s38
	v_add3_u32 v3, v3, v4, s38
	v_add3_u32 v0, v0, v11, s38
	v_add3_u32 v4, v1, v10, s38
	v_perm_b32 v3, v3, v2, s0
	v_perm_b32 v1, v7, v6, s0
	v_perm_b32 v2, v4, v0, s0
	v_perm_b32 v0, v9, v8, s0
	ds_write_b128 v41, v[0:3] offset:16
	v_lshlrev_b32_e32 v41, 4, v39
	v_or_b32_e32 v72, v41, v31
	v_lshl_add_u64 v[0:1], s[88:89], 0, v[176:177]
	v_lshl_add_u64 v[2:3], s[90:91], 0, v[176:177]
	v_mul_u32_u24_e32 v4, 0x90, v72
	v_and_b32_e32 v176, 48, v43
	v_add3_u32 v30, v60, v4, v176
	v_lshl_add_u64 v[28:29], v[0:1], 0, v[176:177]
	v_lshl_add_u64 v[62:63], v[2:3], 0, v[176:177]
	v_lshlrev_b32_e32 v176, 7, v31
	v_or_b32_e32 v68, 0x1000, v176
	v_lshl_add_u64 v[64:65], v[28:29], 0, v[176:177]
	v_lshl_add_u64 v[66:67], v[62:63], 0, v[176:177]
	v_lshl_add_u64 v[20:21], v[28:29], 0, v[68:69]
	v_lshl_add_u64 v[24:25], v[62:63], 0, v[68:69]
	s_waitcnt lgkmcnt(0)
	s_barrier
; __device__ __forceinline__ float sigm(float x) { return __builtin_amdgcn_rcpf(1.f + __expf(-x)); }
; __device__ __forceinline__ f32x4 mfma16(bf16x8 a, bf16x8 b, f32x4 c) { return __builtin_amdgcn_mfma_f32_16x16x32_bf16(a, b, c, 0, 0, 0); }
; __device__ __forceinline__ void mixB1_item(const Params& P, int layer, int idx, const bf16_t* z, float* hsl, float* Pc, float* carryP, float* carryH, char* lds) {
;     ...
;     const bf16_t* wa = (const bf16_t*)(P.ws + OFF_WAT) + (layer * 4 + g) * 4096;
;     const bf16_t* wx = (const bf16_t*)(P.ws + OFF_WXT) + (layer * 4 + g) * 4096;
;     f32x4 ar[4] = {}, ai[4] = {};
; #pragma unroll
;     for (int ks = 0; ks < 2; ++ks) {
;       const bf16x8 xf = *(const bf16x8*)(xcb + (16 * w + fr) * 72 + ks * 32 + 8 * fq);
; #pragma unroll
;       for (int jn = 0; jn < 4; ++jn) {
;         const bf16x8 fa = *(const bf16x8*)(wa + (jn * 16 + fr) * 64 + ks * 32 + 8 * fq);
;         const bf16x8 fx = *(const bf16x8*)(wx + (jn * 16 + fr) * 64 + ks * 32 + 8 * fq);
;         ar[jn] = mfma16(fa, xf, ar[jn]); ai[jn] = mfma16(fx, xf, ai[jn]);
;       }
;     }
;     const int t = 16 * w + fr;
; #pragma unroll
;     for (int jn = 0; jn < 4; ++jn)
; #pragma unroll
;       for (int e = 0; e < 4; ++e) {
;         const int j = jn * 16 + 4 * fq + e, ch = layer * 256 + g * 64 + j;
;         const float r = sigm(ar[jn][e] + P.lru_ba[ch]), ig = sigm(ai[jn][e] + P.lru_bx[ch]);
;         const float lam = P.lru_lam[ch];
;         const float xe = __expf(-lam);
;         float m8; asm volatile("v_mov_b32 %0, 0xc1000000" : "=v"(m8));
;         const float la = m8 * r * (xe * (1.f - xe * (0.5f - xe * (1.f / 3.f))));
;         const float av = __expf(la);
;         const float y2 = 2.f * la;
;         const float om = -y2 * (1.f + y2 * (0.5f + y2 * ((1.f / 6.f) + y2 * ((1.f / 24.f) + y2 * ((1.f / 120.f) + y2 * (1.f / 720.f))))));
;         const float bv = sqrtf(om) * (ig * xcf[t * 65 + j]);
;         aA[t * 65 + j] = av; bB[t * 65 + j] = bv;
	v_lshrrev_b32_e32 v73, 2, v179
	v_and_b32_e32 v73, 12, v73
	v_add_lshl_u32 v80, v73, v42, 2
	global_load_dwordx4 v[84:87], v80, s[78:79]
	global_load_dwordx4 v[88:91], v80, s[78:79] offset:64
	global_load_dwordx4 v[92:95], v80, s[78:79] offset:128
	global_load_dwordx4 v[96:99], v80, s[78:79] offset:192
	global_load_dwordx4 v[100:103], v80, s[62:63]
	global_load_dwordx4 v[104:107], v80, s[62:63] offset:64
	global_load_dwordx4 v[108:111], v80, s[62:63] offset:128
	global_load_dwordx4 v[112:115], v80, s[62:63] offset:192
	global_load_dwordx4 v[116:119], v80, s[64:65]
	global_load_dwordx4 v[120:123], v80, s[64:65] offset:64
	global_load_dwordx4 v[124:127], v80, s[64:65] offset:128
	global_load_dwordx4 v[128:131], v80, s[64:65] offset:192
	ds_read_b128 v[0:3], v30
	global_load_dwordx4 v[4:7], v[64:65], off
	global_load_dwordx4 v[8:11], v[66:67], off
	global_load_dwordx4 v[12:15], v[64:65], off offset:2048
	global_load_dwordx4 v[16:19], v[66:67], off offset:2048
	v_or_b32_e32 v176, 0x1800, v176
	global_load_dwordx4 v[20:23], v[20:21], off
	s_waitcnt vmcnt(4) lgkmcnt(0)
	v_mfma_f32_16x16x32_bf16 v[4:7], v[4:7], v[0:3], 0
	global_load_dwordx4 v[24:27], v[24:25], off
	ds_read_b128 v[56:59], v30 offset:64
	v_lshl_add_u64 v[70:71], v[28:29], 0, 64
	s_waitcnt vmcnt(1)
	v_mfma_f32_16x16x32_bf16 v[44:47], v[20:23], v[0:3], 0
	v_lshl_add_u64 v[20:21], v[28:29], 0, v[176:177]
	global_load_dwordx4 v[20:23], v[20:21], off
	v_lshrrev_b32_e32 v43, 2, v43
	s_waitcnt vmcnt(1)
	v_mfma_f32_16x16x32_bf16 v[48:51], v[24:27], v[0:3], 0
	v_lshl_add_u64 v[24:25], v[62:63], 0, v[176:177]
	global_load_dwordx4 v[24:27], v[24:25], off
	v_lshl_add_u64 v[62:63], v[62:63], 0, 64
	v_mfma_f32_16x16x32_bf16 v[8:11], v[8:11], v[0:3], 0
	v_and_b32_e32 v43, 12, v43
	v_mfma_f32_16x16x32_bf16 v[12:15], v[12:15], v[0:3], 0
	v_mfma_f32_16x16x32_bf16 v[16:19], v[16:19], v[0:3], 0
	s_waitcnt vmcnt(1)
	v_mfma_f32_16x16x32_bf16 v[52:55], v[20:23], v[0:3], 0
	s_waitcnt vmcnt(0)
	v_mfma_f32_16x16x32_bf16 v[0:3], v[24:27], v[0:3], 0
	global_load_dwordx4 v[20:23], v[64:65], off offset:64
	global_load_dwordx4 v[24:27], v[66:67], off offset:64
	s_waitcnt vmcnt(1) lgkmcnt(0)
	v_mfma_f32_16x16x32_bf16 v[28:31], v[20:23], v[56:59], v[4:7]
	s_waitcnt vmcnt(0)
	v_mfma_f32_16x16x32_bf16 v[24:27], v[24:27], v[56:59], v[8:11]
	s_nop 0
	global_load_dwordx4 v[4:7], v[64:65], off offset:2112
	s_nop 0
	global_load_dwordx4 v[8:11], v[66:67], off offset:2112
	s_waitcnt vmcnt(1)
	v_mfma_f32_16x16x32_bf16 v[20:23], v[4:7], v[56:59], v[12:15]
	v_lshl_add_u64 v[4:5], v[70:71], 0, v[68:69]
	global_load_dwordx4 v[4:7], v[4:5], off
	s_waitcnt vmcnt(1)
	v_mfma_f32_16x16x32_bf16 v[16:19], v[8:11], v[56:59], v[16:19]
	v_lshl_add_u64 v[8:9], v[62:63], 0, v[68:69]
	global_load_dwordx4 v[8:11], v[8:9], off
	s_waitcnt vmcnt(1)
	v_mfma_f32_16x16x32_bf16 v[12:15], v[4:7], v[56:59], v[44:47]
	v_lshl_add_u64 v[4:5], v[70:71], 0, v[176:177]
	s_nop 1
	v_lshl_add_u64 v[44:45], v[62:63], 0, v[176:177]
	global_load_dwordx4 v[4:7], v[4:5], off
	s_waitcnt vmcnt(1)
	v_mfma_f32_16x16x32_bf16 v[8:11], v[8:11], v[56:59], v[48:51]
	global_load_dwordx4 v[44:47], v[44:45], off
	s_waitcnt vmcnt(0)
	v_mfma_f32_16x16x32_bf16 v[0:3], v[44:47], v[56:59], v[0:3]
	v_or_b32_e32 v44, v43, v42
	v_lshlrev_b32_e32 v44, 2, v44
	v_mov_b32_e32 v45, v84
	v_mov_b32_e32 v46, v100
	v_add_lshl_u32 v42, v43, v42, 2
	v_mfma_f32_16x16x32_bf16 v[4:7], v[4:7], v[56:59], v[52:55]
	s_waitcnt vmcnt(1)
	v_add_f32_e32 v28, v28, v45
	s_waitcnt vmcnt(0)
	v_add_f32_e32 v24, v24, v46
	v_mul_f32_e32 v24, 0xbfb8aa3b, v24
	v_exp_f32_e32 v24, v24
	v_mul_f32_e32 v28, 0xbfb8aa3b, v28
	v_exp_f32_e32 v45, v28
	v_mov_b32_e32 v28, 1.0
	v_add_f32_e32 v24, 1.0, v24
	v_rcp_f32_e32 v46, v24
	v_mov_b32_e32 v24, v116
	v_add_f32_e32 v45, 1.0, v45
	v_rcp_f32_e32 v45, v45
	v_mov_b32 v44, 0xc1000000
	s_waitcnt vmcnt(0)
	v_mul_f32_e32 v24, 0xbfb8aa3b, v24
	v_exp_f32_e32 v24, v24
	v_mul_f32_e32 v44, v44, v45
	v_fma_f32 v45, v24, s30, 0.5
	v_fma_f32 v45, -v24, v45, 1.0
	v_mul_f32_e32 v24, v24, v45
	v_mul_f32_e32 v24, v44, v24
	v_mul_f32_e32 v44, 0x3fb8aa3b, v24
	v_add_f32_e32 v24, v24, v24
	v_fmamk_f32 v45, v24, 0x3ab60b61, v213
	v_fmaak_f32 v45, v24, v45, 0x3d2aaaab
	v_fmaak_f32 v45, v24, v45, 0x3e2aaaab
	v_fma_f32 v45, v24, v45, 0.5
	v_fma_f32 v45, v24, v45, 1.0
	v_mul_f32_e64 v24, v45, -v24
	v_cmp_gt_f32_e32 vcc, s31, v24
	v_mul_f32_e32 v45, 0x4f800000, v24
	v_exp_f32_e32 v44, v44
	v_cndmask_b32_e32 v24, v24, v45, vcc
	v_sqrt_f32_e32 v45, v24
	s_nop 0
	v_add_u32_e32 v47, -1, v45
	v_fma_f32 v48, -v47, v45, v24
	v_cmp_ge_f32_e64 s[0:1], 0, v48
	v_add_u32_e32 v48, 1, v45
	s_nop 0
	v_cndmask_b32_e64 v47, v45, v47, s[0:1]
	v_fma_f32 v45, -v48, v45, v24
	v_cmp_lt_f32_e64 s[0:1], 0, v45
	s_nop 1
	v_cndmask_b32_e64 v45, v47, v48, s[0:1]
	v_mul_f32_e32 v47, 0x37800000, v45
	v_cndmask_b32_e32 v45, v45, v47, vcc
	v_cmp_class_f32_e32 vcc, v24, v214
	s_nop 1
	v_cndmask_b32_e32 v45, v45, v24, vcc
	v_mad_u32_u24 v24, v72, s33, v43
	v_mov_b32_e32 v43, v85
	v_lshl_add_u32 v24, v24, 2, v60
	ds_read_b32 v47, v24 offset:9216
	s_waitcnt lgkmcnt(0)
	v_mul_f32_e32 v46, v47, v46
	v_mul_f32_e32 v45, v46, v45
	ds_write2st64_b32 v24, v44, v45 offset0:101 offset1:166
	s_waitcnt vmcnt(0)
	v_add_f32_e32 v29, v29, v43
	v_mov_b32_e32 v43, v101
	v_mul_f32_e32 v29, 0xbfb8aa3b, v29
	v_exp_f32_e32 v29, v29
	s_waitcnt vmcnt(0)
	v_add_f32_e32 v25, v25, v43
	v_mov_b32_e32 v43, v117
	v_add_f32_e32 v29, 1.0, v29
	v_rcp_f32_e32 v29, v29
	v_mov_b32 v44, 0xc1000000
	v_mul_f32_e32 v25, 0xbfb8aa3b, v25
	v_exp_f32_e32 v25, v25
	v_mul_f32_e32 v29, v44, v29
	v_add_f32_e32 v25, 1.0, v25
	v_rcp_f32_e32 v25, v25
	s_waitcnt vmcnt(0)
; __device__ __forceinline__ float sigm(float x) { return __builtin_amdgcn_rcpf(1.f + __expf(-x)); }
; __device__ __forceinline__ void mixB1_item(const Params& P, int layer, int idx, const bf16_t* z, float* hsl, float* Pc, float* carryP, float* carryH, char* lds) {
;     ...
; #pragma unroll
;     for (int jn = 0; jn < 4; ++jn)
; #pragma unroll
;       for (int e = 0; e < 4; ++e) {
;         const int j = jn * 16 + 4 * fq + e, ch = layer * 256 + g * 64 + j;
;         const float r = sigm(ar[jn][e] + P.lru_ba[ch]), ig = sigm(ai[jn][e] + P.lru_bx[ch]);
;         const float lam = P.lru_lam[ch];
;         const float xe = __expf(-lam);
;         float m8; asm volatile("v_mov_b32 %0, 0xc1000000" : "=v"(m8));
;         const float la = m8 * r * (xe * (1.f - xe * (0.5f - xe * (1.f / 3.f))));
;         const float av = __expf(la);
;         const float y2 = 2.f * la;
;         const float om = -y2 * (1.f + y2 * (0.5f + y2 * ((1.f / 6.f) + y2 * ((1.f / 24.f) + y2 * ((1.f / 120.f) + y2 * (1.f / 720.f))))));
;         const float bv = sqrtf(om) * (ig * xcf[t * 65 + j]);
;         aA[t * 65 + j] = av; bB[t * 65 + j] = bv;
	v_mul_f32_e32 v43, 0xbfb8aa3b, v43
	v_exp_f32_e32 v43, v43
	s_nop 0
	v_fma_f32 v44, v43, s30, 0.5
	v_fma_f32 v44, -v43, v44, 1.0
	v_mul_f32_e32 v43, v43, v44
	v_mul_f32_e32 v29, v29, v43
	v_mul_f32_e32 v43, 0x3fb8aa3b, v29
	v_add_f32_e32 v29, v29, v29
	v_fmamk_f32 v44, v29, 0x3ab60b61, v213
	v_fmaak_f32 v44, v29, v44, 0x3d2aaaab
	v_fmaak_f32 v44, v29, v44, 0x3e2aaaab
	v_fma_f32 v44, v29, v44, 0.5
	v_fma_f32 v44, v29, v44, 1.0
	v_mul_f32_e64 v29, v44, -v29
	v_cmp_gt_f32_e32 vcc, s31, v29
	v_mul_f32_e32 v44, 0x4f800000, v29
	v_exp_f32_e32 v43, v43
	v_cndmask_b32_e32 v29, v29, v44, vcc
	v_sqrt_f32_e32 v44, v29
	s_nop 0
	v_add_u32_e32 v45, -1, v44
	v_fma_f32 v46, -v45, v44, v29
	v_cmp_ge_f32_e64 s[0:1], 0, v46
	v_add_u32_e32 v46, 1, v44
	s_nop 0
	v_cndmask_b32_e64 v45, v44, v45, s[0:1]
	v_fma_f32 v44, -v46, v44, v29
	v_cmp_lt_f32_e64 s[0:1], 0, v44
	s_nop 1
	v_cndmask_b32_e64 v44, v45, v46, s[0:1]
	v_mul_f32_e32 v45, 0x37800000, v44
	v_cndmask_b32_e32 v44, v44, v45, vcc
	v_cmp_class_f32_e32 vcc, v29, v214
	s_nop 1
	v_cndmask_b32_e32 v29, v44, v29, vcc
	ds_read_b32 v44, v24 offset:9220
	s_waitcnt lgkmcnt(0)
	v_mul_f32_e32 v25, v44, v25
	v_mul_f32_e32 v25, v25, v29
	v_add_u32_e32 v29, 4, v24
	ds_write2st64_b32 v29, v43, v25 offset0:101 offset1:166
	v_mov_b32_e32 v25, v86
	v_mov_b32_e32 v29, v102
	s_waitcnt vmcnt(1)
	v_add_f32_e32 v25, v30, v25
	s_waitcnt vmcnt(0)
	v_add_f32_e32 v26, v26, v29
	v_mov_b32_e32 v29, v118
	v_mul_f32_e32 v25, 0xbfb8aa3b, v25
	v_exp_f32_e32 v25, v25
	v_mov_b32 v30, 0xc1000000
	v_mul_f32_e32 v26, 0xbfb8aa3b, v26
	v_exp_f32_e32 v26, v26
	v_add_f32_e32 v25, 1.0, v25
	v_rcp_f32_e32 v25, v25
	v_add_f32_e32 v26, 1.0, v26
	v_rcp_f32_e32 v26, v26
	v_mul_f32_e32 v25, v30, v25
	s_waitcnt vmcnt(0)
	v_mul_f32_e32 v29, 0xbfb8aa3b, v29
	v_exp_f32_e32 v29, v29
	s_nop 0
	v_fma_f32 v30, v29, s30, 0.5
	v_fma_f32 v30, -v29, v30, 1.0
	v_mul_f32_e32 v29, v29, v30
	v_mul_f32_e32 v25, v25, v29
	v_mul_f32_e32 v29, 0x3fb8aa3b, v25
	v_add_f32_e32 v25, v25, v25
	v_fmamk_f32 v30, v25, 0x3ab60b61, v213
	v_fmaak_f32 v30, v25, v30, 0x3d2aaaab
	v_fmaak_f32 v30, v25, v30, 0x3e2aaaab
	v_fma_f32 v30, v25, v30, 0.5
	v_fma_f32 v30, v25, v30, 1.0
	v_mul_f32_e64 v25, v30, -v25
	v_cmp_gt_f32_e32 vcc, s31, v25
	v_mul_f32_e32 v30, 0x4f800000, v25
	v_exp_f32_e32 v29, v29
	v_cndmask_b32_e32 v25, v25, v30, vcc
	v_sqrt_f32_e32 v30, v25
	s_nop 0
	v_add_u32_e32 v43, -1, v30
	v_fma_f32 v44, -v43, v30, v25
	v_cmp_ge_f32_e64 s[0:1], 0, v44
	v_add_u32_e32 v44, 1, v30
	s_nop 0
	v_cndmask_b32_e64 v43, v30, v43, s[0:1]
	v_fma_f32 v30, -v44, v30, v25
	v_cmp_lt_f32_e64 s[0:1], 0, v30
	s_nop 1
	v_cndmask_b32_e64 v30, v43, v44, s[0:1]
	v_mul_f32_e32 v43, 0x37800000, v30
	v_cndmask_b32_e32 v30, v30, v43, vcc
	v_cmp_class_f32_e32 vcc, v25, v214
	s_nop 1
	v_cndmask_b32_e32 v25, v30, v25, vcc
	ds_read_b32 v30, v24 offset:9224
	s_waitcnt lgkmcnt(0)
	v_mul_f32_e32 v26, v30, v26
	v_mul_f32_e32 v25, v26, v25
	v_add_u32_e32 v26, 8, v24
	ds_write2st64_b32 v26, v29, v25 offset0:101 offset1:166
	v_mov_b32_e32 v25, v87
	v_mov_b32_e32 v26, v103
	s_waitcnt vmcnt(1)
	v_add_f32_e32 v25, v31, v25
	s_waitcnt vmcnt(0)
	v_add_f32_e32 v26, v27, v26
	v_mov_b32_e32 v27, v119
	v_mul_f32_e32 v25, 0xbfb8aa3b, v25
	v_exp_f32_e32 v25, v25
	v_mov_b32 v29, 0xc1000000
	v_mul_f32_e32 v26, 0xbfb8aa3b, v26
	v_exp_f32_e32 v26, v26
	v_add_f32_e32 v25, 1.0, v25
	v_rcp_f32_e32 v25, v25
	v_add_f32_e32 v26, 1.0, v26
	v_rcp_f32_e32 v26, v26
	v_mul_f32_e32 v25, v29, v25
	s_waitcnt vmcnt(0)
	v_mul_f32_e32 v27, 0xbfb8aa3b, v27
	v_exp_f32_e32 v27, v27
	s_nop 0
	v_fma_f32 v29, v27, s30, 0.5
	v_fma_f32 v29, -v27, v29, 1.0
	v_mul_f32_e32 v27, v27, v29
	v_mul_f32_e32 v25, v25, v27
	v_mul_f32_e32 v27, 0x3fb8aa3b, v25
	v_add_f32_e32 v25, v25, v25
	v_fmamk_f32 v29, v25, 0x3ab60b61, v213
	v_fmaak_f32 v29, v25, v29, 0x3d2aaaab
	v_fmaak_f32 v29, v25, v29, 0x3e2aaaab
	v_fma_f32 v29, v25, v29, 0.5
	v_fma_f32 v29, v25, v29, 1.0
	v_mul_f32_e64 v25, v29, -v25
	v_cmp_gt_f32_e32 vcc, s31, v25
	v_mul_f32_e32 v29, 0x4f800000, v25
	v_exp_f32_e32 v27, v27
	v_cndmask_b32_e32 v25, v25, v29, vcc
	v_sqrt_f32_e32 v29, v25
	s_nop 0
	v_add_u32_e32 v30, -1, v29
	v_fma_f32 v31, -v30, v29, v25
	v_cmp_ge_f32_e64 s[0:1], 0, v31
	v_add_u32_e32 v31, 1, v29
	s_nop 0
	v_cndmask_b32_e64 v30, v29, v30, s[0:1]
	v_fma_f32 v29, -v31, v29, v25
	v_cmp_lt_f32_e64 s[0:1], 0, v29
	s_nop 1
	v_cndmask_b32_e64 v29, v30, v31, s[0:1]
	v_mul_f32_e32 v30, 0x37800000, v29
	v_cndmask_b32_e32 v29, v29, v30, vcc
	v_cmp_class_f32_e32 vcc, v25, v214
	s_nop 1
	v_cndmask_b32_e32 v25, v29, v25, vcc
	ds_read_b32 v29, v24 offset:9228
	s_waitcnt lgkmcnt(0)
	v_mul_f32_e32 v26, v29, v26
	v_mul_f32_e32 v25, v26, v25
	v_add_u32_e32 v26, 12, v24
	ds_write2st64_b32 v26, v27, v25 offset0:101 offset1:166
	v_mov_b32_e32 v25, v88
	s_waitcnt vmcnt(0)
	v_add_f32_e32 v20, v20, v25
	v_mov_b32_e32 v25, v104
	v_mul_f32_e32 v20, 0xbfb8aa3b, v20
	v_exp_f32_e32 v20, v20
	s_waitcnt vmcnt(0)
	v_add_f32_e32 v16, v16, v25
	v_mov_b32_e32 v25, v120
	v_add_f32_e32 v20, 1.0, v20
	v_rcp_f32_e32 v20, v20
	v_mov_b32 v26, 0xc1000000
	v_mul_f32_e32 v16, 0xbfb8aa3b, v16
	v_exp_f32_e32 v16, v16
	v_mul_f32_e32 v20, v26, v20
	v_add_f32_e32 v16, 1.0, v16
	v_rcp_f32_e32 v16, v16
	s_waitcnt vmcnt(0)
; __device__ __forceinline__ float sigm(float x) { return __builtin_amdgcn_rcpf(1.f + __expf(-x)); }
; __device__ __forceinline__ void mixB1_item(const Params& P, int layer, int idx, const bf16_t* z, float* hsl, float* Pc, float* carryP, float* carryH, char* lds) {
;     ...
; #pragma unroll
;     for (int jn = 0; jn < 4; ++jn)
; #pragma unroll
;       for (int e = 0; e < 4; ++e) {
;         const int j = jn * 16 + 4 * fq + e, ch = layer * 256 + g * 64 + j;
;         const float r = sigm(ar[jn][e] + P.lru_ba[ch]), ig = sigm(ai[jn][e] + P.lru_bx[ch]);
;         const float lam = P.lru_lam[ch];
;         const float xe = __expf(-lam);
;         float m8; asm volatile("v_mov_b32 %0, 0xc1000000" : "=v"(m8));
;         const float la = m8 * r * (xe * (1.f - xe * (0.5f - xe * (1.f / 3.f))));
;         const float av = __expf(la);
;         const float y2 = 2.f * la;
;         const float om = -y2 * (1.f + y2 * (0.5f + y2 * ((1.f / 6.f) + y2 * ((1.f / 24.f) + y2 * ((1.f / 120.f) + y2 * (1.f / 720.f))))));
;         const float bv = sqrtf(om) * (ig * xcf[t * 65 + j]);
;         aA[t * 65 + j] = av; bB[t * 65 + j] = bv;
	v_mul_f32_e32 v25, 0xbfb8aa3b, v25
	v_exp_f32_e32 v25, v25
	s_nop 0
	v_fma_f32 v26, v25, s30, 0.5
	v_fma_f32 v26, -v25, v26, 1.0
	v_mul_f32_e32 v25, v25, v26
	v_mul_f32_e32 v20, v20, v25
	v_mul_f32_e32 v25, 0x3fb8aa3b, v20
	v_add_f32_e32 v20, v20, v20
	v_fmamk_f32 v26, v20, 0x3ab60b61, v213
	v_fmaak_f32 v26, v20, v26, 0x3d2aaaab
	v_fmaak_f32 v26, v20, v26, 0x3e2aaaab
	v_fma_f32 v26, v20, v26, 0.5
	v_fma_f32 v26, v20, v26, 1.0
	v_mul_f32_e64 v20, v26, -v20
	v_cmp_gt_f32_e32 vcc, s31, v20
	v_mul_f32_e32 v26, 0x4f800000, v20
	v_exp_f32_e32 v25, v25
	v_cndmask_b32_e32 v20, v20, v26, vcc
	v_sqrt_f32_e32 v26, v20
	s_nop 0
	v_add_u32_e32 v27, -1, v26
	v_fma_f32 v29, -v27, v26, v20
	v_cmp_ge_f32_e64 s[0:1], 0, v29
	v_add_u32_e32 v29, 1, v26
	s_nop 0
	v_cndmask_b32_e64 v27, v26, v27, s[0:1]
	v_fma_f32 v26, -v29, v26, v20
	v_cmp_lt_f32_e64 s[0:1], 0, v26
	s_nop 1
	v_cndmask_b32_e64 v26, v27, v29, s[0:1]
	v_mul_f32_e32 v27, 0x37800000, v26
	v_cndmask_b32_e32 v26, v26, v27, vcc
	v_cmp_class_f32_e32 vcc, v20, v214
	s_nop 1
	v_cndmask_b32_e32 v20, v26, v20, vcc
	ds_read_b32 v26, v24 offset:9280
	s_waitcnt lgkmcnt(0)
	v_mul_f32_e32 v16, v26, v16
	v_mul_f32_e32 v16, v16, v20
	v_add_u32_e32 v20, 64, v24
	ds_write2st64_b32 v20, v25, v16 offset0:101 offset1:166
	v_mov_b32_e32 v16, v89
	v_mov_b32_e32 v20, v105
	s_waitcnt vmcnt(1)
	v_add_f32_e32 v16, v21, v16
	s_waitcnt vmcnt(0)
	v_add_f32_e32 v17, v17, v20
	v_mov_b32_e32 v20, v121
	v_mul_f32_e32 v16, 0xbfb8aa3b, v16
	v_exp_f32_e32 v16, v16
	v_mov_b32 v21, 0xc1000000
	v_mul_f32_e32 v17, 0xbfb8aa3b, v17
	v_exp_f32_e32 v17, v17
	v_add_f32_e32 v16, 1.0, v16
	v_rcp_f32_e32 v16, v16
	v_add_f32_e32 v17, 1.0, v17
	v_rcp_f32_e32 v17, v17
	v_mul_f32_e32 v16, v21, v16
	s_waitcnt vmcnt(0)
	v_mul_f32_e32 v20, 0xbfb8aa3b, v20
	v_exp_f32_e32 v20, v20
	s_nop 0
	v_fma_f32 v21, v20, s30, 0.5
	v_fma_f32 v21, -v20, v21, 1.0
	v_mul_f32_e32 v20, v20, v21
	v_mul_f32_e32 v16, v16, v20
	v_mul_f32_e32 v20, 0x3fb8aa3b, v16
	v_add_f32_e32 v16, v16, v16
	v_fmamk_f32 v21, v16, 0x3ab60b61, v213
	v_fmaak_f32 v21, v16, v21, 0x3d2aaaab
	v_fmaak_f32 v21, v16, v21, 0x3e2aaaab
	v_fma_f32 v21, v16, v21, 0.5
	v_fma_f32 v21, v16, v21, 1.0
	v_mul_f32_e64 v16, v21, -v16
	v_cmp_gt_f32_e32 vcc, s31, v16
	v_mul_f32_e32 v21, 0x4f800000, v16
	v_exp_f32_e32 v20, v20
	v_cndmask_b32_e32 v16, v16, v21, vcc
	v_sqrt_f32_e32 v21, v16
	s_nop 0
	v_add_u32_e32 v25, -1, v21
	v_fma_f32 v26, -v25, v21, v16
	v_cmp_ge_f32_e64 s[0:1], 0, v26
	v_add_u32_e32 v26, 1, v21
	s_nop 0
	v_cndmask_b32_e64 v25, v21, v25, s[0:1]
	v_fma_f32 v21, -v26, v21, v16
	v_cmp_lt_f32_e64 s[0:1], 0, v21
	s_nop 1
	v_cndmask_b32_e64 v21, v25, v26, s[0:1]
	v_mul_f32_e32 v25, 0x37800000, v21
	v_cndmask_b32_e32 v21, v21, v25, vcc
	v_cmp_class_f32_e32 vcc, v16, v214
	s_nop 1
	v_cndmask_b32_e32 v16, v21, v16, vcc
	ds_read_b32 v21, v24 offset:9284
	s_waitcnt lgkmcnt(0)
	v_mul_f32_e32 v17, v21, v17
	v_mul_f32_e32 v16, v17, v16
	v_add_u32_e32 v17, 0x44, v24
	ds_write2st64_b32 v17, v20, v16 offset0:101 offset1:166
	v_mov_b32_e32 v16, v90
	v_mov_b32_e32 v17, v106
	s_waitcnt vmcnt(1)
	v_add_f32_e32 v16, v22, v16
	s_waitcnt vmcnt(0)
	v_add_f32_e32 v17, v18, v17
	v_mov_b32_e32 v18, v122
	v_mul_f32_e32 v16, 0xbfb8aa3b, v16
	v_exp_f32_e32 v16, v16
	v_mov_b32 v20, 0xc1000000
	v_mul_f32_e32 v17, 0xbfb8aa3b, v17
	v_exp_f32_e32 v17, v17
	v_add_f32_e32 v16, 1.0, v16
	v_rcp_f32_e32 v16, v16
	v_add_f32_e32 v17, 1.0, v17
	v_rcp_f32_e32 v17, v17
	v_mul_f32_e32 v16, v20, v16
	s_waitcnt vmcnt(0)
	v_mul_f32_e32 v18, 0xbfb8aa3b, v18
	v_exp_f32_e32 v18, v18
	s_nop 0
	v_fma_f32 v20, v18, s30, 0.5
	v_fma_f32 v20, -v18, v20, 1.0
	v_mul_f32_e32 v18, v18, v20
	v_mul_f32_e32 v16, v16, v18
	v_mul_f32_e32 v18, 0x3fb8aa3b, v16
	v_add_f32_e32 v16, v16, v16
	v_fmamk_f32 v20, v16, 0x3ab60b61, v213
	v_fmaak_f32 v20, v16, v20, 0x3d2aaaab
	v_fmaak_f32 v20, v16, v20, 0x3e2aaaab
	v_fma_f32 v20, v16, v20, 0.5
	v_fma_f32 v20, v16, v20, 1.0
	v_mul_f32_e64 v16, v20, -v16
	v_cmp_gt_f32_e32 vcc, s31, v16
	v_mul_f32_e32 v20, 0x4f800000, v16
	v_exp_f32_e32 v18, v18
	v_cndmask_b32_e32 v16, v16, v20, vcc
	v_sqrt_f32_e32 v20, v16
	s_nop 0
	v_add_u32_e32 v21, -1, v20
	v_fma_f32 v22, -v21, v20, v16
	v_cmp_ge_f32_e64 s[0:1], 0, v22
	v_add_u32_e32 v22, 1, v20
	s_nop 0
	v_cndmask_b32_e64 v21, v20, v21, s[0:1]
	v_fma_f32 v20, -v22, v20, v16
	v_cmp_lt_f32_e64 s[0:1], 0, v20
	s_nop 1
	v_cndmask_b32_e64 v20, v21, v22, s[0:1]
	v_mul_f32_e32 v21, 0x37800000, v20
	v_cndmask_b32_e32 v20, v20, v21, vcc
	v_cmp_class_f32_e32 vcc, v16, v214
	s_nop 1
	v_cndmask_b32_e32 v16, v20, v16, vcc
	ds_read_b32 v20, v24 offset:9288
	s_waitcnt lgkmcnt(0)
	v_mul_f32_e32 v17, v20, v17
	v_mul_f32_e32 v16, v17, v16
	v_add_u32_e32 v17, 0x48, v24
	ds_write2st64_b32 v17, v18, v16 offset0:101 offset1:166
	v_mov_b32_e32 v16, v91
	v_mov_b32_e32 v17, v107
	v_mov_b32_e32 v18, v123
	s_waitcnt vmcnt(2)
	v_add_f32_e32 v16, v23, v16
	v_mul_f32_e32 v16, 0xbfb8aa3b, v16
	v_exp_f32_e32 v16, v16
	s_waitcnt vmcnt(0)
	v_mul_f32_e32 v18, 0xbfb8aa3b, v18
	v_exp_f32_e32 v18, v18
	v_add_f32_e32 v17, v19, v17
	v_add_f32_e32 v16, 1.0, v16
	v_rcp_f32_e32 v16, v16
	v_mov_b32 v19, 0xc1000000
	v_mul_f32_e32 v17, 0xbfb8aa3b, v17
	v_exp_f32_e32 v17, v17
	v_mul_f32_e32 v16, v19, v16
	v_fma_f32 v19, v18, s30, 0.5
	v_fma_f32 v19, -v18, v19, 1.0
	v_mul_f32_e32 v18, v18, v19
	v_mul_f32_e32 v16, v16, v18
	v_mul_f32_e32 v18, 0x3fb8aa3b, v16
	v_add_f32_e32 v16, v16, v16
	v_fmamk_f32 v19, v16, 0x3ab60b61, v213
	v_fmaak_f32 v19, v16, v19, 0x3d2aaaab
	v_fmaak_f32 v19, v16, v19, 0x3e2aaaab
	v_fma_f32 v19, v16, v19, 0.5
	v_fma_f32 v19, v16, v19, 1.0
	v_mul_f32_e64 v16, v19, -v16
	v_cmp_gt_f32_e32 vcc, s31, v16
	v_mul_f32_e32 v19, 0x4f800000, v16
	v_add_f32_e32 v17, 1.0, v17
	v_cndmask_b32_e32 v16, v16, v19, vcc
	v_sqrt_f32_e32 v19, v16
	v_rcp_f32_e32 v17, v17
	v_exp_f32_e32 v18, v18
	v_add_u32_e32 v20, -1, v19
	v_fma_f32 v21, -v20, v19, v16
	v_cmp_ge_f32_e64 s[0:1], 0, v21
	v_add_u32_e32 v21, 1, v19
	s_nop 0
	v_cndmask_b32_e64 v20, v19, v20, s[0:1]
	v_fma_f32 v19, -v21, v19, v16
	v_cmp_lt_f32_e64 s[0:1], 0, v19
	s_nop 1
	v_cndmask_b32_e64 v19, v20, v21, s[0:1]
	v_mul_f32_e32 v20, 0x37800000, v19
	v_cndmask_b32_e32 v19, v19, v20, vcc
	v_cmp_class_f32_e32 vcc, v16, v214
	s_nop 1
	v_cndmask_b32_e32 v16, v19, v16, vcc
	ds_read_b32 v19, v24 offset:9292
	s_waitcnt lgkmcnt(0)
; __device__ __forceinline__ float sigm(float x) { return __builtin_amdgcn_rcpf(1.f + __expf(-x)); }
; __device__ __forceinline__ void mixB1_item(const Params& P, int layer, int idx, const bf16_t* z, float* hsl, float* Pc, float* carryP, float* carryH, char* lds) {
;     ...
; #pragma unroll
;     for (int jn = 0; jn < 4; ++jn)
; #pragma unroll
;       for (int e = 0; e < 4; ++e) {
;         const int j = jn * 16 + 4 * fq + e, ch = layer * 256 + g * 64 + j;
;         const float r = sigm(ar[jn][e] + P.lru_ba[ch]), ig = sigm(ai[jn][e] + P.lru_bx[ch]);
;         const float lam = P.lru_lam[ch];
;         const float xe = __expf(-lam);
;         float m8; asm volatile("v_mov_b32 %0, 0xc1000000" : "=v"(m8));
;         const float la = m8 * r * (xe * (1.f - xe * (0.5f - xe * (1.f / 3.f))));
;         const float av = __expf(la);
;         const float y2 = 2.f * la;
;         const float om = -y2 * (1.f + y2 * (0.5f + y2 * ((1.f / 6.f) + y2 * ((1.f / 24.f) + y2 * ((1.f / 120.f) + y2 * (1.f / 720.f))))));
;         const float bv = sqrtf(om) * (ig * xcf[t * 65 + j]);
;         aA[t * 65 + j] = av; bB[t * 65 + j] = bv;
	v_mul_f32_e32 v17, v19, v17
	v_mul_f32_e32 v16, v17, v16
	v_add_u32_e32 v17, 0x4c, v24
	ds_write2st64_b32 v17, v18, v16 offset0:101 offset1:166
	v_mov_b32_e32 v16, v92
	s_waitcnt vmcnt(0)
	v_add_f32_e32 v12, v12, v16
	v_mov_b32_e32 v16, v108
	v_mul_f32_e32 v12, 0xbfb8aa3b, v12
	v_exp_f32_e32 v12, v12
	s_waitcnt vmcnt(0)
	v_add_f32_e32 v8, v8, v16
	v_mov_b32_e32 v16, v124
	v_add_f32_e32 v12, 1.0, v12
	v_rcp_f32_e32 v12, v12
	v_mov_b32 v17, 0xc1000000
	v_mul_f32_e32 v8, 0xbfb8aa3b, v8
	v_exp_f32_e32 v8, v8
	v_mul_f32_e32 v12, v17, v12
	v_add_f32_e32 v8, 1.0, v8
	v_rcp_f32_e32 v8, v8
	s_waitcnt vmcnt(0)
	v_mul_f32_e32 v16, 0xbfb8aa3b, v16
	v_exp_f32_e32 v16, v16
	s_nop 0
	v_fma_f32 v17, v16, s30, 0.5
	v_fma_f32 v17, -v16, v17, 1.0
	v_mul_f32_e32 v16, v16, v17
	v_mul_f32_e32 v12, v12, v16
	v_mul_f32_e32 v16, 0x3fb8aa3b, v12
	v_add_f32_e32 v12, v12, v12
	v_fmamk_f32 v17, v12, 0x3ab60b61, v213
	v_fmaak_f32 v17, v12, v17, 0x3d2aaaab
	v_fmaak_f32 v17, v12, v17, 0x3e2aaaab
	v_fma_f32 v17, v12, v17, 0.5
	v_fma_f32 v17, v12, v17, 1.0
	v_mul_f32_e64 v12, v17, -v12
	v_cmp_gt_f32_e32 vcc, s31, v12
	v_mul_f32_e32 v17, 0x4f800000, v12
	v_exp_f32_e32 v16, v16
	v_cndmask_b32_e32 v12, v12, v17, vcc
	v_sqrt_f32_e32 v17, v12
	s_nop 0
	v_add_u32_e32 v18, -1, v17
	v_fma_f32 v19, -v18, v17, v12
	v_cmp_ge_f32_e64 s[0:1], 0, v19
	v_add_u32_e32 v19, 1, v17
	s_nop 0
	v_cndmask_b32_e64 v18, v17, v18, s[0:1]
	v_fma_f32 v17, -v19, v17, v12
	v_cmp_lt_f32_e64 s[0:1], 0, v17
	s_nop 1
	v_cndmask_b32_e64 v17, v18, v19, s[0:1]
	v_mul_f32_e32 v18, 0x37800000, v17
	v_cndmask_b32_e32 v17, v17, v18, vcc
	v_cmp_class_f32_e32 vcc, v12, v214
	s_nop 1
	v_cndmask_b32_e32 v12, v17, v12, vcc
	ds_read_b32 v17, v24 offset:9344
	s_waitcnt lgkmcnt(0)
	v_mul_f32_e32 v8, v17, v8
	v_mul_f32_e32 v8, v8, v12
	v_add_u32_e32 v12, 0x80, v24
	ds_write2st64_b32 v12, v16, v8 offset0:101 offset1:166
	v_mov_b32_e32 v8, v93
	v_mov_b32_e32 v12, v109
	s_waitcnt vmcnt(1)
	v_add_f32_e32 v8, v13, v8
	s_waitcnt vmcnt(0)
	v_add_f32_e32 v9, v9, v12
	v_mov_b32_e32 v12, v125
	v_mul_f32_e32 v8, 0xbfb8aa3b, v8
	v_exp_f32_e32 v8, v8
	v_mov_b32 v13, 0xc1000000
	v_mul_f32_e32 v9, 0xbfb8aa3b, v9
	v_exp_f32_e32 v9, v9
	v_add_f32_e32 v8, 1.0, v8
	v_rcp_f32_e32 v8, v8
	v_add_f32_e32 v9, 1.0, v9
	v_rcp_f32_e32 v9, v9
	v_mul_f32_e32 v8, v13, v8
	s_waitcnt vmcnt(0)
	v_mul_f32_e32 v12, 0xbfb8aa3b, v12
	v_exp_f32_e32 v12, v12
	s_nop 0
	v_fma_f32 v13, v12, s30, 0.5
	v_fma_f32 v13, -v12, v13, 1.0
	v_mul_f32_e32 v12, v12, v13
	v_mul_f32_e32 v8, v8, v12
	v_mul_f32_e32 v12, 0x3fb8aa3b, v8
	v_add_f32_e32 v8, v8, v8
	v_fmamk_f32 v13, v8, 0x3ab60b61, v213
	v_fmaak_f32 v13, v8, v13, 0x3d2aaaab
	v_fmaak_f32 v13, v8, v13, 0x3e2aaaab
	v_fma_f32 v13, v8, v13, 0.5
	v_fma_f32 v13, v8, v13, 1.0
	v_mul_f32_e64 v8, v13, -v8
	v_cmp_gt_f32_e32 vcc, s31, v8
	v_mul_f32_e32 v13, 0x4f800000, v8
	v_exp_f32_e32 v12, v12
	v_cndmask_b32_e32 v8, v8, v13, vcc
	v_sqrt_f32_e32 v13, v8
	s_nop 0
	v_add_u32_e32 v16, -1, v13
	v_fma_f32 v17, -v16, v13, v8
	v_cmp_ge_f32_e64 s[0:1], 0, v17
	v_add_u32_e32 v17, 1, v13
	s_nop 0
	v_cndmask_b32_e64 v16, v13, v16, s[0:1]
	v_fma_f32 v13, -v17, v13, v8
	v_cmp_lt_f32_e64 s[0:1], 0, v13
	s_nop 1
	v_cndmask_b32_e64 v13, v16, v17, s[0:1]
	v_mul_f32_e32 v16, 0x37800000, v13
	v_cndmask_b32_e32 v13, v13, v16, vcc
	v_cmp_class_f32_e32 vcc, v8, v214
	s_nop 1
	v_cndmask_b32_e32 v8, v13, v8, vcc
	ds_read_b32 v13, v24 offset:9348
	s_waitcnt lgkmcnt(0)
	v_mul_f32_e32 v9, v13, v9
	v_mul_f32_e32 v8, v9, v8
	v_add_u32_e32 v9, 0x84, v24
	ds_write2st64_b32 v9, v12, v8 offset0:101 offset1:166
	v_mov_b32_e32 v8, v94
	v_mov_b32_e32 v9, v110
	s_waitcnt vmcnt(1)
	v_add_f32_e32 v8, v14, v8
	s_waitcnt vmcnt(0)
	v_add_f32_e32 v9, v10, v9
	v_mov_b32_e32 v10, v126
	v_mul_f32_e32 v8, 0xbfb8aa3b, v8
	v_exp_f32_e32 v8, v8
	v_mov_b32 v12, 0xc1000000
	v_mul_f32_e32 v9, 0xbfb8aa3b, v9
	v_exp_f32_e32 v9, v9
	v_add_f32_e32 v8, 1.0, v8
	v_rcp_f32_e32 v8, v8
	v_add_f32_e32 v9, 1.0, v9
	v_rcp_f32_e32 v9, v9
	v_mul_f32_e32 v8, v12, v8
	s_waitcnt vmcnt(0)
	v_mul_f32_e32 v10, 0xbfb8aa3b, v10
	v_exp_f32_e32 v10, v10
	s_nop 0
	v_fma_f32 v12, v10, s30, 0.5
	v_fma_f32 v12, -v10, v12, 1.0
	v_mul_f32_e32 v10, v10, v12
	v_mul_f32_e32 v8, v8, v10
	v_mul_f32_e32 v10, 0x3fb8aa3b, v8
	v_add_f32_e32 v8, v8, v8
	v_fmamk_f32 v12, v8, 0x3ab60b61, v213
	v_fmaak_f32 v12, v8, v12, 0x3d2aaaab
	v_fmaak_f32 v12, v8, v12, 0x3e2aaaab
	v_fma_f32 v12, v8, v12, 0.5
	v_fma_f32 v12, v8, v12, 1.0
	v_mul_f32_e64 v8, v12, -v8
	v_cmp_gt_f32_e32 vcc, s31, v8
	v_mul_f32_e32 v12, 0x4f800000, v8
	v_exp_f32_e32 v10, v10
	v_cndmask_b32_e32 v8, v8, v12, vcc
	v_sqrt_f32_e32 v12, v8
	s_nop 0
	v_add_u32_e32 v13, -1, v12
	v_fma_f32 v14, -v13, v12, v8
	v_cmp_ge_f32_e64 s[0:1], 0, v14
	v_add_u32_e32 v14, 1, v12
	s_nop 0
	v_cndmask_b32_e64 v13, v12, v13, s[0:1]
	v_fma_f32 v12, -v14, v12, v8
	v_cmp_lt_f32_e64 s[0:1], 0, v12
	s_nop 1
	v_cndmask_b32_e64 v12, v13, v14, s[0:1]
	v_mul_f32_e32 v13, 0x37800000, v12
	v_cndmask_b32_e32 v12, v12, v13, vcc
	v_cmp_class_f32_e32 vcc, v8, v214
	s_nop 1
	v_cndmask_b32_e32 v8, v12, v8, vcc
	ds_read_b32 v12, v24 offset:9352
	s_waitcnt lgkmcnt(0)
	v_mul_f32_e32 v9, v12, v9
	v_mul_f32_e32 v8, v9, v8
	v_add_u32_e32 v9, 0x88, v24
	ds_write2st64_b32 v9, v10, v8 offset0:101 offset1:166
	v_mov_b32_e32 v8, v95
	v_mov_b32_e32 v9, v111
	v_mov_b32_e32 v10, v127
	s_waitcnt vmcnt(2)
	v_add_f32_e32 v8, v15, v8
	v_mul_f32_e32 v8, 0xbfb8aa3b, v8
	v_exp_f32_e32 v8, v8
	s_waitcnt vmcnt(0)
; __device__ __forceinline__ float sigm(float x) { return __builtin_amdgcn_rcpf(1.f + __expf(-x)); }
; __device__ __forceinline__ void mixB1_item(const Params& P, int layer, int idx, const bf16_t* z, float* hsl, float* Pc, float* carryP, float* carryH, char* lds) {
;     ...
; #pragma unroll
;     for (int jn = 0; jn < 4; ++jn)
; #pragma unroll
;       for (int e = 0; e < 4; ++e) {
;         const int j = jn * 16 + 4 * fq + e, ch = layer * 256 + g * 64 + j;
;         const float r = sigm(ar[jn][e] + P.lru_ba[ch]), ig = sigm(ai[jn][e] + P.lru_bx[ch]);
;         const float lam = P.lru_lam[ch];
;         const float xe = __expf(-lam);
;         float m8; asm volatile("v_mov_b32 %0, 0xc1000000" : "=v"(m8));
;         const float la = m8 * r * (xe * (1.f - xe * (0.5f - xe * (1.f / 3.f))));
;         const float av = __expf(la);
;         const float y2 = 2.f * la;
;         const float om = -y2 * (1.f + y2 * (0.5f + y2 * ((1.f / 6.f) + y2 * ((1.f / 24.f) + y2 * ((1.f / 120.f) + y2 * (1.f / 720.f))))));
;         const float bv = sqrtf(om) * (ig * xcf[t * 65 + j]);
;         aA[t * 65 + j] = av; bB[t * 65 + j] = bv;
	v_mul_f32_e32 v10, 0xbfb8aa3b, v10
	v_exp_f32_e32 v10, v10
	v_add_f32_e32 v9, v11, v9
	v_add_f32_e32 v8, 1.0, v8
	v_rcp_f32_e32 v8, v8
	v_mov_b32 v11, 0xc1000000
	v_mul_f32_e32 v9, 0xbfb8aa3b, v9
	v_exp_f32_e32 v9, v9
	v_mul_f32_e32 v8, v11, v8
	v_fma_f32 v11, v10, s30, 0.5
	v_fma_f32 v11, -v10, v11, 1.0
	v_mul_f32_e32 v10, v10, v11
	v_mul_f32_e32 v8, v8, v10
	v_mul_f32_e32 v10, 0x3fb8aa3b, v8
	v_add_f32_e32 v8, v8, v8
	v_fmamk_f32 v11, v8, 0x3ab60b61, v213
	v_fmaak_f32 v11, v8, v11, 0x3d2aaaab
	v_fmaak_f32 v11, v8, v11, 0x3e2aaaab
	v_fma_f32 v11, v8, v11, 0.5
	v_fma_f32 v11, v8, v11, 1.0
	v_mul_f32_e64 v8, v11, -v8
	v_cmp_gt_f32_e32 vcc, s31, v8
	v_mul_f32_e32 v11, 0x4f800000, v8
	v_add_f32_e32 v9, 1.0, v9
	v_cndmask_b32_e32 v8, v8, v11, vcc
	v_sqrt_f32_e32 v11, v8
	v_rcp_f32_e32 v9, v9
	v_exp_f32_e32 v10, v10
	v_add_u32_e32 v12, -1, v11
	v_fma_f32 v13, -v12, v11, v8
	v_cmp_ge_f32_e64 s[0:1], 0, v13
	v_add_u32_e32 v13, 1, v11
	s_nop 0
	v_cndmask_b32_e64 v12, v11, v12, s[0:1]
	v_fma_f32 v11, -v13, v11, v8
	v_cmp_lt_f32_e64 s[0:1], 0, v11
	s_nop 1
	v_cndmask_b32_e64 v11, v12, v13, s[0:1]
	v_mul_f32_e32 v12, 0x37800000, v11
	v_cndmask_b32_e32 v11, v11, v12, vcc
	v_cmp_class_f32_e32 vcc, v8, v214
	s_nop 1
	v_cndmask_b32_e32 v8, v11, v8, vcc
	ds_read_b32 v11, v24 offset:9356
	s_waitcnt lgkmcnt(0)
	v_mul_f32_e32 v9, v11, v9
	v_mul_f32_e32 v8, v9, v8
	v_add_u32_e32 v9, 0x8c, v24
	ds_write2st64_b32 v9, v10, v8 offset0:101 offset1:166
	v_mov_b32_e32 v8, v96
	s_waitcnt vmcnt(0)
	v_add_f32_e32 v4, v4, v8
	v_mov_b32_e32 v8, v112
	v_mul_f32_e32 v4, 0xbfb8aa3b, v4
	v_exp_f32_e32 v4, v4
	s_waitcnt vmcnt(0)
	v_add_f32_e32 v0, v0, v8
	v_mov_b32_e32 v8, v128
	v_add_f32_e32 v4, 1.0, v4
	v_rcp_f32_e32 v4, v4
	v_mov_b32 v9, 0xc1000000
	v_mul_f32_e32 v0, 0xbfb8aa3b, v0
	v_exp_f32_e32 v0, v0
	v_mul_f32_e32 v4, v9, v4
	v_add_f32_e32 v0, 1.0, v0
	v_rcp_f32_e32 v0, v0
	s_waitcnt vmcnt(0)
	v_mul_f32_e32 v8, 0xbfb8aa3b, v8
	v_exp_f32_e32 v8, v8
	s_nop 0
	v_fma_f32 v9, v8, s30, 0.5
	v_fma_f32 v9, -v8, v9, 1.0
	v_mul_f32_e32 v8, v8, v9
	v_mul_f32_e32 v4, v4, v8
	v_mul_f32_e32 v8, 0x3fb8aa3b, v4
	v_add_f32_e32 v4, v4, v4
	v_fmamk_f32 v9, v4, 0x3ab60b61, v213
	v_fmaak_f32 v9, v4, v9, 0x3d2aaaab
	v_fmaak_f32 v9, v4, v9, 0x3e2aaaab
	v_fma_f32 v9, v4, v9, 0.5
	v_fma_f32 v9, v4, v9, 1.0
	v_mul_f32_e64 v4, v9, -v4
	v_cmp_gt_f32_e32 vcc, s31, v4
	v_mul_f32_e32 v9, 0x4f800000, v4
	v_exp_f32_e32 v8, v8
	v_cndmask_b32_e32 v4, v4, v9, vcc
	v_sqrt_f32_e32 v9, v4
	s_nop 0
	v_add_u32_e32 v10, -1, v9
	v_fma_f32 v11, -v10, v9, v4
	v_cmp_ge_f32_e64 s[0:1], 0, v11
	v_add_u32_e32 v11, 1, v9
	s_nop 0
	v_cndmask_b32_e64 v10, v9, v10, s[0:1]
	v_fma_f32 v9, -v11, v9, v4
	v_cmp_lt_f32_e64 s[0:1], 0, v9
	s_nop 1
	v_cndmask_b32_e64 v9, v10, v11, s[0:1]
	v_mul_f32_e32 v10, 0x37800000, v9
	v_cndmask_b32_e32 v9, v9, v10, vcc
	v_cmp_class_f32_e32 vcc, v4, v214
	s_nop 1
	v_cndmask_b32_e32 v4, v9, v4, vcc
	ds_read_b32 v9, v24 offset:9408
	s_waitcnt lgkmcnt(0)
	v_mul_f32_e32 v0, v9, v0
	v_mul_f32_e32 v0, v0, v4
	v_add_u32_e32 v4, 0xc0, v24
	ds_write2st64_b32 v4, v8, v0 offset0:101 offset1:166
	v_mov_b32_e32 v0, v97
	v_mov_b32_e32 v4, v113
	s_waitcnt vmcnt(1)
	v_add_f32_e32 v0, v5, v0
	s_waitcnt vmcnt(0)
	v_add_f32_e32 v1, v1, v4
	v_mov_b32_e32 v4, v129
	v_mul_f32_e32 v0, 0xbfb8aa3b, v0
	v_exp_f32_e32 v0, v0
	v_mov_b32 v5, 0xc1000000
	v_mul_f32_e32 v1, 0xbfb8aa3b, v1
	v_exp_f32_e32 v1, v1
	v_add_f32_e32 v0, 1.0, v0
	v_rcp_f32_e32 v0, v0
	v_add_f32_e32 v1, 1.0, v1
	v_rcp_f32_e32 v1, v1
	v_mul_f32_e32 v0, v5, v0
	s_waitcnt vmcnt(0)
	v_mul_f32_e32 v4, 0xbfb8aa3b, v4
	v_exp_f32_e32 v4, v4
	s_nop 0
	v_fma_f32 v5, v4, s30, 0.5
	v_fma_f32 v5, -v4, v5, 1.0
	v_mul_f32_e32 v4, v4, v5
	v_mul_f32_e32 v0, v0, v4
	v_mul_f32_e32 v4, 0x3fb8aa3b, v0
	v_add_f32_e32 v0, v0, v0
	v_fmamk_f32 v5, v0, 0x3ab60b61, v213
	v_fmaak_f32 v5, v0, v5, 0x3d2aaaab
	v_fmaak_f32 v5, v0, v5, 0x3e2aaaab
	v_fma_f32 v5, v0, v5, 0.5
	v_fma_f32 v5, v0, v5, 1.0
	v_mul_f32_e64 v0, v5, -v0
	v_cmp_gt_f32_e32 vcc, s31, v0
	v_mul_f32_e32 v5, 0x4f800000, v0
	v_exp_f32_e32 v4, v4
	v_cndmask_b32_e32 v0, v0, v5, vcc
	v_sqrt_f32_e32 v5, v0
	s_nop 0
	v_add_u32_e32 v8, -1, v5
	v_fma_f32 v9, -v8, v5, v0
	v_cmp_ge_f32_e64 s[0:1], 0, v9
	v_add_u32_e32 v9, 1, v5
	s_nop 0
	v_cndmask_b32_e64 v8, v5, v8, s[0:1]
	v_fma_f32 v5, -v9, v5, v0
	v_cmp_lt_f32_e64 s[0:1], 0, v5
	s_nop 1
	v_cndmask_b32_e64 v5, v8, v9, s[0:1]
	v_mul_f32_e32 v8, 0x37800000, v5
	v_cndmask_b32_e32 v5, v5, v8, vcc
	v_cmp_class_f32_e32 vcc, v0, v214
	s_nop 1
	v_cndmask_b32_e32 v0, v5, v0, vcc
	ds_read_b32 v5, v24 offset:9412
	s_waitcnt lgkmcnt(0)
	v_mul_f32_e32 v1, v5, v1
	v_mul_f32_e32 v0, v1, v0
	v_add_u32_e32 v1, 0xc4, v24
	ds_write2st64_b32 v1, v4, v0 offset0:101 offset1:166
	v_mov_b32_e32 v0, v98
	v_mov_b32_e32 v1, v114
	s_waitcnt vmcnt(1)
	v_add_f32_e32 v0, v6, v0
	s_waitcnt vmcnt(0)
	v_add_f32_e32 v1, v2, v1
	v_mov_b32_e32 v2, v130
	v_mul_f32_e32 v0, 0xbfb8aa3b, v0
	v_exp_f32_e32 v0, v0
	v_mov_b32 v4, 0xc1000000
	v_mul_f32_e32 v1, 0xbfb8aa3b, v1
	v_exp_f32_e32 v1, v1
	v_add_f32_e32 v0, 1.0, v0
	v_rcp_f32_e32 v0, v0
	v_add_f32_e32 v1, 1.0, v1
	v_rcp_f32_e32 v1, v1
	v_mul_f32_e32 v0, v4, v0
	s_waitcnt vmcnt(0)
; __device__ __forceinline__ float sigm(float x) { return __builtin_amdgcn_rcpf(1.f + __expf(-x)); }
; __device__ __forceinline__ void mixB1_item(const Params& P, int layer, int idx, const bf16_t* z, float* hsl, float* Pc, float* carryP, float* carryH, char* lds) {
;     ...
;         const int j = jn * 16 + 4 * fq + e, ch = layer * 256 + g * 64 + j;
;         const float r = sigm(ar[jn][e] + P.lru_ba[ch]), ig = sigm(ai[jn][e] + P.lru_bx[ch]);
;         const float lam = P.lru_lam[ch];
;         const float xe = __expf(-lam);
;         float m8; asm volatile("v_mov_b32 %0, 0xc1000000" : "=v"(m8));
;         const float la = m8 * r * (xe * (1.f - xe * (0.5f - xe * (1.f / 3.f))));
;         const float av = __expf(la);
;         const float y2 = 2.f * la;
;         const float om = -y2 * (1.f + y2 * (0.5f + y2 * ((1.f / 6.f) + y2 * ((1.f / 24.f) + y2 * ((1.f / 120.f) + y2 * (1.f / 720.f))))));
;         const float bv = sqrtf(om) * (ig * xcf[t * 65 + j]);
;         aA[t * 65 + j] = av; bB[t * 65 + j] = bv;
;       }
;   }
;   __syncthreads();
;   {
;     const int q = tid >> 6, j = tid & 63;
;     float Pq = 1.f, hq = 0.f;
; #pragma unroll
;     for (int i = 0; i < 16; ++i) { const int t = q * 16 + i; const float av = aA[t * 65 + j], bv = bB[t * 65 + j]; hq = av * hq + bv; Pq *= av; aA[t * 65 + j] = Pq; bB[t * 65 + j] = hq; }
;     sm[q * 64 + j] = Pq; sm[256 + q * 64 + j] = hq;
;     __syncthreads();
;     float Pin = 1.f, Hin = 0.f;
;     for (int qq = 0; qq < q; ++qq) { const float pp = sm[qq * 64 + j], hh = sm[256 + qq * 64 + j]; Hin = pp * Hin + hh; Pin *= pp; }
	v_mul_f32_e32 v2, 0xbfb8aa3b, v2
	v_exp_f32_e32 v2, v2
	s_nop 0
	v_fma_f32 v4, v2, s30, 0.5
	v_fma_f32 v4, -v2, v4, 1.0
	v_mul_f32_e32 v2, v2, v4
	v_mul_f32_e32 v0, v0, v2
	v_mul_f32_e32 v2, 0x3fb8aa3b, v0
	v_add_f32_e32 v0, v0, v0
	v_fmamk_f32 v4, v0, 0x3ab60b61, v213
	v_fmaak_f32 v4, v0, v4, 0x3d2aaaab
	v_fmaak_f32 v4, v0, v4, 0x3e2aaaab
	v_fma_f32 v4, v0, v4, 0.5
	v_fma_f32 v4, v0, v4, 1.0
	v_mul_f32_e64 v0, v4, -v0
	v_cmp_gt_f32_e32 vcc, s31, v0
	v_mul_f32_e32 v4, 0x4f800000, v0
	v_exp_f32_e32 v2, v2
	v_cndmask_b32_e32 v0, v0, v4, vcc
	v_sqrt_f32_e32 v4, v0
	s_nop 0
	v_add_u32_e32 v5, -1, v4
	v_fma_f32 v6, -v5, v4, v0
	v_cmp_ge_f32_e64 s[0:1], 0, v6
	v_add_u32_e32 v6, 1, v4
	s_nop 0
	v_cndmask_b32_e64 v5, v4, v5, s[0:1]
	v_fma_f32 v4, -v6, v4, v0
	v_cmp_lt_f32_e64 s[0:1], 0, v4
	s_nop 1
	v_cndmask_b32_e64 v4, v5, v6, s[0:1]
	v_mul_f32_e32 v5, 0x37800000, v4
	v_cndmask_b32_e32 v4, v4, v5, vcc
	v_cmp_class_f32_e32 vcc, v0, v214
	s_nop 1
	v_cndmask_b32_e32 v0, v4, v0, vcc
	ds_read_b32 v4, v24 offset:9416
	s_waitcnt lgkmcnt(0)
	v_mul_f32_e32 v1, v4, v1
	v_mul_f32_e32 v0, v1, v0
	v_add_u32_e32 v1, 0xc8, v24
	ds_write2st64_b32 v1, v2, v0 offset0:101 offset1:166
	v_mov_b32_e32 v0, v99
	v_mov_b32_e32 v1, v115
	v_mov_b32_e32 v2, v131
	s_waitcnt vmcnt(2)
	v_add_f32_e32 v0, v7, v0
	v_mul_f32_e32 v0, 0xbfb8aa3b, v0
	v_exp_f32_e32 v0, v0
	s_waitcnt vmcnt(0)
	v_mul_f32_e32 v2, 0xbfb8aa3b, v2
	v_exp_f32_e32 v2, v2
	v_add_f32_e32 v1, v3, v1
	v_add_f32_e32 v0, 1.0, v0
	v_rcp_f32_e32 v0, v0
	v_mov_b32 v3, 0xc1000000
	v_mul_f32_e32 v1, 0xbfb8aa3b, v1
	v_exp_f32_e32 v1, v1
	v_mul_f32_e32 v0, v3, v0
	v_fma_f32 v3, v2, s30, 0.5
	v_fma_f32 v3, -v2, v3, 1.0
	v_mul_f32_e32 v2, v2, v3
	v_mul_f32_e32 v0, v0, v2
	v_mul_f32_e32 v2, 0x3fb8aa3b, v0
	v_add_f32_e32 v0, v0, v0
	v_fmamk_f32 v3, v0, 0x3ab60b61, v213
	v_fmaak_f32 v3, v0, v3, 0x3d2aaaab
	v_fmaak_f32 v3, v0, v3, 0x3e2aaaab
	v_fma_f32 v3, v0, v3, 0.5
	v_fma_f32 v3, v0, v3, 1.0
	v_mul_f32_e64 v0, v3, -v0
	v_cmp_gt_f32_e32 vcc, s31, v0
	v_mul_f32_e32 v3, 0x4f800000, v0
	v_add_f32_e32 v1, 1.0, v1
	v_cndmask_b32_e32 v0, v0, v3, vcc
	v_sqrt_f32_e32 v3, v0
	v_rcp_f32_e32 v1, v1
	v_exp_f32_e32 v2, v2
	v_add_u32_e32 v4, -1, v3
	v_fma_f32 v5, -v4, v3, v0
	v_cmp_ge_f32_e64 s[0:1], 0, v5
	v_add_u32_e32 v5, 1, v3
	s_nop 0
	v_cndmask_b32_e64 v4, v3, v4, s[0:1]
	v_fma_f32 v3, -v5, v3, v0
	v_cmp_lt_f32_e64 s[0:1], 0, v3
	s_nop 1
	v_cndmask_b32_e64 v3, v4, v5, s[0:1]
	v_mul_f32_e32 v4, 0x37800000, v3
	v_cndmask_b32_e32 v3, v3, v4, vcc
	v_cmp_class_f32_e32 vcc, v0, v214
	s_movk_i32 s0, 0x410
	s_nop 0
	v_cndmask_b32_e32 v0, v3, v0, vcc
	ds_read_b32 v3, v24 offset:9420
	v_cmp_lt_u32_e32 vcc, 63, v40
	s_waitcnt lgkmcnt(0)
	v_mul_f32_e32 v1, v3, v1
	v_mul_f32_e32 v0, v1, v0
	v_add_u32_e32 v1, 0xcc, v24
	ds_write2st64_b32 v1, v2, v0 offset0:101 offset1:166
	v_mad_u32_u24 v0, v39, s0, v38
	v_lshl_add_u32 v2, v0, 2, v60
	v_add_u32_e32 v3, 0x6400, v2
	v_add_u32_e32 v6, 0xa400, v2
	s_waitcnt lgkmcnt(0)
	s_barrier
	ds_read2_b32 v[0:1], v3 offset0:64 offset1:129
	ds_read2_b32 v[4:5], v6 offset0:128 offset1:193
	v_add_u32_e32 v9, 0xa800, v2
	s_waitcnt lgkmcnt(1)
	v_mul_f32_e32 v8, v0, v1
	s_waitcnt lgkmcnt(0)
	v_fma_f32 v4, 0, v0, v4
	v_fmac_f32_e32 v5, v4, v1
	v_add_u32_e32 v0, 0x6600, v2
	ds_write2_b32 v6, v4, v5 offset0:128 offset1:193
	ds_read2_b32 v[0:1], v0 offset0:66 offset1:131
	ds_read2_b32 v[6:7], v9 offset0:2 offset1:67
	s_waitcnt lgkmcnt(0)
	v_fma_f32 v4, v5, v0, v6
	v_mul_f32_e32 v0, v8, v0
	v_fmac_f32_e32 v7, v4, v1
	ds_write2_b32 v3, v8, v0 offset0:129 offset1:194
	ds_write2_b32 v9, v4, v7 offset0:2 offset1:67
	v_add_u32_e32 v8, 0x6800, v2
	v_mul_f32_e32 v3, v0, v1
	ds_read2_b32 v[0:1], v8 offset0:68 offset1:133
	ds_read2_b32 v[4:5], v9 offset0:132 offset1:197
	s_waitcnt lgkmcnt(0)
	v_fma_f32 v4, v7, v0, v4
	v_mul_f32_e32 v0, v3, v0
	v_fmac_f32_e32 v5, v4, v1
	ds_write2_b32 v8, v3, v0 offset0:3 offset1:68
	v_mul_f32_e32 v3, v0, v1
	ds_write2_b32 v9, v4, v5 offset0:132 offset1:197
	v_add_u32_e32 v0, 0x6a00, v2
	v_add_u32_e32 v9, 0xac00, v2
	ds_read2_b32 v[0:1], v0 offset0:70 offset1:135
	ds_read2_b32 v[6:7], v9 offset0:6 offset1:71
	s_waitcnt lgkmcnt(0)
	v_fma_f32 v4, v5, v0, v6
	v_mul_f32_e32 v0, v3, v0
	v_fmac_f32_e32 v7, v4, v1
	ds_write2_b32 v8, v3, v0 offset0:133 offset1:198
	ds_write2_b32 v9, v4, v7 offset0:6 offset1:71
	v_add_u32_e32 v8, 0x6c00, v2
	v_mul_f32_e32 v3, v0, v1
	ds_read2_b32 v[0:1], v8 offset0:72 offset1:137
	ds_read2_b32 v[4:5], v9 offset0:136 offset1:201
	s_waitcnt lgkmcnt(0)
	v_fma_f32 v4, v7, v0, v4
	v_mul_f32_e32 v0, v3, v0
	v_fmac_f32_e32 v5, v4, v1
	ds_write2_b32 v8, v3, v0 offset0:7 offset1:72
	v_mul_f32_e32 v3, v0, v1
	ds_write2_b32 v9, v4, v5 offset0:136 offset1:201
	v_add_u32_e32 v0, 0x6e00, v2
	v_add_u32_e32 v9, 0xb000, v2
	ds_read2_b32 v[0:1], v0 offset0:74 offset1:139
	ds_read2_b32 v[6:7], v9 offset0:10 offset1:75
	s_waitcnt lgkmcnt(0)
	v_fma_f32 v4, v5, v0, v6
	v_mul_f32_e32 v0, v3, v0
	v_fmac_f32_e32 v7, v4, v1
	ds_write2_b32 v8, v3, v0 offset0:137 offset1:202
	ds_write2_b32 v9, v4, v7 offset0:10 offset1:75
	v_add_u32_e32 v8, 0x7000, v2
	v_mul_f32_e32 v3, v0, v1
	ds_read2_b32 v[4:5], v8 offset0:76 offset1:141
	ds_read2_b32 v[0:1], v9 offset0:140 offset1:205
	s_waitcnt lgkmcnt(0)
	v_fma_f32 v0, v7, v4, v0
	v_fmac_f32_e32 v1, v0, v5
	v_mul_f32_e32 v4, v3, v4
	ds_write2_b32 v9, v0, v1 offset0:140 offset1:205
	v_add_u32_e32 v0, 0x7200, v2
	ds_write2_b32 v8, v3, v4 offset0:11 offset1:76
	v_mul_f32_e32 v3, v4, v5
	ds_read2_b32 v[4:5], v0 offset0:78 offset1:143
	v_add_u32_e32 v0, 0xb400, v2
	ds_read2_b32 v[6:7], v0 offset0:14 offset1:79
	s_waitcnt lgkmcnt(0)
	v_fma_f32 v1, v1, v4, v6
	v_mul_f32_e32 v4, v3, v4
	ds_write2_b32 v8, v3, v4 offset0:141 offset1:206
	v_mul_f32_e32 v3, v4, v5
	v_fmac_f32_e32 v7, v1, v5
	ds_write_b32 v2, v3 offset:29756
	ds_write2_b32 v0, v1, v7 offset0:14 offset1:79
	v_lshl_add_u32 v0, v40, 2, v60
	v_mov_b32_e32 v1, 0
	ds_write2st64_b32 v0, v3, v7 offset0:231 offset1:235
	s_waitcnt lgkmcnt(0)
	s_barrier
	s_and_saveexec_b64 s[0:1], vcc
	s_cbranch_execz .LBB0_566
	v_lshl_add_u32 v3, v38, 2, v34
	v_mov_b32_e32 v28, 1.0
	v_mov_b32_e32 v1, 0
	s_mov_b64 s[30:31], 0
	v_mov_b32_e32 v4, v39
